# write-through (sc1) on all 16-byte phase-output stores so the grid barriers' L2 writeback has less to flush
# speedup vs baseline: 1.0201x; 1.0156x over previous
; #define LAS __attribute__((address_space(3)))
; __global__ void __launch_bounds__(NT, 2) fwd_kernel(Args args) {
;     ...
;               const int ng = r % 96, ks = r / 96, cq = lane & 15, kr = lane >> 4; const int n = 64 * ng + 4 * cq;
;               f32x4 a0 = {0.f, 0.f, 0.f, 0.f}, a1 = a0, a2 = a0, a3 = a0, a4 = a0;
;               const float* wp = w_mod + (size_t)(128 * ks + kr) * 6144 + n;
; #pragma unroll 8
;               for (int i = 0; i < 32; ++i) { const f32x4 w = *(const f32x4*)(wp + (size_t)(4 * i) * 6144); const int k = 128 * ks + 4 * i + kr;
;                   a0 += w * ((LAS float*)(lds + 16384 * 0 + 12288))[k]; a1 += w * ((LAS float*)(lds + 16384 * 1 + 12288))[k]; a2 += w * ((LAS float*)(lds + 16384 * 2 + 12288))[k];
;                   a3 += w * ((LAS float*)(lds + 16384 * 3 + 12288))[k]; a4 += w * ((LAS float*)(lds + 16384 * 4 + 12288))[k]; }
.LBB0_18:
	s_waitcnt lgkmcnt(13)
	v_add_co_u32_e32 v36, vcc, s70, v24
	global_load_dwordx4 v[2:5], v[24:25], off
	s_waitcnt lgkmcnt(12)
	v_addc_co_u32_e32 v37, vcc, -1, v25, vcc
	s_waitcnt lgkmcnt(11)
	v_add_co_u32_e32 v40, vcc, s71, v24
	v_add_u32_e32 v10, s0, v7
	s_waitcnt lgkmcnt(10)
	v_addc_co_u32_e32 v41, vcc, -1, v25, vcc
	s_waitcnt lgkmcnt(5)
	v_add_co_u32_e32 v44, vcc, s72, v24
	v_add_u32_e32 v90, 0x13210, v10
	s_waitcnt lgkmcnt(4)
	v_addc_co_u32_e32 v45, vcc, -1, v25, vcc
	s_waitcnt lgkmcnt(1)
	v_add_co_u32_e32 v48, vcc, s73, v24
	v_add_u32_e32 v98, 0x13220, v10
	s_waitcnt lgkmcnt(0)
	v_addc_co_u32_e32 v49, vcc, -1, v25, vcc
	v_add_co_u32_e32 v70, vcc, s74, v24
	global_load_dwordx4 v[36:39], v[36:37], off
	s_nop 0
	global_load_dwordx4 v[40:43], v[40:41], off
	s_nop 0
	global_load_dwordx4 v[44:47], v[44:45], off
	s_nop 0
	global_load_dwordx4 v[66:69], v[48:49], off
	v_addc_co_u32_e32 v71, vcc, 0, v25, vcc
	v_add_co_u32_e32 v74, vcc, s75, v24
	global_load_dwordx4 v[70:73], v[70:71], off
	s_nop 0
	v_addc_co_u32_e32 v75, vcc, 0, v25, vcc
	v_add_co_u32_e32 v78, vcc, s84, v24
	global_load_dwordx4 v[74:77], v[74:75], off
	s_nop 0
	v_addc_co_u32_e32 v79, vcc, 0, v25, vcc
	global_load_dwordx4 v[78:81], v[78:79], off
	v_add_u32_e32 v48, 0x13200, v10
	v_add_u32_e32 v108, 0x13230, v10
	v_add_u32_e32 v110, 0x13240, v10
	v_add_u32_e32 v112, 0x13250, v10
	v_add_u32_e32 v91, 0x3000, v10
	v_add_u32_e32 v99, 0x7000, v10
	v_add_u32_e32 v109, 0xb000, v10
	v_add_u32_e32 v111, 0xf000, v10
	v_add_u32_e32 v113, 0x13260, v10
	v_add_u32_e32 v123, 0x13270, v10
	ds_read_b32 v10, v48
	ds_read2_b32 v[48:49], v91 offset0:128 offset1:132
	ds_read2_b32 v[82:83], v91 offset0:136 offset1:140
	ds_read2_b32 v[84:85], v99 offset0:128 offset1:132
	ds_read2_b32 v[86:87], v109 offset0:128 offset1:132
	ds_read2_b32 v[88:89], v111 offset0:128 offset1:132
	ds_read_b32 v90, v90
	ds_read2_b32 v[92:93], v99 offset0:136 offset1:140
	ds_read2_b32 v[94:95], v109 offset0:136 offset1:140
	ds_read2_b32 v[96:97], v111 offset0:136 offset1:140
	ds_read_b32 v98, v98
	ds_read2_b32 v[100:101], v91 offset0:144 offset1:148
	ds_read2_b32 v[102:103], v99 offset0:144 offset1:148
	ds_read2_b32 v[104:105], v109 offset0:144 offset1:148
	ds_read2_b32 v[106:107], v111 offset0:144 offset1:148
	ds_read_b32 v108, v108
	ds_read_b32 v110, v110
	ds_read_b32 v112, v112
	ds_read2_b32 v[114:115], v91 offset0:152 offset1:156
	ds_read2_b32 v[116:117], v99 offset0:152 offset1:156
	ds_read2_b32 v[118:119], v109 offset0:152 offset1:156
	ds_read2_b32 v[120:121], v111 offset0:152 offset1:156
	ds_read_b32 v122, v113
	ds_read_b32 v124, v123
	s_waitcnt lgkmcnt(14)
	v_mov_b32_e32 v126, v49
	v_mov_b32_e32 v128, v85
	v_mov_b32_e32 v130, v87
	v_mov_b32_e32 v132, v89
	v_mov_b32_e32 v134, v83
	v_mov_b32_e32 v136, v93
	v_mov_b32_e32 v138, v95
	v_mov_b32_e32 v140, v97
	s_waitcnt lgkmcnt(12)
	v_mov_b32_e32 v142, v101
	s_waitcnt lgkmcnt(11)
	v_mov_b32_e32 v144, v103
	s_waitcnt lgkmcnt(10)
	v_mov_b32_e32 v146, v105
	s_waitcnt lgkmcnt(9)
	v_mov_b32_e32 v148, v107
	s_addk_i32 s0, 0x80
	s_waitcnt lgkmcnt(5)
	v_mov_b32_e32 v150, v115
	s_waitcnt lgkmcnt(4)
	v_mov_b32_e32 v152, v117
	s_waitcnt lgkmcnt(3)
	v_mov_b32_e32 v154, v119
	s_waitcnt lgkmcnt(2)
	v_mov_b32_e32 v156, v121
	v_lshl_add_u64 v[24:25], v[24:25], 0, s[24:25]
	s_cmp_lg_u32 s0, 0
	s_waitcnt vmcnt(6)
	v_pk_fma_f32 v[16:17], v[38:39], v[10:11], v[16:17] op_sel_hi:[1,0,1]
	v_pk_fma_f32 v[30:31], v[36:37], v[10:11], v[30:31] op_sel_hi:[1,0,1]
	v_pk_fma_f32 v[22:23], v[38:39], v[48:49], v[22:23] op_sel_hi:[1,0,1]
	v_pk_fma_f32 v[34:35], v[36:37], v[48:49], v[34:35] op_sel_hi:[1,0,1]
	v_pk_fma_f32 v[20:21], v[38:39], v[84:85], v[20:21] op_sel_hi:[1,0,1]
	v_pk_fma_f32 v[32:33], v[36:37], v[84:85], v[32:33] op_sel_hi:[1,0,1]
	v_pk_fma_f32 v[18:19], v[38:39], v[86:87], v[18:19] op_sel_hi:[1,0,1]
	v_pk_fma_f32 v[28:29], v[36:37], v[86:87], v[28:29] op_sel_hi:[1,0,1]
	v_pk_fma_f32 v[8:9], v[38:39], v[88:89], v[8:9] op_sel_hi:[1,0,1]
	v_pk_fma_f32 v[26:27], v[36:37], v[88:89], v[26:27] op_sel_hi:[1,0,1]
	s_waitcnt vmcnt(5)
	v_pk_fma_f32 v[22:23], v[42:43], v[126:127], v[22:23] op_sel_hi:[1,0,1]
	v_pk_fma_f32 v[34:35], v[40:41], v[126:127], v[34:35] op_sel_hi:[1,0,1]
	v_pk_fma_f32 v[20:21], v[42:43], v[128:129], v[20:21] op_sel_hi:[1,0,1]
	v_pk_fma_f32 v[32:33], v[40:41], v[128:129], v[32:33] op_sel_hi:[1,0,1]
	v_pk_fma_f32 v[18:19], v[42:43], v[130:131], v[18:19] op_sel_hi:[1,0,1]
	v_pk_fma_f32 v[28:29], v[40:41], v[130:131], v[28:29] op_sel_hi:[1,0,1]
	v_pk_fma_f32 v[8:9], v[42:43], v[132:133], v[8:9] op_sel_hi:[1,0,1]
	v_pk_fma_f32 v[26:27], v[40:41], v[132:133], v[26:27] op_sel_hi:[1,0,1]
	v_pk_fma_f32 v[16:17], v[42:43], v[90:91], v[16:17] op_sel_hi:[1,0,1]
	v_pk_fma_f32 v[30:31], v[40:41], v[90:91], v[30:31] op_sel_hi:[1,0,1]
	s_waitcnt vmcnt(4)
	v_pk_fma_f32 v[16:17], v[46:47], v[98:99], v[16:17] op_sel_hi:[1,0,1]
	v_pk_fma_f32 v[30:31], v[44:45], v[98:99], v[30:31] op_sel_hi:[1,0,1]
	v_pk_fma_f32 v[22:23], v[46:47], v[82:83], v[22:23] op_sel_hi:[1,0,1]
	v_pk_fma_f32 v[34:35], v[44:45], v[82:83], v[34:35] op_sel_hi:[1,0,1]
	v_pk_fma_f32 v[20:21], v[46:47], v[92:93], v[20:21] op_sel_hi:[1,0,1]
	v_pk_fma_f32 v[32:33], v[44:45], v[92:93], v[32:33] op_sel_hi:[1,0,1]
	v_pk_fma_f32 v[18:19], v[46:47], v[94:95], v[18:19] op_sel_hi:[1,0,1]
	v_pk_fma_f32 v[28:29], v[44:45], v[94:95], v[28:29] op_sel_hi:[1,0,1]
	v_pk_fma_f32 v[8:9], v[46:47], v[96:97], v[8:9] op_sel_hi:[1,0,1]
	v_pk_fma_f32 v[26:27], v[44:45], v[96:97], v[26:27] op_sel_hi:[1,0,1]
	s_waitcnt vmcnt(3)
; #define LAS __attribute__((address_space(3)))
; __device__ __forceinline__ float shx(float v, int o, int lane) { return __builtin_bit_cast(float, __builtin_amdgcn_ds_bpermute((lane ^ o) << 2, __builtin_bit_cast(int, v))); }
; __global__ void __launch_bounds__(NT, 2) fwd_kernel(Args args) {
;     ...
;               for (int i = 0; i < 32; ++i) { const f32x4 w = *(const f32x4*)(wp + (size_t)(4 * i) * 6144); const int k = 128 * ks + 4 * i + kr;
;                   a0 += w * ((LAS float*)(lds + 16384 * 0 + 12288))[k]; a1 += w * ((LAS float*)(lds + 16384 * 1 + 12288))[k]; a2 += w * ((LAS float*)(lds + 16384 * 2 + 12288))[k];
;                   a3 += w * ((LAS float*)(lds + 16384 * 3 + 12288))[k]; a4 += w * ((LAS float*)(lds + 16384 * 4 + 12288))[k]; }
; #pragma unroll
;               for (int e = 0; e < 4; ++e) { a0[e] += shx(a0[e], 16, lane); a0[e] += shx(a0[e], 32, lane); a1[e] += shx(a1[e], 16, lane); a1[e] += shx(a1[e], 32, lane); a2[e] += shx(a2[e], 16, lane); a2[e] += shx(a2[e], 32, lane);
;                   a3[e] += shx(a3[e], 16, lane); a3[e] += shx(a3[e], 32, lane); a4[e] += shx(a4[e], 16, lane); a4[e] += shx(a4[e], 32, lane); }
;               if (kr == 0) { float* p = MODP + (size_t)(ks * 5) * 6144 + n; *(f32x4*)p = a0; *(f32x4*)(p + 6144) = a1; *(f32x4*)(p + 2 * 6144) = a2; *(f32x4*)(p + 3 * 6144) = a3; *(f32x4*)(p + 4 * 6144) = a4; } }
	v_pk_fma_f32 v[22:23], v[68:69], v[134:135], v[22:23] op_sel_hi:[1,0,1]
	v_pk_fma_f32 v[34:35], v[66:67], v[134:135], v[34:35] op_sel_hi:[1,0,1]
	v_pk_fma_f32 v[20:21], v[68:69], v[136:137], v[20:21] op_sel_hi:[1,0,1]
	v_pk_fma_f32 v[32:33], v[66:67], v[136:137], v[32:33] op_sel_hi:[1,0,1]
	v_pk_fma_f32 v[18:19], v[68:69], v[138:139], v[18:19] op_sel_hi:[1,0,1]
	v_pk_fma_f32 v[28:29], v[66:67], v[138:139], v[28:29] op_sel_hi:[1,0,1]
	v_pk_fma_f32 v[8:9], v[68:69], v[140:141], v[8:9] op_sel_hi:[1,0,1]
	v_pk_fma_f32 v[26:27], v[66:67], v[140:141], v[26:27] op_sel_hi:[1,0,1]
	v_pk_fma_f32 v[16:17], v[68:69], v[108:109], v[16:17] op_sel_hi:[1,0,1]
	v_pk_fma_f32 v[30:31], v[66:67], v[108:109], v[30:31] op_sel_hi:[1,0,1]
	v_pk_fma_f32 v[22:23], v[4:5], v[100:101], v[22:23] op_sel_hi:[1,0,1]
	v_pk_fma_f32 v[34:35], v[2:3], v[100:101], v[34:35] op_sel_hi:[1,0,1]
	v_pk_fma_f32 v[20:21], v[4:5], v[102:103], v[20:21] op_sel_hi:[1,0,1]
	v_pk_fma_f32 v[32:33], v[2:3], v[102:103], v[32:33] op_sel_hi:[1,0,1]
	v_pk_fma_f32 v[18:19], v[4:5], v[104:105], v[18:19] op_sel_hi:[1,0,1]
	v_pk_fma_f32 v[28:29], v[2:3], v[104:105], v[28:29] op_sel_hi:[1,0,1]
	v_pk_fma_f32 v[8:9], v[4:5], v[106:107], v[8:9] op_sel_hi:[1,0,1]
	v_pk_fma_f32 v[26:27], v[2:3], v[106:107], v[26:27] op_sel_hi:[1,0,1]
	v_pk_fma_f32 v[4:5], v[4:5], v[110:111], v[16:17] op_sel_hi:[1,0,1]
	v_pk_fma_f32 v[2:3], v[2:3], v[110:111], v[30:31] op_sel_hi:[1,0,1]
	s_waitcnt vmcnt(2)
	v_pk_fma_f32 v[16:17], v[72:73], v[142:143], v[22:23] op_sel_hi:[1,0,1]
	v_pk_fma_f32 v[22:23], v[70:71], v[142:143], v[34:35] op_sel_hi:[1,0,1]
	v_pk_fma_f32 v[20:21], v[72:73], v[144:145], v[20:21] op_sel_hi:[1,0,1]
	v_pk_fma_f32 v[30:31], v[70:71], v[144:145], v[32:33] op_sel_hi:[1,0,1]
	v_pk_fma_f32 v[18:19], v[72:73], v[146:147], v[18:19] op_sel_hi:[1,0,1]
	v_pk_fma_f32 v[28:29], v[70:71], v[146:147], v[28:29] op_sel_hi:[1,0,1]
	v_pk_fma_f32 v[8:9], v[72:73], v[148:149], v[8:9] op_sel_hi:[1,0,1]
	v_pk_fma_f32 v[26:27], v[70:71], v[148:149], v[26:27] op_sel_hi:[1,0,1]
	v_pk_fma_f32 v[4:5], v[72:73], v[112:113], v[4:5] op_sel_hi:[1,0,1]
	v_pk_fma_f32 v[2:3], v[70:71], v[112:113], v[2:3] op_sel_hi:[1,0,1]
	s_waitcnt vmcnt(1)
	v_pk_fma_f32 v[16:17], v[76:77], v[114:115], v[16:17] op_sel_hi:[1,0,1]
	v_pk_fma_f32 v[32:33], v[74:75], v[114:115], v[22:23] op_sel_hi:[1,0,1]
	v_pk_fma_f32 v[20:21], v[76:77], v[116:117], v[20:21] op_sel_hi:[1,0,1]
	v_pk_fma_f32 v[30:31], v[74:75], v[116:117], v[30:31] op_sel_hi:[1,0,1]
	v_pk_fma_f32 v[18:19], v[76:77], v[118:119], v[18:19] op_sel_hi:[1,0,1]
	v_pk_fma_f32 v[28:29], v[74:75], v[118:119], v[28:29] op_sel_hi:[1,0,1]
	v_pk_fma_f32 v[8:9], v[76:77], v[120:121], v[8:9] op_sel_hi:[1,0,1]
	v_pk_fma_f32 v[26:27], v[74:75], v[120:121], v[26:27] op_sel_hi:[1,0,1]
	s_waitcnt lgkmcnt(1)
	v_pk_fma_f32 v[4:5], v[76:77], v[122:123], v[4:5] op_sel_hi:[1,0,1]
	v_pk_fma_f32 v[2:3], v[74:75], v[122:123], v[2:3] op_sel_hi:[1,0,1]
	s_waitcnt vmcnt(0)
	v_pk_fma_f32 v[22:23], v[80:81], v[150:151], v[16:17] op_sel_hi:[1,0,1]
	v_pk_fma_f32 v[34:35], v[78:79], v[150:151], v[32:33] op_sel_hi:[1,0,1]
	v_pk_fma_f32 v[20:21], v[80:81], v[152:153], v[20:21] op_sel_hi:[1,0,1]
	v_pk_fma_f32 v[32:33], v[78:79], v[152:153], v[30:31] op_sel_hi:[1,0,1]
	v_pk_fma_f32 v[18:19], v[80:81], v[154:155], v[18:19] op_sel_hi:[1,0,1]
	v_pk_fma_f32 v[28:29], v[78:79], v[154:155], v[28:29] op_sel_hi:[1,0,1]
	v_pk_fma_f32 v[8:9], v[80:81], v[156:157], v[8:9] op_sel_hi:[1,0,1]
	v_pk_fma_f32 v[26:27], v[78:79], v[156:157], v[26:27] op_sel_hi:[1,0,1]
	s_waitcnt lgkmcnt(0)
	v_pk_fma_f32 v[16:17], v[80:81], v[124:125], v[4:5] op_sel_hi:[1,0,1]
	v_pk_fma_f32 v[30:31], v[78:79], v[124:125], v[2:3] op_sel_hi:[1,0,1]
	s_cbranch_scc1 .LBB0_18
	ds_bpermute_b32 v38, v51, v26
	ds_bpermute_b32 v39, v51, v27
	ds_bpermute_b32 v2, v51, v34
	ds_bpermute_b32 v24, v51, v32
	ds_bpermute_b32 v3, v51, v35
	ds_bpermute_b32 v36, v51, v28
	ds_bpermute_b32 v40, v51, v30
	ds_bpermute_b32 v25, v51, v33
	ds_bpermute_b32 v37, v51, v29
	ds_bpermute_b32 v41, v51, v31
	s_waitcnt lgkmcnt(8)
	v_pk_add_f32 v[26:27], v[26:27], v[38:39]
	ds_bpermute_b32 v38, v51, v22
	ds_bpermute_b32 v42, v51, v20
	ds_bpermute_b32 v39, v51, v23
	ds_bpermute_b32 v44, v51, v18
	ds_bpermute_b32 v46, v51, v8
	ds_bpermute_b32 v48, v51, v16
	ds_bpermute_b32 v43, v51, v21
	ds_bpermute_b32 v45, v51, v19
	ds_bpermute_b32 v47, v51, v9
	ds_bpermute_b32 v49, v51, v17
	s_waitcnt lgkmcnt(14)
	v_pk_add_f32 v[2:3], v[34:35], v[2:3]
	s_waitcnt lgkmcnt(12)
	v_pk_add_f32 v[24:25], v[32:33], v[24:25]
	s_waitcnt lgkmcnt(11)
	v_pk_add_f32 v[28:29], v[28:29], v[36:37]
	s_waitcnt lgkmcnt(10)
	v_pk_add_f32 v[30:31], v[30:31], v[40:41]
	s_waitcnt lgkmcnt(7)
	v_pk_add_f32 v[22:23], v[22:23], v[38:39]
	s_waitcnt lgkmcnt(3)
	v_pk_add_f32 v[20:21], v[20:21], v[42:43]
	s_waitcnt lgkmcnt(2)
	v_pk_add_f32 v[18:19], v[18:19], v[44:45]
	s_waitcnt lgkmcnt(1)
	v_pk_add_f32 v[8:9], v[8:9], v[46:47]
	s_waitcnt lgkmcnt(0)
	v_pk_add_f32 v[16:17], v[16:17], v[48:49]
	ds_bpermute_b32 v4, v52, v2
	ds_bpermute_b32 v5, v52, v3
	ds_bpermute_b32 v32, v52, v24
	ds_bpermute_b32 v33, v52, v25
	ds_bpermute_b32 v34, v52, v28
	ds_bpermute_b32 v35, v52, v29
	ds_bpermute_b32 v36, v52, v26
	ds_bpermute_b32 v37, v52, v27
	ds_bpermute_b32 v40, v52, v30
	ds_bpermute_b32 v41, v52, v31
	ds_bpermute_b32 v38, v52, v22
	ds_bpermute_b32 v39, v52, v23
	ds_bpermute_b32 v42, v52, v20
	ds_bpermute_b32 v43, v52, v21
	ds_bpermute_b32 v44, v52, v18
	ds_bpermute_b32 v45, v52, v19
	ds_bpermute_b32 v46, v52, v8
	ds_bpermute_b32 v47, v52, v9
	ds_bpermute_b32 v48, v52, v16
	ds_bpermute_b32 v49, v52, v17
	s_and_saveexec_b64 s[0:1], s[4:5]
	s_cbranch_execz .LBB0_21
	s_mul_i32 s12, s12, 0x1e000
	s_add_u32 s12, s6, s12
	s_addc_u32 s13, s7, 0
	v_lshlrev_b32_e32 v10, 2, v6
	s_waitcnt lgkmcnt(0)
	v_pk_add_f32 v[68:69], v[16:17], v[48:49]
	v_pk_add_f32 v[48:49], v[8:9], v[46:47]
	v_pk_add_f32 v[46:47], v[26:27], v[36:37]
	v_pk_add_f32 v[26:27], v[20:21], v[42:43]
	v_pk_add_f32 v[20:21], v[2:3], v[4:5]
	v_lshl_add_u64 v[2:3], s[12:13], 0, v[10:11]
	v_add_co_u32_e32 v4, vcc, s69, v2
	v_pk_add_f32 v[24:25], v[24:25], v[32:33]
	s_nop 0
	v_addc_co_u32_e32 v5, vcc, 0, v3, vcc
	global_store_dwordx4 v[4:5], v[24:27], off sc1
	v_add_co_u32_e32 v4, vcc, 0xc000, v2
	v_pk_add_f32 v[18:19], v[18:19], v[44:45]
	v_pk_add_f32 v[16:17], v[28:29], v[34:35]
	v_addc_co_u32_e32 v5, vcc, 0, v3, vcc
	global_store_dwordx4 v[4:5], v[16:19], off sc1
	v_add_co_u32_e32 v4, vcc, 0x12000, v2
	v_pk_add_f32 v[66:67], v[30:31], v[40:41]
	s_nop 0
	v_addc_co_u32_e32 v5, vcc, 0, v3, vcc
	v_add_co_u32_e32 v2, vcc, 0x18000, v2
	v_pk_add_f32 v[22:23], v[22:23], v[38:39]
	s_nop 0
	v_addc_co_u32_e32 v3, vcc, 0, v3, vcc
	global_store_dwordx4 v10, v[20:23], s[12:13] sc1
	global_store_dwordx4 v[4:5], v[46:49], off sc1
	global_store_dwordx4 v[2:3], v[66:69], off sc1

; #define LAS __attribute__((address_space(3)))
; __device__ __forceinline__ unsigned pk2(float lo, float hi) { const f32x2cv v = {lo, hi}; const bf16x2cv b = __builtin_convertvector(v, bf16x2cv); return __builtin_bit_cast(unsigned, b); }
; #define LDS_WAIT() asm volatile("s_waitcnt lgkmcnt(0)" ::: "memory")
; __device__ __forceinline__ void transpose_item(const float* W, int K, int N, bf16* WT, int dst_row0, int k0, int n0, LAS float* scr, int lane) {
; #pragma unroll
;     for (int i = 0; i < 8; ++i) { const int kk = 8 * i + (lane >> 3), c4 = 4 * (lane & 7), n = n0 + c4;
;         const f32x4 v = (n < N) ? *(const f32x4*)(W + (size_t)(k0 + kk) * N + n) : (f32x4){0.f, 0.f, 0.f, 0.f};
;         scr[kk * 33 + c4] = v.x; scr[kk * 33 + c4 + 1] = v.y; scr[kk * 33 + c4 + 2] = v.z; scr[kk * 33 + c4 + 3] = v.w; }
;     LDS_WAIT(); asm volatile("" ::: "memory");
;     const int c = lane & 7;
; #pragma unroll
;     for (int j = 0; j < 4; ++j) { const int n = (lane >> 3) + 8 * j; const LAS float* s = scr + (8 * c) * 33 + n;
;         v4u o; o.x = pk2(s[0 * 33], s[1 * 33]); o.y = pk2(s[2 * 33], s[3 * 33]); o.z = pk2(s[4 * 33], s[5 * 33]); o.w = pk2(s[6 * 33], s[7 * 33]);
;         *(v4u*)(WT + (size_t)(dst_row0 + n) * K + k0 + 8 * c) = o; }
;     LDS_WAIT(); asm volatile("" ::: "memory");
.LBB0_22:
	s_mov_b32 s3, 0
	s_and_b64 vcc, exec, s[0:1]
	s_cbranch_vccz .LBB0_24
	s_load_dwordx8 s[88:95], s[20:21], 0xc0
	s_lshl_b32 s0, s34, 5
	s_and_b32 s0, s0, 0x3e0
	s_lshl_b32 s1, s34, 1
	s_and_b32 s1, s1, 0xfc0
	v_or_b32_e32 v2, s0, v54
	s_add_i32 s14, s1, 0xfffff4c0
	v_lshlrev_b32_e32 v10, 2, v2
	s_waitcnt lgkmcnt(0)
	v_lshl_add_u64 v[36:37], s[88:89], 0, v[10:11]
	v_or_b32_e32 v10, s14, v53
	v_lshlrev_b64 v[2:3], 12, v[10:11]
	v_or_b32_e32 v10, s14, v57
	v_lshlrev_b64 v[4:5], 12, v[10:11]
	v_or_b32_e32 v10, s14, v58
	v_lshlrev_b64 v[16:17], 12, v[10:11]
	v_or_b32_e32 v10, s14, v59
	v_lshlrev_b64 v[18:19], 12, v[10:11]
	v_or_b32_e32 v10, s14, v60
	v_lshlrev_b64 v[24:25], 12, v[10:11]
	v_or_b32_e32 v10, s14, v61
	v_lshlrev_b64 v[26:27], 12, v[10:11]
	v_lshl_add_u64 v[2:3], v[36:37], 0, v[2:3]
	v_lshl_add_u64 v[6:7], v[36:37], 0, v[4:5]
	v_lshl_add_u64 v[16:17], v[36:37], 0, v[16:17]
	v_lshl_add_u64 v[20:21], v[36:37], 0, v[18:19]
	v_lshl_add_u64 v[24:25], v[36:37], 0, v[24:25]
	v_lshl_add_u64 v[28:29], v[36:37], 0, v[26:27]
	global_load_dwordx4 v[2:5], v[2:3], off
	s_nop 0
	global_load_dwordx4 v[6:9], v[6:7], off
	s_nop 0
	global_load_dwordx4 v[16:19], v[16:17], off
	s_nop 0
	global_load_dwordx4 v[20:23], v[20:21], off
	s_nop 0
	global_load_dwordx4 v[24:27], v[24:25], off
	s_nop 0
	global_load_dwordx4 v[28:31], v[28:29], off
	v_or_b32_e32 v10, s14, v62
	v_lshlrev_b64 v[32:33], 12, v[10:11]
	v_lshl_add_u64 v[32:33], v[36:37], 0, v[32:33]
	v_or_b32_e32 v10, s14, v63
	global_load_dwordx4 v[32:35], v[32:33], off
	v_lshlrev_b64 v[38:39], 12, v[10:11]
	v_lshl_add_u64 v[36:37], v[36:37], 0, v[38:39]
	global_load_dwordx4 v[36:39], v[36:37], off
	v_add_u32_e32 v46, v55, v56
	v_add_u32_e32 v47, 0x420, v46
	v_add_u32_e32 v48, 0x428, v46
	v_add_u32_e32 v49, 0x840, v46
	v_add_u32_e32 v66, 0x848, v46
	v_add_u32_e32 v67, 0xc60, v46
	v_add_u32_e32 v68, 0xc68, v46
	v_add_u32_e32 v69, 0x1080, v46
	v_add_u32_e32 v70, 0x1088, v46
	v_add_u32_e32 v71, 0x14a0, v46
	v_add_u32_e32 v72, 0x14a8, v46
	v_add_u32_e32 v73, 0x18c0, v46
	v_add_u32_e32 v74, 0x18c8, v46
	v_add_u32_e32 v75, 0x1ce0, v46
	v_add_u32_e32 v76, 0x1ce8, v46
	v_or_b32_e32 v10, s0, v53
	v_or_b32_e32 v44, s0, v57
	v_lshl_add_u64 v[40:41], s[14:15], 1, v[12:13]
	v_lshlrev_b32_e32 v10, 11, v10
	v_lshl_add_u64 v[42:43], v[40:41], 0, v[10:11]
	v_lshlrev_b32_e32 v10, 11, v44
	v_lshl_add_u64 v[44:45], v[40:41], 0, v[10:11]
	s_mov_b32 s3, 7
	s_waitcnt vmcnt(7)
	ds_write2_b32 v46, v2, v3 offset1:1
	ds_write2_b32 v46, v4, v5 offset0:2 offset1:3
	s_waitcnt vmcnt(6)
	ds_write2_b32 v47, v6, v7 offset1:1
	ds_write2_b32 v48, v8, v9 offset1:1
	s_waitcnt vmcnt(5)
	ds_write2_b32 v49, v16, v17 offset1:1
	ds_write2_b32 v66, v18, v19 offset1:1
	s_waitcnt vmcnt(4)
	ds_write2_b32 v67, v20, v21 offset1:1
	ds_write2_b32 v68, v22, v23 offset1:1
	s_waitcnt vmcnt(3)
	ds_write2_b32 v69, v24, v25 offset1:1
	ds_write2_b32 v70, v26, v27 offset1:1
	s_waitcnt vmcnt(2)
	ds_write2_b32 v71, v28, v29 offset1:1
	ds_write2_b32 v72, v30, v31 offset1:1
	s_waitcnt vmcnt(1)
	ds_write2_b32 v73, v32, v33 offset1:1
	ds_write2_b32 v74, v34, v35 offset1:1
	s_waitcnt vmcnt(0)
	ds_write2_b32 v75, v36, v37 offset1:1
	ds_write2_b32 v76, v38, v39 offset1:1
	s_waitcnt lgkmcnt(0)
	ds_read2_b32 v[6:7], v64 offset0:33 offset1:41
	ds_read2_b32 v[8:9], v64 offset1:8
	ds_read2_b32 v[16:17], v64 offset0:66 offset1:74
	ds_read2_b32 v[18:19], v64 offset0:99 offset1:107
	ds_read2_b32 v[20:21], v64 offset0:132 offset1:140
	ds_read2_b32 v[22:23], v64 offset0:165 offset1:173
	ds_read2_b32 v[24:25], v64 offset0:198 offset1:206
	ds_read2_b32 v[26:27], v64 offset0:231 offset1:239
	ds_read2_b32 v[28:29], v64 offset0:49 offset1:57
	ds_read2_b32 v[30:31], v64 offset0:16 offset1:24
	ds_read2_b32 v[32:33], v64 offset0:82 offset1:90
	ds_read2_b32 v[34:35], v64 offset0:115 offset1:123
	ds_read2_b32 v[36:37], v64 offset0:148 offset1:156
	ds_read2_b32 v[38:39], v64 offset0:181 offset1:189
	ds_read2_b32 v[46:47], v64 offset0:214 offset1:222
	s_waitcnt lgkmcnt(13)
	v_cvt_pk_bf16_f32 v2, v8, v6
	s_waitcnt lgkmcnt(11)
	v_cvt_pk_bf16_f32 v3, v16, v18
	v_cvt_pk_bf16_f32 v6, v9, v7
	v_cvt_pk_bf16_f32 v7, v17, v19
	ds_read2_b32 v[16:17], v64 offset0:247 offset1:255
	s_waitcnt lgkmcnt(10)
	v_cvt_pk_bf16_f32 v8, v21, v23
	s_waitcnt lgkmcnt(8)
	v_cvt_pk_bf16_f32 v9, v25, v27
	global_store_dwordx4 v[44:45], v[6:9], off sc1
	v_cvt_pk_bf16_f32 v4, v20, v22
	v_cvt_pk_bf16_f32 v5, v24, v26
	v_or_b32_e32 v6, s0, v58
	v_lshlrev_b32_e32 v10, 11, v6
	global_store_dwordx4 v[42:43], v[2:5], off sc1
	v_lshl_add_u64 v[6:7], v[40:41], 0, v[10:11]
	s_waitcnt lgkmcnt(6)
	v_cvt_pk_bf16_f32 v2, v30, v28
	s_waitcnt lgkmcnt(4)
	v_cvt_pk_bf16_f32 v3, v32, v34
	s_waitcnt lgkmcnt(2)
	v_cvt_pk_bf16_f32 v4, v36, v38
	s_waitcnt lgkmcnt(0)
	v_cvt_pk_bf16_f32 v5, v46, v16
	global_store_dwordx4 v[6:7], v[2:5], off sc1
	v_or_b32_e32 v6, s0, v59
	v_lshlrev_b32_e32 v10, 11, v6
	v_cvt_pk_bf16_f32 v2, v31, v29
	v_cvt_pk_bf16_f32 v3, v33, v35
	v_cvt_pk_bf16_f32 v4, v37, v39
	v_cvt_pk_bf16_f32 v5, v47, v17
	v_lshl_add_u64 v[6:7], v[40:41], 0, v[10:11]
	global_store_dwordx4 v[6:7], v[2:5], off sc1
	s_waitcnt lgkmcnt(0)

; #define LAS __attribute__((address_space(3)))
; __device__ __forceinline__ unsigned pk2(float lo, float hi) { const f32x2cv v = {lo, hi}; const bf16x2cv b = __builtin_convertvector(v, bf16x2cv); return __builtin_bit_cast(unsigned, b); }
; #define LDS_WAIT() asm volatile("s_waitcnt lgkmcnt(0)" ::: "memory")
; __device__ __forceinline__ void transpose_item(const float* W, int K, int N, bf16* WT, int dst_row0, int k0, int n0, LAS float* scr, int lane) {
; #pragma unroll
;     for (int i = 0; i < 8; ++i) { const int kk = 8 * i + (lane >> 3), c4 = 4 * (lane & 7), n = n0 + c4;
;         const f32x4 v = (n < N) ? *(const f32x4*)(W + (size_t)(k0 + kk) * N + n) : (f32x4){0.f, 0.f, 0.f, 0.f};
;         scr[kk * 33 + c4] = v.x; scr[kk * 33 + c4 + 1] = v.y; scr[kk * 33 + c4 + 2] = v.z; scr[kk * 33 + c4 + 3] = v.w; }
;     LDS_WAIT(); asm volatile("" ::: "memory");
;     const int c = lane & 7;
; #pragma unroll
;     for (int j = 0; j < 4; ++j) { const int n = (lane >> 3) + 8 * j; const LAS float* s = scr + (8 * c) * 33 + n;
;         v4u o; o.x = pk2(s[0 * 33], s[1 * 33]); o.y = pk2(s[2 * 33], s[3 * 33]); o.z = pk2(s[4 * 33], s[5 * 33]); o.w = pk2(s[6 * 33], s[7 * 33]);
;         *(v4u*)(WT + (size_t)(dst_row0 + n) * K + k0 + 8 * c) = o; }
;     LDS_WAIT(); asm volatile("" ::: "memory");
.LBB0_39:
	s_or_b64 exec, exec, s[0:1]
	v_add_u32_e32 v16, 0x18c0, v10
	s_waitcnt vmcnt(1)
	ds_write2_b32 v16, v6, v7 offset1:1
	v_add_u32_e32 v6, 0x18c8, v10
	ds_write2_b32 v6, v8, v9 offset1:1
	v_add_u32_e32 v6, 0x1ce0, v10
	s_waitcnt vmcnt(0)
	ds_write2_b32 v6, v2, v3 offset1:1
	v_add_u32_e32 v2, 0x1ce8, v10
	ds_write2_b32 v2, v4, v5 offset1:1
	s_waitcnt lgkmcnt(0)
	ds_read2_b32 v[6:7], v64 offset0:33 offset1:41
	ds_read2_b32 v[8:9], v64 offset1:8
	ds_read2_b32 v[16:17], v64 offset0:66 offset1:74
	ds_read2_b32 v[18:19], v64 offset0:99 offset1:107
	ds_read2_b32 v[20:21], v64 offset0:132 offset1:140
	ds_read2_b32 v[22:23], v64 offset0:165 offset1:173
	ds_read2_b32 v[24:25], v64 offset0:198 offset1:206
	ds_read2_b32 v[26:27], v64 offset0:231 offset1:239
	v_add_u32_e32 v30, s12, v53
	s_ashr_i32 s83, s82, 31
	v_ashrrev_i32_e32 v31, 31, v30
	v_lshl_add_u64 v[28:29], s[82:83], 1, v[14:15]
	v_lshlrev_b64 v[30:31], 11, v[30:31]
	s_waitcnt lgkmcnt(6)
	v_cvt_pk_bf16_f32 v2, v8, v6
	s_waitcnt lgkmcnt(4)
	v_cvt_pk_bf16_f32 v3, v16, v18
	s_waitcnt lgkmcnt(2)
	v_cvt_pk_bf16_f32 v4, v20, v22
	s_waitcnt lgkmcnt(0)
	v_cvt_pk_bf16_f32 v5, v24, v26
	v_lshl_add_u64 v[30:31], v[28:29], 0, v[30:31]
	v_add_u32_e32 v6, s12, v57
	global_store_dwordx4 v[30:31], v[2:5], off sc1
	s_mov_b32 s3, 7
	s_nop 0
	v_cvt_pk_bf16_f32 v2, v9, v7
	v_ashrrev_i32_e32 v7, 31, v6
	v_cvt_pk_bf16_f32 v3, v17, v19
	v_cvt_pk_bf16_f32 v4, v21, v23
	v_cvt_pk_bf16_f32 v5, v25, v27
	v_lshlrev_b64 v[6:7], 11, v[6:7]
	ds_read2_b32 v[8:9], v64 offset0:49 offset1:57
	ds_read2_b32 v[16:17], v64 offset0:16 offset1:24
	ds_read2_b32 v[18:19], v64 offset0:82 offset1:90
	ds_read2_b32 v[20:21], v64 offset0:115 offset1:123
	ds_read2_b32 v[22:23], v64 offset0:148 offset1:156
	ds_read2_b32 v[24:25], v64 offset0:181 offset1:189
	ds_read2_b32 v[26:27], v64 offset0:214 offset1:222
	ds_read2_b32 v[30:31], v64 offset0:247 offset1:255
	v_lshl_add_u64 v[6:7], v[28:29], 0, v[6:7]
	global_store_dwordx4 v[6:7], v[2:5], off sc1
	v_add_u32_e32 v6, s12, v58
	v_ashrrev_i32_e32 v7, 31, v6
	v_lshlrev_b64 v[6:7], 11, v[6:7]
	s_waitcnt lgkmcnt(6)
	v_cvt_pk_bf16_f32 v2, v16, v8
	s_waitcnt lgkmcnt(4)
	v_cvt_pk_bf16_f32 v3, v18, v20
	s_waitcnt lgkmcnt(2)
	v_cvt_pk_bf16_f32 v4, v22, v24
	s_waitcnt lgkmcnt(0)
	v_cvt_pk_bf16_f32 v5, v26, v30
	v_lshl_add_u64 v[6:7], v[28:29], 0, v[6:7]
	global_store_dwordx4 v[6:7], v[2:5], off sc1
	v_add_u32_e32 v6, s12, v59
	v_ashrrev_i32_e32 v7, 31, v6
	v_lshlrev_b64 v[6:7], 11, v[6:7]
	v_cvt_pk_bf16_f32 v2, v17, v9
	v_cvt_pk_bf16_f32 v3, v19, v21
	v_cvt_pk_bf16_f32 v4, v23, v25
	v_cvt_pk_bf16_f32 v5, v27, v31
	v_lshl_add_u64 v[6:7], v[28:29], 0, v[6:7]
	global_store_dwordx4 v[6:7], v[2:5], off sc1
	s_waitcnt lgkmcnt(0)

; __device__ __forceinline__ unsigned cvt_pk_bf16(float lo, float hi) { unsigned r; asm volatile("v_cvt_pk_bf16_f32 %0, %1, %2" : "=v"(r) : "v"(lo), "v"(hi)); return r; }
; __device__ __forceinline__ float silu_f(float x) { return x * __builtin_amdgcn_rcpf(1.0f + __expf(-x)); }
;     __device__ __forceinline__ void operator()(const f32x4 (&acc)[2][2][4][2], const Unit& u, int wr, int wc, int fr, int fq) const {
;         const int row0 = u.pm * BM + wr * 64 + fr;
; #pragma unroll
;         for (int bj = 0; bj < 2; ++bj) {
;             const int col0 = u.pn * BM + bj * HALF + wc * 32 + 8 * fq;
;             if (col0 >= 2880) continue;
;             const float sc = (col0 < 256) ? 0.125f : 1.0f;
; #pragma unroll
;             for (int ai = 0; ai < 2; ++ai)
; #pragma unroll
;                 for (int m = 0; m < 4; ++m) {
;                     f32x4 v0 = acc[ai][bj][m][0] * sc, v1 = acc[ai][bj][m][1] * sc;
;                     if (col0 >= 1024 && col0 < 2048) {
; #pragma unroll
;                         for (int e = 0; e < 4; ++e) { v0[e] = silu_f(v0[e]); v1[e] = silu_f(v1[e]); } }
;                     u32x4 w; w.x = cvt_pk_bf16(v0[0], v0[1]); w.y = cvt_pk_bf16(v0[2], v0[3]); w.z = cvt_pk_bf16(v1[0], v1[1]); w.w = cvt_pk_bf16(v1[2], v1[3]);
;                     *(u32x4*)(O + (size_t)(row0 + ai * HALF + m * 16) * 2880 + col0) = w;
;                 }
;         }
.LBB0_276:
	v_cvt_pk_bf16_f32 v126, v126, v127
	v_cvt_pk_bf16_f32 v127, v128, v129
	s_nop 0
	v_cvt_pk_bf16_f32 v128, v122, v123
	v_mov_b64_e32 v[122:123], s[18:19]
	v_ashrrev_i32_e32 v147, 31, v146
	v_mad_i64_i32 v[122:123], s[0:1], v156, s95, v[122:123]
	v_lshl_add_u64 v[122:123], v[146:147], 1, v[122:123]
	v_mov_b32_e32 v149, v148
	v_cvt_pk_bf16_f32 v129, v124, v125
	global_store_dwordx4 v[122:123], v[126:129], off sc1
	v_mov_b32_e32 v122, v148
	v_mov_b32_e32 v123, v148
	v_cndmask_b32_e64 v124, 0, 1, s[90:91]
	v_pk_mul_f32 v[120:121], v[122:123], v[120:121]
	v_pk_mul_f32 v[118:119], v[148:149], v[118:119]
	v_pk_mul_f32 v[116:117], v[122:123], v[116:117]
	v_cmp_ne_u32_e64 s[6:7], 1, v124
	s_andn2_b64 vcc, exec, s[90:91]
	v_pk_mul_f32 v[114:115], v[148:149], v[114:115]
	s_cbranch_vccnz .LBB0_278
	v_mul_f32_e32 v125, 0xbfb8aa3b, v114
	v_mul_f32_e32 v126, 0xbfb8aa3b, v119
	v_exp_f32_e32 v125, v125
	v_exp_f32_e32 v127, v126
	v_mul_f32_e32 v129, 0xbfb8aa3b, v116
	v_mul_f32_e32 v124, 0xbfb8aa3b, v118
	v_add_f32_e32 v125, 1.0, v125
	v_rcp_f32_e32 v126, v125
	v_add_f32_e32 v125, 1.0, v127
	v_mul_f32_e32 v127, 0xbfb8aa3b, v115
	v_mul_f32_e32 v128, 0xbfb8aa3b, v120
	v_exp_f32_e32 v129, v129
	v_mul_f32_e32 v157, 0xbfb8aa3b, v121
	v_mul_f32_e32 v158, 0xbfb8aa3b, v117
	v_exp_f32_e32 v124, v124
	v_exp_f32_e32 v127, v127
	v_exp_f32_e32 v128, v128
	v_exp_f32_e32 v157, v157
	v_exp_f32_e32 v159, v158
	v_add_f32_e32 v129, 1.0, v129
	v_add_f32_e32 v124, 1.0, v124
	v_add_f32_e32 v127, 1.0, v127
	v_add_f32_e32 v128, 1.0, v128
	v_rcp_f32_e32 v158, v129
	v_add_f32_e32 v129, 1.0, v157
	v_add_f32_e32 v157, 1.0, v159
	v_rcp_f32_e32 v124, v124
	v_rcp_f32_e32 v125, v125
	v_rcp_f32_e32 v128, v128
	v_rcp_f32_e32 v129, v129
	v_rcp_f32_e32 v159, v157
	v_rcp_f32_e32 v127, v127
	v_pk_mul_f32 v[118:119], v[118:119], v[124:125]
	v_pk_mul_f32 v[120:121], v[120:121], v[128:129]
	v_pk_mul_f32 v[116:117], v[116:117], v[158:159]
	v_pk_mul_f32 v[114:115], v[114:115], v[126:127]
.LBB0_278:
	v_cvt_pk_bf16_f32 v118, v118, v119
	v_cvt_pk_bf16_f32 v119, v120, v121
	s_nop 0
	v_cvt_pk_bf16_f32 v120, v114, v115
	v_cvt_pk_bf16_f32 v121, v116, v117
	v_or_b32_e32 v116, 16, v156
	v_mov_b64_e32 v[114:115], s[18:19]
	v_mad_i64_i32 v[114:115], s[0:1], v116, s95, v[114:115]
	v_lshl_add_u64 v[114:115], v[146:147], 1, v[114:115]
	v_pk_mul_f32 v[112:113], v[122:123], v[112:113]
	v_pk_mul_f32 v[110:111], v[148:149], v[110:111]
	v_pk_mul_f32 v[108:109], v[122:123], v[108:109]
	s_and_b64 vcc, exec, s[6:7]
	v_pk_mul_f32 v[106:107], v[148:149], v[106:107]
	global_store_dwordx4 v[114:115], v[118:121], off sc1
	s_cbranch_vccnz .LBB0_280
	v_mul_f32_e32 v115, 0xbfb8aa3b, v106
	v_mul_f32_e32 v116, 0xbfb8aa3b, v111
	v_exp_f32_e32 v115, v115
	v_exp_f32_e32 v117, v116
	v_mul_f32_e32 v119, 0xbfb8aa3b, v108
	v_mul_f32_e32 v120, 0xbfb8aa3b, v113
	v_add_f32_e32 v115, 1.0, v115
	v_mul_f32_e32 v114, 0xbfb8aa3b, v110
	v_rcp_f32_e32 v116, v115
	v_add_f32_e32 v115, 1.0, v117
	v_mul_f32_e32 v117, 0xbfb8aa3b, v107
	v_mul_f32_e32 v118, 0xbfb8aa3b, v112
	v_exp_f32_e32 v119, v119
	v_exp_f32_e32 v121, v120
	v_mul_f32_e32 v120, 0xbfb8aa3b, v109
	v_exp_f32_e32 v114, v114
	v_exp_f32_e32 v117, v117
	v_exp_f32_e32 v118, v118
	v_exp_f32_e32 v122, v120
	v_add_f32_e32 v119, 1.0, v119
	v_add_f32_e32 v114, 1.0, v114
	v_add_f32_e32 v117, 1.0, v117
	v_add_f32_e32 v118, 1.0, v118
	v_rcp_f32_e32 v120, v119
	v_add_f32_e32 v119, 1.0, v121
	v_add_f32_e32 v121, 1.0, v122
	v_rcp_f32_e32 v114, v114
	v_rcp_f32_e32 v115, v115
	v_rcp_f32_e32 v118, v118
	v_rcp_f32_e32 v119, v119
	v_rcp_f32_e32 v121, v121
	v_rcp_f32_e32 v117, v117
	v_pk_mul_f32 v[110:111], v[110:111], v[114:115]
	v_pk_mul_f32 v[112:113], v[112:113], v[118:119]
	v_pk_mul_f32 v[108:109], v[108:109], v[120:121]
	v_pk_mul_f32 v[106:107], v[106:107], v[116:117]
.LBB0_280:
	v_cvt_pk_bf16_f32 v110, v110, v111
	v_cvt_pk_bf16_f32 v111, v112, v113
	s_nop 0
	v_cvt_pk_bf16_f32 v112, v106, v107
	v_cvt_pk_bf16_f32 v113, v108, v109
	v_or_b32_e32 v108, 32, v156
	v_mov_b64_e32 v[106:107], s[18:19]
	v_mad_i64_i32 v[106:107], s[0:1], v108, s95, v[106:107]
	v_lshl_add_u64 v[106:107], v[146:147], 1, v[106:107]
	global_store_dwordx4 v[106:107], v[110:113], off sc1
	v_mov_b32_e32 v106, v148
	v_mov_b32_e32 v107, v148
	v_pk_mul_f32 v[104:105], v[106:107], v[104:105]
	v_pk_mul_f32 v[102:103], v[148:149], v[102:103]
	v_pk_mul_f32 v[100:101], v[106:107], v[100:101]
	s_and_b64 vcc, exec, s[6:7]
	v_pk_mul_f32 v[98:99], v[148:149], v[98:99]
	s_cbranch_vccnz .LBB0_282
	v_mul_f32_e32 v109, 0xbfb8aa3b, v98
	v_mul_f32_e32 v110, 0xbfb8aa3b, v103
	v_exp_f32_e32 v109, v109
	v_exp_f32_e32 v111, v110
	v_mul_f32_e32 v113, 0xbfb8aa3b, v100
	v_mul_f32_e32 v114, 0xbfb8aa3b, v105
	v_add_f32_e32 v109, 1.0, v109
	v_mul_f32_e32 v108, 0xbfb8aa3b, v102
	v_rcp_f32_e32 v110, v109
	v_add_f32_e32 v109, 1.0, v111
	v_mul_f32_e32 v111, 0xbfb8aa3b, v99
	v_mul_f32_e32 v112, 0xbfb8aa3b, v104
	v_exp_f32_e32 v113, v113
	v_exp_f32_e32 v115, v114
	v_mul_f32_e32 v114, 0xbfb8aa3b, v101
	v_exp_f32_e32 v108, v108
	v_exp_f32_e32 v111, v111
	v_exp_f32_e32 v112, v112
	v_exp_f32_e32 v116, v114
	v_add_f32_e32 v113, 1.0, v113
	v_add_f32_e32 v108, 1.0, v108
	v_add_f32_e32 v111, 1.0, v111
	v_add_f32_e32 v112, 1.0, v112
	v_rcp_f32_e32 v114, v113
	v_add_f32_e32 v113, 1.0, v115
	v_add_f32_e32 v115, 1.0, v116
	v_rcp_f32_e32 v108, v108
	v_rcp_f32_e32 v109, v109
	v_rcp_f32_e32 v112, v112
	v_rcp_f32_e32 v113, v113
	v_rcp_f32_e32 v115, v115
	v_rcp_f32_e32 v111, v111
	v_pk_mul_f32 v[102:103], v[102:103], v[108:109]
	v_pk_mul_f32 v[104:105], v[104:105], v[112:113]
	v_pk_mul_f32 v[100:101], v[100:101], v[114:115]
	v_pk_mul_f32 v[98:99], v[98:99], v[110:111]
; __device__ __forceinline__ unsigned cvt_pk_bf16(float lo, float hi) { unsigned r; asm volatile("v_cvt_pk_bf16_f32 %0, %1, %2" : "=v"(r) : "v"(lo), "v"(hi)); return r; }
; __device__ __forceinline__ float silu_f(float x) { return x * __builtin_amdgcn_rcpf(1.0f + __expf(-x)); }
;     __device__ __forceinline__ void operator()(const f32x4 (&acc)[2][2][4][2], const Unit& u, int wr, int wc, int fr, int fq) const {
;         const int row0 = u.pm * BM + wr * 64 + fr;
; #pragma unroll
;         for (int bj = 0; bj < 2; ++bj) {
;             const int col0 = u.pn * BM + bj * HALF + wc * 32 + 8 * fq;
;             if (col0 >= 2880) continue;
;             const float sc = (col0 < 256) ? 0.125f : 1.0f;
; #pragma unroll
;             for (int ai = 0; ai < 2; ++ai)
; #pragma unroll
;                 for (int m = 0; m < 4; ++m) {
;                     f32x4 v0 = acc[ai][bj][m][0] * sc, v1 = acc[ai][bj][m][1] * sc;
;                     if (col0 >= 1024 && col0 < 2048) {
; #pragma unroll
;                         for (int e = 0; e < 4; ++e) { v0[e] = silu_f(v0[e]); v1[e] = silu_f(v1[e]); } }
;                     u32x4 w; w.x = cvt_pk_bf16(v0[0], v0[1]); w.y = cvt_pk_bf16(v0[2], v0[3]); w.z = cvt_pk_bf16(v1[0], v1[1]); w.w = cvt_pk_bf16(v1[2], v1[3]);
;                     *(u32x4*)(O + (size_t)(row0 + ai * HALF + m * 16) * 2880 + col0) = w;
;                 }
;         }
.LBB0_282:
	v_cvt_pk_bf16_f32 v102, v102, v103
	v_cvt_pk_bf16_f32 v103, v104, v105
	s_nop 0
	v_cvt_pk_bf16_f32 v104, v98, v99
	v_cvt_pk_bf16_f32 v105, v100, v101
	v_or_b32_e32 v100, 48, v156
	v_mov_b64_e32 v[98:99], s[18:19]
	v_mad_i64_i32 v[98:99], s[0:1], v100, s95, v[98:99]
	v_lshl_add_u64 v[98:99], v[146:147], 1, v[98:99]
	v_pk_mul_f32 v[96:97], v[106:107], v[96:97]
	v_pk_mul_f32 v[94:95], v[148:149], v[94:95]
	v_pk_mul_f32 v[92:93], v[106:107], v[92:93]
	s_and_b64 vcc, exec, s[6:7]
	v_pk_mul_f32 v[90:91], v[148:149], v[90:91]
	global_store_dwordx4 v[98:99], v[102:105], off sc1
	s_cbranch_vccnz .LBB0_284
	v_mul_f32_e32 v99, 0xbfb8aa3b, v90
	v_mul_f32_e32 v100, 0xbfb8aa3b, v95
	v_exp_f32_e32 v99, v99
	v_exp_f32_e32 v101, v100
	v_mul_f32_e32 v103, 0xbfb8aa3b, v92
	v_mul_f32_e32 v104, 0xbfb8aa3b, v97
	v_add_f32_e32 v99, 1.0, v99
	v_mul_f32_e32 v98, 0xbfb8aa3b, v94
	v_rcp_f32_e32 v100, v99
	v_add_f32_e32 v99, 1.0, v101
	v_mul_f32_e32 v101, 0xbfb8aa3b, v91
	v_mul_f32_e32 v102, 0xbfb8aa3b, v96
	v_exp_f32_e32 v103, v103
	v_exp_f32_e32 v105, v104
	v_mul_f32_e32 v104, 0xbfb8aa3b, v93
	v_exp_f32_e32 v98, v98
	v_exp_f32_e32 v101, v101
	v_exp_f32_e32 v102, v102
	v_exp_f32_e32 v106, v104
	v_add_f32_e32 v103, 1.0, v103
	v_add_f32_e32 v98, 1.0, v98
	v_add_f32_e32 v101, 1.0, v101
	v_add_f32_e32 v102, 1.0, v102
	v_rcp_f32_e32 v104, v103
	v_add_f32_e32 v103, 1.0, v105
	v_add_f32_e32 v105, 1.0, v106
	v_rcp_f32_e32 v98, v98
	v_rcp_f32_e32 v99, v99
	v_rcp_f32_e32 v102, v102
	v_rcp_f32_e32 v103, v103
	v_rcp_f32_e32 v105, v105
	v_rcp_f32_e32 v101, v101
	v_pk_mul_f32 v[94:95], v[94:95], v[98:99]
	v_pk_mul_f32 v[96:97], v[96:97], v[102:103]
	v_pk_mul_f32 v[92:93], v[92:93], v[104:105]
	v_pk_mul_f32 v[90:91], v[90:91], v[100:101]
.LBB0_284:
	v_add_u32_e32 v98, 0x80, v156
	v_cvt_pk_bf16_f32 v94, v94, v95
	v_cvt_pk_bf16_f32 v95, v96, v97
	v_cvt_pk_bf16_f32 v96, v90, v91
	v_mov_b64_e32 v[90:91], s[18:19]
	v_mad_i64_i32 v[90:91], s[0:1], v98, s95, v[90:91]
	v_lshl_add_u64 v[90:91], v[146:147], 1, v[90:91]
	v_cvt_pk_bf16_f32 v97, v92, v93
	global_store_dwordx4 v[90:91], v[94:97], off sc1
	v_mov_b32_e32 v90, v148
	v_mov_b32_e32 v91, v148
	v_pk_mul_f32 v[88:89], v[90:91], v[88:89]
	v_pk_mul_f32 v[86:87], v[148:149], v[86:87]
	v_pk_mul_f32 v[84:85], v[90:91], v[84:85]
	s_and_b64 vcc, exec, s[6:7]
	v_pk_mul_f32 v[82:83], v[148:149], v[82:83]
	s_cbranch_vccnz .LBB0_286
	v_mul_f32_e32 v93, 0xbfb8aa3b, v82
	v_mul_f32_e32 v94, 0xbfb8aa3b, v87
	v_exp_f32_e32 v93, v93
	v_exp_f32_e32 v95, v94
	v_mul_f32_e32 v97, 0xbfb8aa3b, v84
	v_mul_f32_e32 v98, 0xbfb8aa3b, v89
	v_add_f32_e32 v93, 1.0, v93
	v_mul_f32_e32 v92, 0xbfb8aa3b, v86
	v_rcp_f32_e32 v94, v93
	v_add_f32_e32 v93, 1.0, v95
	v_mul_f32_e32 v95, 0xbfb8aa3b, v83
	v_mul_f32_e32 v96, 0xbfb8aa3b, v88
	v_exp_f32_e32 v97, v97
	v_exp_f32_e32 v99, v98
	v_mul_f32_e32 v98, 0xbfb8aa3b, v85
	v_exp_f32_e32 v92, v92
	v_exp_f32_e32 v95, v95
	v_exp_f32_e32 v96, v96
	v_exp_f32_e32 v100, v98
	v_add_f32_e32 v97, 1.0, v97
	v_add_f32_e32 v92, 1.0, v92
	v_add_f32_e32 v95, 1.0, v95
	v_add_f32_e32 v96, 1.0, v96
	v_rcp_f32_e32 v98, v97
	v_add_f32_e32 v97, 1.0, v99
	v_add_f32_e32 v99, 1.0, v100
	v_rcp_f32_e32 v92, v92
	v_rcp_f32_e32 v93, v93
	v_rcp_f32_e32 v96, v96
	v_rcp_f32_e32 v97, v97
	v_rcp_f32_e32 v99, v99
	v_rcp_f32_e32 v95, v95
	v_pk_mul_f32 v[86:87], v[86:87], v[92:93]
	v_pk_mul_f32 v[88:89], v[88:89], v[96:97]
	v_pk_mul_f32 v[84:85], v[84:85], v[98:99]
	v_pk_mul_f32 v[82:83], v[82:83], v[94:95]
; __device__ __forceinline__ unsigned cvt_pk_bf16(float lo, float hi) { unsigned r; asm volatile("v_cvt_pk_bf16_f32 %0, %1, %2" : "=v"(r) : "v"(lo), "v"(hi)); return r; }
; __device__ __forceinline__ float silu_f(float x) { return x * __builtin_amdgcn_rcpf(1.0f + __expf(-x)); }
;     __device__ __forceinline__ void operator()(const f32x4 (&acc)[2][2][4][2], const Unit& u, int wr, int wc, int fr, int fq) const {
;         const int row0 = u.pm * BM + wr * 64 + fr;
; #pragma unroll
;         for (int bj = 0; bj < 2; ++bj) {
;             const int col0 = u.pn * BM + bj * HALF + wc * 32 + 8 * fq;
;             if (col0 >= 2880) continue;
;             const float sc = (col0 < 256) ? 0.125f : 1.0f;
; #pragma unroll
;             for (int ai = 0; ai < 2; ++ai)
; #pragma unroll
;                 for (int m = 0; m < 4; ++m) {
;                     f32x4 v0 = acc[ai][bj][m][0] * sc, v1 = acc[ai][bj][m][1] * sc;
;                     if (col0 >= 1024 && col0 < 2048) {
; #pragma unroll
;                         for (int e = 0; e < 4; ++e) { v0[e] = silu_f(v0[e]); v1[e] = silu_f(v1[e]); } }
;                     u32x4 w; w.x = cvt_pk_bf16(v0[0], v0[1]); w.y = cvt_pk_bf16(v0[2], v0[3]); w.z = cvt_pk_bf16(v1[0], v1[1]); w.w = cvt_pk_bf16(v1[2], v1[3]);
;                     *(u32x4*)(O + (size_t)(row0 + ai * HALF + m * 16) * 2880 + col0) = w;
;                 }
;         }
.LBB0_286:
	v_cvt_pk_bf16_f32 v86, v86, v87
	v_cvt_pk_bf16_f32 v87, v88, v89
	s_nop 0
	v_cvt_pk_bf16_f32 v88, v82, v83
	v_cvt_pk_bf16_f32 v89, v84, v85
	v_add_u32_e32 v84, 0x90, v156
	v_mov_b64_e32 v[82:83], s[18:19]
	v_mad_i64_i32 v[82:83], s[0:1], v84, s95, v[82:83]
	v_lshl_add_u64 v[82:83], v[146:147], 1, v[82:83]
	v_pk_mul_f32 v[80:81], v[90:91], v[80:81]
	v_pk_mul_f32 v[78:79], v[148:149], v[78:79]
	v_pk_mul_f32 v[76:77], v[90:91], v[76:77]
	s_and_b64 vcc, exec, s[6:7]
	v_pk_mul_f32 v[74:75], v[148:149], v[74:75]
	global_store_dwordx4 v[82:83], v[86:89], off sc1
	s_cbranch_vccnz .LBB0_288
	v_mul_f32_e32 v83, 0xbfb8aa3b, v74
	v_mul_f32_e32 v84, 0xbfb8aa3b, v79
	v_exp_f32_e32 v83, v83
	v_exp_f32_e32 v85, v84
	v_mul_f32_e32 v87, 0xbfb8aa3b, v76
	v_mul_f32_e32 v88, 0xbfb8aa3b, v81
	v_add_f32_e32 v83, 1.0, v83
	v_mul_f32_e32 v82, 0xbfb8aa3b, v78
	v_rcp_f32_e32 v84, v83
	v_add_f32_e32 v83, 1.0, v85
	v_mul_f32_e32 v85, 0xbfb8aa3b, v75
	v_mul_f32_e32 v86, 0xbfb8aa3b, v80
	v_exp_f32_e32 v87, v87
	v_exp_f32_e32 v89, v88
	v_mul_f32_e32 v88, 0xbfb8aa3b, v77
	v_exp_f32_e32 v82, v82
	v_exp_f32_e32 v85, v85
	v_exp_f32_e32 v86, v86
	v_exp_f32_e32 v90, v88
	v_add_f32_e32 v87, 1.0, v87
	v_add_f32_e32 v82, 1.0, v82
	v_add_f32_e32 v85, 1.0, v85
	v_add_f32_e32 v86, 1.0, v86
	v_rcp_f32_e32 v88, v87
	v_add_f32_e32 v87, 1.0, v89
	v_add_f32_e32 v89, 1.0, v90
	v_rcp_f32_e32 v82, v82
	v_rcp_f32_e32 v83, v83
	v_rcp_f32_e32 v86, v86
	v_rcp_f32_e32 v87, v87
	v_rcp_f32_e32 v89, v89
	v_rcp_f32_e32 v85, v85
	v_pk_mul_f32 v[78:79], v[78:79], v[82:83]
	v_pk_mul_f32 v[80:81], v[80:81], v[86:87]
	v_pk_mul_f32 v[76:77], v[76:77], v[88:89]
	v_pk_mul_f32 v[74:75], v[74:75], v[84:85]
.LBB0_288:
	v_cvt_pk_bf16_f32 v78, v78, v79
	v_cvt_pk_bf16_f32 v79, v80, v81
	s_nop 0
	v_cvt_pk_bf16_f32 v80, v74, v75
	v_cvt_pk_bf16_f32 v81, v76, v77
	v_add_u32_e32 v76, 0xa0, v156
	v_mov_b64_e32 v[74:75], s[18:19]
	v_mad_i64_i32 v[74:75], s[0:1], v76, s95, v[74:75]
	v_lshl_add_u64 v[74:75], v[146:147], 1, v[74:75]
	global_store_dwordx4 v[74:75], v[78:81], off sc1
	v_mov_b32_e32 v74, v148
	v_mov_b32_e32 v75, v148
	v_pk_mul_f32 v[72:73], v[74:75], v[72:73]
	v_pk_mul_f32 v[70:71], v[148:149], v[70:71]
	v_pk_mul_f32 v[68:69], v[74:75], v[68:69]
	s_and_b64 vcc, exec, s[6:7]
	v_pk_mul_f32 v[66:67], v[148:149], v[66:67]
	s_cbranch_vccnz .LBB0_290
	v_mul_f32_e32 v75, 0xbfb8aa3b, v66
	v_mul_f32_e32 v76, 0xbfb8aa3b, v71
	v_exp_f32_e32 v75, v75
	v_exp_f32_e32 v77, v76
	v_mul_f32_e32 v79, 0xbfb8aa3b, v68
	v_mul_f32_e32 v80, 0xbfb8aa3b, v73
	v_add_f32_e32 v75, 1.0, v75
	v_mul_f32_e32 v74, 0xbfb8aa3b, v70
	v_rcp_f32_e32 v76, v75
	v_add_f32_e32 v75, 1.0, v77
	v_mul_f32_e32 v77, 0xbfb8aa3b, v67
	v_mul_f32_e32 v78, 0xbfb8aa3b, v72
	v_exp_f32_e32 v79, v79
	v_exp_f32_e32 v81, v80
	v_mul_f32_e32 v80, 0xbfb8aa3b, v69
	v_exp_f32_e32 v74, v74
	v_exp_f32_e32 v77, v77
	v_exp_f32_e32 v78, v78
	v_exp_f32_e32 v82, v80
	v_add_f32_e32 v79, 1.0, v79
	v_add_f32_e32 v74, 1.0, v74
	v_add_f32_e32 v77, 1.0, v77
	v_add_f32_e32 v78, 1.0, v78
	v_rcp_f32_e32 v80, v79
	v_add_f32_e32 v79, 1.0, v81
	v_add_f32_e32 v81, 1.0, v82
	v_rcp_f32_e32 v74, v74
	v_rcp_f32_e32 v75, v75
	v_rcp_f32_e32 v78, v78
	v_rcp_f32_e32 v79, v79
	v_rcp_f32_e32 v81, v81
	v_rcp_f32_e32 v77, v77
	v_pk_mul_f32 v[70:71], v[70:71], v[74:75]
	v_pk_mul_f32 v[72:73], v[72:73], v[78:79]
	v_pk_mul_f32 v[68:69], v[68:69], v[80:81]
	v_pk_mul_f32 v[66:67], v[66:67], v[76:77]
.LBB0_290:
	v_cvt_pk_bf16_f32 v70, v70, v71
	v_cvt_pk_bf16_f32 v71, v72, v73
	s_nop 0
	v_cvt_pk_bf16_f32 v72, v66, v67
	v_cvt_pk_bf16_f32 v73, v68, v69
	v_add_u32_e32 v68, 0xb0, v156
	v_mov_b64_e32 v[66:67], s[18:19]
	v_mad_i64_i32 v[66:67], s[0:1], v68, s95, v[66:67]
	v_lshl_add_u64 v[66:67], v[146:147], 1, v[66:67]
	global_store_dwordx4 v[66:67], v[70:73], off sc1

; __device__ __forceinline__ unsigned cvt_pk_bf16(float lo, float hi) { unsigned r; asm volatile("v_cvt_pk_bf16_f32 %0, %1, %2" : "=v"(r) : "v"(lo), "v"(hi)); return r; }
; __device__ __forceinline__ float silu_f(float x) { return x * __builtin_amdgcn_rcpf(1.0f + __expf(-x)); }
;     __device__ __forceinline__ void operator()(const f32x4 (&acc)[2][2][4][2], const Unit& u, int wr, int wc, int fr, int fq) const {
;         const int row0 = u.pm * BM + wr * 64 + fr;
; #pragma unroll
;         for (int bj = 0; bj < 2; ++bj) {
;             const int col0 = u.pn * BM + bj * HALF + wc * 32 + 8 * fq;
;             if (col0 >= 2880) continue;
;             const float sc = (col0 < 256) ? 0.125f : 1.0f;
; #pragma unroll
;             for (int ai = 0; ai < 2; ++ai)
; #pragma unroll
;                 for (int m = 0; m < 4; ++m) {
;                     f32x4 v0 = acc[ai][bj][m][0] * sc, v1 = acc[ai][bj][m][1] * sc;
;                     if (col0 >= 1024 && col0 < 2048) {
; #pragma unroll
;                         for (int e = 0; e < 4; ++e) { v0[e] = silu_f(v0[e]); v1[e] = silu_f(v1[e]); } }
;                     u32x4 w; w.x = cvt_pk_bf16(v0[0], v0[1]); w.y = cvt_pk_bf16(v0[2], v0[3]); w.z = cvt_pk_bf16(v1[0], v1[1]); w.w = cvt_pk_bf16(v1[2], v1[3]);
;                     *(u32x4*)(O + (size_t)(row0 + ai * HALF + m * 16) * 2880 + col0) = w;
;                 }
;         }
.LBB0_294:
	v_cvt_pk_bf16_f32 v62, v62, v63
	v_cvt_pk_bf16_f32 v63, v64, v65
	s_nop 0
	v_cvt_pk_bf16_f32 v64, v58, v59
	v_mov_b64_e32 v[58:59], s[18:19]
	v_mad_i64_i32 v[58:59], s[0:1], v156, s95, v[58:59]
	v_ashrrev_i32_e32 v147, 31, v146
	v_lshl_add_u64 v[58:59], v[146:147], 1, v[58:59]
	v_mov_b32_e32 v67, v66
	v_cvt_pk_bf16_f32 v65, v60, v61
	global_store_dwordx4 v[58:59], v[62:65], off offset:256 sc1
	v_mov_b32_e32 v58, v66
	v_mov_b32_e32 v59, v66
	v_cndmask_b32_e64 v60, 0, 1, s[86:87]
	v_pk_mul_f32 v[56:57], v[58:59], v[56:57]
	v_pk_mul_f32 v[54:55], v[66:67], v[54:55]
	v_pk_mul_f32 v[52:53], v[58:59], v[52:53]
	v_cmp_ne_u32_e64 s[6:7], 1, v60
	s_andn2_b64 vcc, exec, s[86:87]
	v_pk_mul_f32 v[50:51], v[66:67], v[50:51]
	s_cbranch_vccnz .LBB0_296
	v_mul_f32_e32 v61, 0xbfb8aa3b, v50
	v_mul_f32_e32 v62, 0xbfb8aa3b, v55
	v_exp_f32_e32 v61, v61
	v_exp_f32_e32 v63, v62
	v_mul_f32_e32 v65, 0xbfb8aa3b, v52
	v_mul_f32_e32 v68, 0xbfb8aa3b, v57
	v_add_f32_e32 v61, 1.0, v61
	v_mul_f32_e32 v60, 0xbfb8aa3b, v54
	v_rcp_f32_e32 v62, v61
	v_add_f32_e32 v61, 1.0, v63
	v_mul_f32_e32 v63, 0xbfb8aa3b, v51
	v_mul_f32_e32 v64, 0xbfb8aa3b, v56
	v_exp_f32_e32 v65, v65
	v_exp_f32_e32 v69, v68
	v_mul_f32_e32 v68, 0xbfb8aa3b, v53
	v_exp_f32_e32 v60, v60
	v_exp_f32_e32 v63, v63
	v_exp_f32_e32 v64, v64
	v_exp_f32_e32 v70, v68
	v_add_f32_e32 v65, 1.0, v65
	v_add_f32_e32 v60, 1.0, v60
	v_add_f32_e32 v63, 1.0, v63
	v_add_f32_e32 v64, 1.0, v64
	v_rcp_f32_e32 v68, v65
	v_add_f32_e32 v65, 1.0, v69
	v_add_f32_e32 v69, 1.0, v70
	v_rcp_f32_e32 v60, v60
	v_rcp_f32_e32 v61, v61
	v_rcp_f32_e32 v64, v64
	v_rcp_f32_e32 v65, v65
	v_rcp_f32_e32 v69, v69
	v_rcp_f32_e32 v63, v63
	v_pk_mul_f32 v[54:55], v[54:55], v[60:61]
	v_pk_mul_f32 v[56:57], v[56:57], v[64:65]
	v_pk_mul_f32 v[52:53], v[52:53], v[68:69]
	v_pk_mul_f32 v[50:51], v[50:51], v[62:63]
.LBB0_296:
	v_cvt_pk_bf16_f32 v54, v54, v55
	v_cvt_pk_bf16_f32 v55, v56, v57
	s_nop 0
	v_cvt_pk_bf16_f32 v56, v50, v51
	v_cvt_pk_bf16_f32 v57, v52, v53
	v_or_b32_e32 v52, 16, v156
	v_mov_b64_e32 v[50:51], s[18:19]
	v_mad_i64_i32 v[50:51], s[0:1], v52, s95, v[50:51]
	v_lshl_add_u64 v[50:51], v[146:147], 1, v[50:51]
	v_pk_mul_f32 v[48:49], v[58:59], v[48:49]
	v_pk_mul_f32 v[46:47], v[66:67], v[46:47]
	v_pk_mul_f32 v[44:45], v[58:59], v[44:45]
	s_and_b64 vcc, exec, s[6:7]
	v_pk_mul_f32 v[42:43], v[66:67], v[42:43]
	global_store_dwordx4 v[50:51], v[54:57], off offset:256 sc1
	s_cbranch_vccnz .LBB0_298
	v_mul_f32_e32 v51, 0xbfb8aa3b, v42
	v_mul_f32_e32 v52, 0xbfb8aa3b, v47
	v_exp_f32_e32 v51, v51
	v_exp_f32_e32 v53, v52
	v_mul_f32_e32 v55, 0xbfb8aa3b, v44
	v_mul_f32_e32 v56, 0xbfb8aa3b, v49
	v_add_f32_e32 v51, 1.0, v51
	v_mul_f32_e32 v50, 0xbfb8aa3b, v46
	v_rcp_f32_e32 v52, v51
	v_add_f32_e32 v51, 1.0, v53
	v_mul_f32_e32 v53, 0xbfb8aa3b, v43
	v_mul_f32_e32 v54, 0xbfb8aa3b, v48
	v_exp_f32_e32 v55, v55
	v_exp_f32_e32 v57, v56
	v_mul_f32_e32 v56, 0xbfb8aa3b, v45
	v_exp_f32_e32 v50, v50
	v_exp_f32_e32 v53, v53
	v_exp_f32_e32 v54, v54
	v_exp_f32_e32 v58, v56
	v_add_f32_e32 v55, 1.0, v55
	v_add_f32_e32 v50, 1.0, v50
	v_add_f32_e32 v53, 1.0, v53
	v_add_f32_e32 v54, 1.0, v54
	v_rcp_f32_e32 v56, v55
	v_add_f32_e32 v55, 1.0, v57
	v_add_f32_e32 v57, 1.0, v58
	v_rcp_f32_e32 v50, v50
	v_rcp_f32_e32 v51, v51
	v_rcp_f32_e32 v54, v54
	v_rcp_f32_e32 v55, v55
	v_rcp_f32_e32 v57, v57
	v_rcp_f32_e32 v53, v53
	v_pk_mul_f32 v[46:47], v[46:47], v[50:51]
	v_pk_mul_f32 v[48:49], v[48:49], v[54:55]
	v_pk_mul_f32 v[44:45], v[44:45], v[56:57]
	v_pk_mul_f32 v[42:43], v[42:43], v[52:53]
.LBB0_298:
	v_cvt_pk_bf16_f32 v46, v46, v47
	v_cvt_pk_bf16_f32 v47, v48, v49
	s_nop 0
	v_cvt_pk_bf16_f32 v48, v42, v43
	v_cvt_pk_bf16_f32 v49, v44, v45
	v_or_b32_e32 v44, 32, v156
	v_mov_b64_e32 v[42:43], s[18:19]
	v_mad_i64_i32 v[42:43], s[0:1], v44, s95, v[42:43]
	v_lshl_add_u64 v[42:43], v[146:147], 1, v[42:43]
	global_store_dwordx4 v[42:43], v[46:49], off offset:256 sc1
	v_mov_b32_e32 v42, v66
	v_mov_b32_e32 v43, v66
	v_pk_mul_f32 v[40:41], v[42:43], v[40:41]
	v_pk_mul_f32 v[38:39], v[66:67], v[38:39]
	v_pk_mul_f32 v[36:37], v[42:43], v[36:37]
	s_and_b64 vcc, exec, s[6:7]
	v_pk_mul_f32 v[34:35], v[66:67], v[34:35]
	s_cbranch_vccnz .LBB0_300
	v_mul_f32_e32 v45, 0xbfb8aa3b, v34
	v_mul_f32_e32 v46, 0xbfb8aa3b, v39
	v_exp_f32_e32 v45, v45
	v_exp_f32_e32 v47, v46
	v_mul_f32_e32 v49, 0xbfb8aa3b, v36
	v_mul_f32_e32 v50, 0xbfb8aa3b, v41
	v_add_f32_e32 v45, 1.0, v45
	v_mul_f32_e32 v44, 0xbfb8aa3b, v38
	v_rcp_f32_e32 v46, v45
	v_add_f32_e32 v45, 1.0, v47
	v_mul_f32_e32 v47, 0xbfb8aa3b, v35
	v_mul_f32_e32 v48, 0xbfb8aa3b, v40
	v_exp_f32_e32 v49, v49
	v_exp_f32_e32 v51, v50
	v_mul_f32_e32 v50, 0xbfb8aa3b, v37
	v_exp_f32_e32 v44, v44
	v_exp_f32_e32 v47, v47
	v_exp_f32_e32 v48, v48
	v_exp_f32_e32 v52, v50
	v_add_f32_e32 v49, 1.0, v49
	v_add_f32_e32 v44, 1.0, v44
	v_add_f32_e32 v47, 1.0, v47
	v_add_f32_e32 v48, 1.0, v48
	v_rcp_f32_e32 v50, v49
	v_add_f32_e32 v49, 1.0, v51
	v_add_f32_e32 v51, 1.0, v52
	v_rcp_f32_e32 v44, v44
	v_rcp_f32_e32 v45, v45
	v_rcp_f32_e32 v48, v48
	v_rcp_f32_e32 v49, v49
	v_rcp_f32_e32 v51, v51
	v_rcp_f32_e32 v47, v47
	v_pk_mul_f32 v[38:39], v[38:39], v[44:45]
	v_pk_mul_f32 v[40:41], v[40:41], v[48:49]
	v_pk_mul_f32 v[36:37], v[36:37], v[50:51]
	v_pk_mul_f32 v[34:35], v[34:35], v[46:47]
; __device__ __forceinline__ unsigned cvt_pk_bf16(float lo, float hi) { unsigned r; asm volatile("v_cvt_pk_bf16_f32 %0, %1, %2" : "=v"(r) : "v"(lo), "v"(hi)); return r; }
; __device__ __forceinline__ float silu_f(float x) { return x * __builtin_amdgcn_rcpf(1.0f + __expf(-x)); }
;     __device__ __forceinline__ void operator()(const f32x4 (&acc)[2][2][4][2], const Unit& u, int wr, int wc, int fr, int fq) const {
;         const int row0 = u.pm * BM + wr * 64 + fr;
; #pragma unroll
;         for (int bj = 0; bj < 2; ++bj) {
;             const int col0 = u.pn * BM + bj * HALF + wc * 32 + 8 * fq;
;             if (col0 >= 2880) continue;
;             const float sc = (col0 < 256) ? 0.125f : 1.0f;
; #pragma unroll
;             for (int ai = 0; ai < 2; ++ai)
; #pragma unroll
;                 for (int m = 0; m < 4; ++m) {
;                     f32x4 v0 = acc[ai][bj][m][0] * sc, v1 = acc[ai][bj][m][1] * sc;
;                     if (col0 >= 1024 && col0 < 2048) {
; #pragma unroll
;                         for (int e = 0; e < 4; ++e) { v0[e] = silu_f(v0[e]); v1[e] = silu_f(v1[e]); } }
;                     u32x4 w; w.x = cvt_pk_bf16(v0[0], v0[1]); w.y = cvt_pk_bf16(v0[2], v0[3]); w.z = cvt_pk_bf16(v1[0], v1[1]); w.w = cvt_pk_bf16(v1[2], v1[3]);
;                     *(u32x4*)(O + (size_t)(row0 + ai * HALF + m * 16) * 2880 + col0) = w;
;                 }
;         }
.LBB0_300:
	v_cvt_pk_bf16_f32 v38, v38, v39
	v_cvt_pk_bf16_f32 v39, v40, v41
	s_nop 0
	v_cvt_pk_bf16_f32 v40, v34, v35
	v_cvt_pk_bf16_f32 v41, v36, v37
	v_or_b32_e32 v36, 48, v156
	v_mov_b64_e32 v[34:35], s[18:19]
	v_mad_i64_i32 v[34:35], s[0:1], v36, s95, v[34:35]
	v_lshl_add_u64 v[34:35], v[146:147], 1, v[34:35]
	v_pk_mul_f32 v[32:33], v[42:43], v[32:33]
	v_pk_mul_f32 v[30:31], v[66:67], v[30:31]
	v_pk_mul_f32 v[28:29], v[42:43], v[28:29]
	s_and_b64 vcc, exec, s[6:7]
	v_pk_mul_f32 v[26:27], v[66:67], v[26:27]
	global_store_dwordx4 v[34:35], v[38:41], off offset:256 sc1
	s_cbranch_vccnz .LBB0_302
	v_mul_f32_e32 v35, 0xbfb8aa3b, v26
	v_mul_f32_e32 v36, 0xbfb8aa3b, v31
	v_exp_f32_e32 v35, v35
	v_exp_f32_e32 v37, v36
	v_mul_f32_e32 v39, 0xbfb8aa3b, v28
	v_mul_f32_e32 v40, 0xbfb8aa3b, v33
	v_add_f32_e32 v35, 1.0, v35
	v_mul_f32_e32 v34, 0xbfb8aa3b, v30
	v_rcp_f32_e32 v36, v35
	v_add_f32_e32 v35, 1.0, v37
	v_mul_f32_e32 v37, 0xbfb8aa3b, v27
	v_mul_f32_e32 v38, 0xbfb8aa3b, v32
	v_exp_f32_e32 v39, v39
	v_exp_f32_e32 v41, v40
	v_mul_f32_e32 v40, 0xbfb8aa3b, v29
	v_exp_f32_e32 v34, v34
	v_exp_f32_e32 v37, v37
	v_exp_f32_e32 v38, v38
	v_exp_f32_e32 v42, v40
	v_add_f32_e32 v39, 1.0, v39
	v_add_f32_e32 v34, 1.0, v34
	v_add_f32_e32 v37, 1.0, v37
	v_add_f32_e32 v38, 1.0, v38
	v_rcp_f32_e32 v40, v39
	v_add_f32_e32 v39, 1.0, v41
	v_add_f32_e32 v41, 1.0, v42
	v_rcp_f32_e32 v34, v34
	v_rcp_f32_e32 v35, v35
	v_rcp_f32_e32 v38, v38
	v_rcp_f32_e32 v39, v39
	v_rcp_f32_e32 v41, v41
	v_rcp_f32_e32 v37, v37
	v_pk_mul_f32 v[30:31], v[30:31], v[34:35]
	v_pk_mul_f32 v[32:33], v[32:33], v[38:39]
	v_pk_mul_f32 v[28:29], v[28:29], v[40:41]
	v_pk_mul_f32 v[26:27], v[26:27], v[36:37]
.LBB0_302:
	v_add_u32_e32 v34, 0x80, v156
	v_cvt_pk_bf16_f32 v30, v30, v31
	v_cvt_pk_bf16_f32 v31, v32, v33
	v_cvt_pk_bf16_f32 v32, v26, v27
	v_mov_b64_e32 v[26:27], s[18:19]
	v_mad_i64_i32 v[26:27], s[0:1], v34, s95, v[26:27]
	v_lshl_add_u64 v[26:27], v[146:147], 1, v[26:27]
	v_cvt_pk_bf16_f32 v33, v28, v29
	global_store_dwordx4 v[26:27], v[30:33], off offset:256 sc1
	v_mov_b32_e32 v26, v66
	v_mov_b32_e32 v27, v66
	v_pk_mul_f32 v[24:25], v[26:27], v[24:25]
	v_pk_mul_f32 v[22:23], v[66:67], v[22:23]
	v_pk_mul_f32 v[20:21], v[26:27], v[20:21]
	s_and_b64 vcc, exec, s[6:7]
	v_pk_mul_f32 v[18:19], v[66:67], v[18:19]
	s_cbranch_vccnz .LBB0_304
	v_mul_f32_e32 v29, 0xbfb8aa3b, v18
	v_mul_f32_e32 v30, 0xbfb8aa3b, v23
	v_exp_f32_e32 v29, v29
	v_exp_f32_e32 v31, v30
	v_mul_f32_e32 v33, 0xbfb8aa3b, v20
	v_mul_f32_e32 v34, 0xbfb8aa3b, v25
	v_add_f32_e32 v29, 1.0, v29
	v_mul_f32_e32 v28, 0xbfb8aa3b, v22
	v_rcp_f32_e32 v30, v29
	v_add_f32_e32 v29, 1.0, v31
	v_mul_f32_e32 v31, 0xbfb8aa3b, v19
	v_mul_f32_e32 v32, 0xbfb8aa3b, v24
	v_exp_f32_e32 v33, v33
	v_exp_f32_e32 v35, v34
	v_mul_f32_e32 v34, 0xbfb8aa3b, v21
	v_exp_f32_e32 v28, v28
	v_exp_f32_e32 v31, v31
	v_exp_f32_e32 v32, v32
	v_exp_f32_e32 v36, v34
	v_add_f32_e32 v33, 1.0, v33
	v_add_f32_e32 v28, 1.0, v28
	v_add_f32_e32 v31, 1.0, v31
	v_add_f32_e32 v32, 1.0, v32
	v_rcp_f32_e32 v34, v33
	v_add_f32_e32 v33, 1.0, v35
	v_add_f32_e32 v35, 1.0, v36
	v_rcp_f32_e32 v28, v28
	v_rcp_f32_e32 v29, v29
	v_rcp_f32_e32 v32, v32
	v_rcp_f32_e32 v33, v33
	v_rcp_f32_e32 v35, v35
	v_rcp_f32_e32 v31, v31
	v_pk_mul_f32 v[22:23], v[22:23], v[28:29]
	v_pk_mul_f32 v[24:25], v[24:25], v[32:33]
	v_pk_mul_f32 v[20:21], v[20:21], v[34:35]
	v_pk_mul_f32 v[18:19], v[18:19], v[30:31]
; __device__ __forceinline__ unsigned cvt_pk_bf16(float lo, float hi) { unsigned r; asm volatile("v_cvt_pk_bf16_f32 %0, %1, %2" : "=v"(r) : "v"(lo), "v"(hi)); return r; }
; __device__ __forceinline__ float silu_f(float x) { return x * __builtin_amdgcn_rcpf(1.0f + __expf(-x)); }
;     __device__ __forceinline__ void operator()(const f32x4 (&acc)[2][2][4][2], const Unit& u, int wr, int wc, int fr, int fq) const {
;         const int row0 = u.pm * BM + wr * 64 + fr;
; #pragma unroll
;         for (int bj = 0; bj < 2; ++bj) {
;             const int col0 = u.pn * BM + bj * HALF + wc * 32 + 8 * fq;
;             if (col0 >= 2880) continue;
;             const float sc = (col0 < 256) ? 0.125f : 1.0f;
; #pragma unroll
;             for (int ai = 0; ai < 2; ++ai)
; #pragma unroll
;                 for (int m = 0; m < 4; ++m) {
;                     f32x4 v0 = acc[ai][bj][m][0] * sc, v1 = acc[ai][bj][m][1] * sc;
;                     if (col0 >= 1024 && col0 < 2048) {
; #pragma unroll
;                         for (int e = 0; e < 4; ++e) { v0[e] = silu_f(v0[e]); v1[e] = silu_f(v1[e]); } }
;                     u32x4 w; w.x = cvt_pk_bf16(v0[0], v0[1]); w.y = cvt_pk_bf16(v0[2], v0[3]); w.z = cvt_pk_bf16(v1[0], v1[1]); w.w = cvt_pk_bf16(v1[2], v1[3]);
;                     *(u32x4*)(O + (size_t)(row0 + ai * HALF + m * 16) * 2880 + col0) = w;
;                 }
;         }
.LBB0_304:
	v_cvt_pk_bf16_f32 v22, v22, v23
	v_cvt_pk_bf16_f32 v23, v24, v25
	s_nop 0
	v_cvt_pk_bf16_f32 v24, v18, v19
	v_cvt_pk_bf16_f32 v25, v20, v21
	v_add_u32_e32 v20, 0x90, v156
	v_mov_b64_e32 v[18:19], s[18:19]
	v_mad_i64_i32 v[18:19], s[0:1], v20, s95, v[18:19]
	v_lshl_add_u64 v[18:19], v[146:147], 1, v[18:19]
	v_pk_mul_f32 v[16:17], v[26:27], v[16:17]
	v_pk_mul_f32 v[14:15], v[66:67], v[14:15]
	v_pk_mul_f32 v[12:13], v[26:27], v[12:13]
	s_and_b64 vcc, exec, s[6:7]
	v_pk_mul_f32 v[10:11], v[66:67], v[10:11]
	global_store_dwordx4 v[18:19], v[22:25], off offset:256 sc1
	s_cbranch_vccnz .LBB0_306
	v_mul_f32_e32 v19, 0xbfb8aa3b, v10
	v_mul_f32_e32 v20, 0xbfb8aa3b, v15
	v_exp_f32_e32 v19, v19
	v_exp_f32_e32 v21, v20
	v_mul_f32_e32 v23, 0xbfb8aa3b, v12
	v_mul_f32_e32 v24, 0xbfb8aa3b, v17
	v_add_f32_e32 v19, 1.0, v19
	v_mul_f32_e32 v18, 0xbfb8aa3b, v14
	v_rcp_f32_e32 v20, v19
	v_add_f32_e32 v19, 1.0, v21
	v_mul_f32_e32 v21, 0xbfb8aa3b, v11
	v_mul_f32_e32 v22, 0xbfb8aa3b, v16
	v_exp_f32_e32 v23, v23
	v_exp_f32_e32 v25, v24
	v_mul_f32_e32 v24, 0xbfb8aa3b, v13
	v_exp_f32_e32 v18, v18
	v_exp_f32_e32 v21, v21
	v_exp_f32_e32 v22, v22
	v_exp_f32_e32 v26, v24
	v_add_f32_e32 v23, 1.0, v23
	v_add_f32_e32 v18, 1.0, v18
	v_add_f32_e32 v21, 1.0, v21
	v_add_f32_e32 v22, 1.0, v22
	v_rcp_f32_e32 v24, v23
	v_add_f32_e32 v23, 1.0, v25
	v_add_f32_e32 v25, 1.0, v26
	v_rcp_f32_e32 v18, v18
	v_rcp_f32_e32 v19, v19
	v_rcp_f32_e32 v22, v22
	v_rcp_f32_e32 v23, v23
	v_rcp_f32_e32 v25, v25
	v_rcp_f32_e32 v21, v21
	v_pk_mul_f32 v[14:15], v[14:15], v[18:19]
	v_pk_mul_f32 v[16:17], v[16:17], v[22:23]
	v_pk_mul_f32 v[12:13], v[12:13], v[24:25]
	v_pk_mul_f32 v[10:11], v[10:11], v[20:21]
.LBB0_306:
	v_cvt_pk_bf16_f32 v14, v14, v15
	v_cvt_pk_bf16_f32 v15, v16, v17
	s_nop 0
	v_cvt_pk_bf16_f32 v16, v10, v11
	v_cvt_pk_bf16_f32 v17, v12, v13
	v_add_u32_e32 v12, 0xa0, v156
	v_mov_b64_e32 v[10:11], s[18:19]
	v_mad_i64_i32 v[10:11], s[0:1], v12, s95, v[10:11]
	v_lshl_add_u64 v[10:11], v[146:147], 1, v[10:11]
	global_store_dwordx4 v[10:11], v[14:17], off offset:256 sc1
	v_mov_b32_e32 v10, v66
	v_mov_b32_e32 v11, v66
	v_pk_mul_f32 v[8:9], v[10:11], v[8:9]
	v_pk_mul_f32 v[6:7], v[66:67], v[6:7]
	v_pk_mul_f32 v[4:5], v[10:11], v[4:5]
	s_and_b64 vcc, exec, s[6:7]
	v_pk_mul_f32 v[2:3], v[66:67], v[2:3]
	s_cbranch_vccnz .LBB0_308
	v_mul_f32_e32 v11, 0xbfb8aa3b, v2
	v_mul_f32_e32 v12, 0xbfb8aa3b, v7
	v_exp_f32_e32 v11, v11
	v_exp_f32_e32 v13, v12
	v_mul_f32_e32 v15, 0xbfb8aa3b, v4
	v_mul_f32_e32 v16, 0xbfb8aa3b, v9
	v_add_f32_e32 v11, 1.0, v11
	v_mul_f32_e32 v10, 0xbfb8aa3b, v6
	v_rcp_f32_e32 v12, v11
	v_add_f32_e32 v11, 1.0, v13
	v_mul_f32_e32 v13, 0xbfb8aa3b, v3
	v_mul_f32_e32 v14, 0xbfb8aa3b, v8
	v_exp_f32_e32 v15, v15
	v_exp_f32_e32 v17, v16
	v_mul_f32_e32 v16, 0xbfb8aa3b, v5
	v_exp_f32_e32 v10, v10
	v_exp_f32_e32 v13, v13
	v_exp_f32_e32 v14, v14
	v_exp_f32_e32 v18, v16
	v_add_f32_e32 v15, 1.0, v15
	v_add_f32_e32 v10, 1.0, v10
	v_add_f32_e32 v13, 1.0, v13
	v_add_f32_e32 v14, 1.0, v14
	v_rcp_f32_e32 v16, v15
	v_add_f32_e32 v15, 1.0, v17
	v_add_f32_e32 v17, 1.0, v18
	v_rcp_f32_e32 v10, v10
	v_rcp_f32_e32 v11, v11
	v_rcp_f32_e32 v14, v14
	v_rcp_f32_e32 v15, v15
	v_rcp_f32_e32 v17, v17
	v_rcp_f32_e32 v13, v13
	v_pk_mul_f32 v[6:7], v[6:7], v[10:11]
	v_pk_mul_f32 v[8:9], v[8:9], v[14:15]
	v_pk_mul_f32 v[4:5], v[4:5], v[16:17]
	v_pk_mul_f32 v[2:3], v[2:3], v[12:13]
.LBB0_308:
	v_cvt_pk_bf16_f32 v6, v6, v7
	v_cvt_pk_bf16_f32 v7, v8, v9
	s_nop 0
	v_cvt_pk_bf16_f32 v8, v2, v3
	v_cvt_pk_bf16_f32 v9, v4, v5
	v_add_u32_e32 v4, 0xb0, v156
	v_mov_b64_e32 v[2:3], s[18:19]
	v_mad_i64_i32 v[2:3], s[0:1], v4, s95, v[2:3]
	v_lshl_add_u64 v[2:3], v[146:147], 1, v[2:3]
	global_store_dwordx4 v[2:3], v[6:9], off offset:256 sc1

; __global__ void __launch_bounds__(NT, 2) fwd_kernel(Args args) {
;     ...
;                 const int ch = it / 3, third = it % 3, ch0 = third * 256 + 8 * (tid & 31), t0 = 4 * (tid >> 5);
;                 const bool lat = ch < NCHL; const int bb = lat ? (ch >> 6) : ((ch - 256) >> 2), cc = lat ? (ch & 63) : ((ch - 256) & 3);
;                 f32x4 w[9][2];
; #pragma unroll
;                 for (int k9 = 0; k9 < 9; ++k9) { w[k9][0] = *(const f32x4*)(conv_w + k9 * 768 + ch0); w[k9][1] = *(const f32x4*)(conv_w + k9 * 768 + ch0 + 4); }
;                 const f32x4 cb0 = *(const f32x4*)(conv_b + ch0), cb1 = *(const f32x4*)(conv_b + ch0 + 4);
;                 v4u xr[3][6];
; #pragma unroll
;                 for (int dr = 0; dr < 3; ++dr)
; #pragma unroll
;                     for (int c6 = 0; c6 < 6; ++c6) {
;                         int mrow; bool ok;
;                         if (lat) { const int rr = cc + dr - 1, tt = t0 + c6 - 1; ok = (rr >= 0) && (rr < 64) && (tt >= 0) && (tt < 64);
;                             const int rc = rr < 0 ? 0 : (rr > 63 ? 63 : rr), tc = tt < 0 ? 0 : (tt > 63 ? 63 : tt); mrow = bb * SEQ + rc * 64 + tc; }
;                         else { const int tt = cc * 64 + t0 + c6 - 1; ok = (dr == 1) && (tt >= 0) && (tt < 256); const int tc = tt < 0 ? 0 : (tt > 255 ? 255 : tt); mrow = MLAT + bb * CTX + tc; }
;                         v4u xv = *(const v4u*)(PROJ + (size_t)mrow * LDP + PX + ch0);
;                         xv.x = ok ? xv.x : 0u; xv.y = ok ? xv.y : 0u; xv.z = ok ? xv.z : 0u; xv.w = ok ? xv.w : 0u;
;                         xr[dr][c6] = xv;
;                     }
.LBB0_381:
	s_waitcnt vmcnt(1)
	v_cndmask_b32_e64 v185, 0, v142, s[12:13]
	v_cndmask_b32_e64 v182, 0, v145, s[12:13]
	v_cndmask_b32_e64 v145, 0, v140, s[90:91]
	v_cndmask_b32_e64 v140, 0, v141, s[90:91]
	v_cndmask_b32_e64 v141, 0, v94, s[52:53]
	v_cndmask_b32_e64 v142, 0, v97, s[52:53]
	v_cndmask_b32_e64 v94, 0, v91, s[30:31]
	v_cndmask_b32_e64 v91, 0, v92, s[30:31]
	v_cndmask_b32_e64 v92, 0, v88, s[28:29]
	v_cndmask_b32_e64 v88, 0, v89, s[28:29]
	v_cndmask_b32_e64 v89, 0, v82, s[24:25]
	v_cndmask_b32_e64 v97, 0, v83, s[24:25]
	v_mov_b64_e32 v[82:83], s[18:19]
	v_cndmask_b32_e64 v184, 0, v143, s[12:13]
	v_cndmask_b32_e64 v183, 0, v144, s[12:13]
	v_cndmask_b32_e64 v144, 0, v95, s[52:53]
	v_cndmask_b32_e64 v143, 0, v96, s[52:53]
	v_cndmask_b32_e64 v95, 0, v90, s[30:31]
	v_cndmask_b32_e64 v90, 0, v93, s[30:31]
	v_cndmask_b32_e64 v96, 0, v86, s[28:29]
	v_cndmask_b32_e64 v93, 0, v87, s[28:29]
	v_mad_i64_i32 v[82:83], s[4:5], v166, s94, v[82:83]
	v_lshlrev_b64 v[86:87], 1, v[152:153]
	v_lshl_add_u64 v[82:83], v[82:83], 0, v[86:87]
	v_add_co_u32_e32 v82, vcc, s72, v82
	v_cndmask_b32_e64 v181, 0, v98, s[54:55]
	s_nop 0
	v_addc_co_u32_e32 v83, vcc, 0, v83, vcc
	v_cndmask_b32_e64 v180, 0, v99, s[54:55]
	v_cndmask_b32_e64 v98, 0, v84, s[24:25]
	v_cndmask_b32_e64 v99, 0, v85, s[24:25]
	global_load_dwordx4 v[82:85], v[82:83], off
	s_waitcnt vmcnt(1)
	v_cndmask_b32_e64 v171, 0, v148, s[34:35]
	v_cndmask_b32_e64 v170, 0, v149, s[34:35]
	v_lshlrev_b32_e32 v148, 16, v96
	v_and_b32_e32 v149, 0xffff0000, v96
	v_cndmask_b32_e64 v191, 0, v130, s[84:85]
	v_cndmask_b32_e64 v130, 0, v118, s[80:81]
	v_cndmask_b32_e64 v118, 0, v117, s[68:69]
	v_cndmask_b32_e64 v117, 0, v106, s[62:63]
	v_cndmask_b32_e64 v163, 0, v104, s[56:57]
	v_cndmask_b32_e64 v162, 0, v105, s[56:57]
	v_lshlrev_b32_e32 v104, 16, v95
	v_and_b32_e32 v105, 0xffff0000, v95
	v_cndmask_b32_e64 v189, 0, v132, s[84:85]
	v_cndmask_b32_e64 v132, 0, v121, s[80:81]
	v_cndmask_b32_e64 v121, 0, v110, s[66:67]
	v_lshlrev_b32_e32 v194, 16, v117
	v_and_b32_e32 v195, 0xffff0000, v117
	v_cndmask_b32_e64 v160, 0, v127, s[6:7]
	v_cndmask_b32_e64 v127, 0, v114, s[68:69]
	v_lshlrev_b32_e32 v154, 16, v121
	v_and_b32_e32 v155, 0xffff0000, v121
	v_cndmask_b32_e64 v190, 0, v131, s[84:85]
	v_cndmask_b32_e64 v131, 0, v119, s[80:81]
	v_cndmask_b32_e64 v119, 0, v116, s[68:69]
	v_cndmask_b32_e64 v116, 0, v107, s[62:63]
	v_cndmask_b32_e64 v107, 0, v108, s[62:63]
	v_cndmask_b32_e64 v106, 0, v109, s[62:63]
	v_lshlrev_b32_e32 v108, 16, v127
	v_and_b32_e32 v109, 0xffff0000, v127
	v_cndmask_b32_e64 v157, 0, v134, s[88:89]
	v_cndmask_b32_e64 v156, 0, v133, s[84:85]
	v_lshlrev_b32_e32 v198, 16, v191
	v_and_b32_e32 v199, 0xffff0000, v191
	v_cndmask_b32_e64 v187, 0, v138, s[90:91]
	v_cndmask_b32_e64 v186, 0, v139, s[90:91]
	v_cndmask_b32_e64 v139, 0, v136, s[88:89]
	v_cndmask_b32_e64 v188, 0, v137, s[88:89]
	v_cndmask_b32_e64 v161, 0, v126, s[6:7]
	v_cndmask_b32_e64 v175, 0, v124, s[82:83]
	v_cndmask_b32_e64 v174, 0, v125, s[82:83]
	v_cndmask_b32_e64 v133, 0, v120, s[80:81]
	v_cndmask_b32_e64 v126, 0, v115, s[68:69]
	v_cndmask_b32_e64 v120, 0, v111, s[66:67]
	v_cndmask_b32_e64 v111, 0, v112, s[66:67]
	v_cndmask_b32_e64 v110, 0, v113, s[66:67]
	v_lshlrev_b32_e32 v192, 16, v97
	v_and_b32_e32 v193, 0xffff0000, v97
	v_lshlrev_b32_e32 v136, 16, v93
	v_and_b32_e32 v137, 0xffff0000, v93
	v_lshlrev_b32_e32 v124, 16, v92
	v_and_b32_e32 v125, 0xffff0000, v92
	v_lshlrev_b32_e32 v114, 16, v88
	v_and_b32_e32 v115, 0xffff0000, v88
	v_lshlrev_b32_e32 v92, 16, v91
	v_and_b32_e32 v93, 0xffff0000, v91
	v_lshlrev_b32_e32 v88, 16, v90
	v_lshlrev_b32_e32 v96, 16, v119
	v_and_b32_e32 v97, 0xffff0000, v119
	v_and_b32_e32 v91, 0xffff0000, v118
	v_and_b32_e32 v119, 0xffff0000, v156
	v_cndmask_b32_e64 v173, 0, v146, s[34:35]
	v_cndmask_b32_e64 v172, 0, v147, s[34:35]
	v_cndmask_b32_e64 v138, 0, v135, s[88:89]
	v_lshlrev_b32_e32 v146, 16, v120
	v_and_b32_e32 v147, 0xffff0000, v120
	v_lshlrev_b32_e32 v134, 16, v111
	v_and_b32_e32 v135, 0xffff0000, v111
	v_lshlrev_b32_e32 v120, 16, v110
	v_and_b32_e32 v121, 0xffff0000, v110
	v_lshlrev_b32_e32 v110, 16, v187
	v_and_b32_e32 v111, 0xffff0000, v187
	v_lshlrev_b32_e32 v112, 16, v99
	v_and_b32_e32 v113, 0xffff0000, v99
	v_and_b32_e32 v99, 0xffff0000, v94
	v_and_b32_e32 v95, 0xffff0000, v140
	v_cndmask_b32_e64 v177, 0, v122, s[82:83]
	v_cndmask_b32_e64 v176, 0, v123, s[82:83]
	v_lshlrev_b32_e32 v196, 16, v116
	v_and_b32_e32 v197, 0xffff0000, v116
	s_waitcnt vmcnt(0)
; __device__ __forceinline__ unsigned pk2(float lo, float hi) { const f32x2cv v = {lo, hi}; const bf16x2cv b = __builtin_convertvector(v, bf16x2cv); return __builtin_bit_cast(unsigned, b); }
; __device__ __forceinline__ float silu(float x) { return x * __builtin_amdgcn_rcpf(1.0f + __expf(-x)); }
; __global__ void __launch_bounds__(NT, 2) fwd_kernel(Args args) {
;     ...
; #pragma unroll
;                 for (int tk = 0; tk < 4; ++tk) {
;                     float acc[8] = {cb0.x, cb0.y, cb0.z, cb0.w, cb1.x, cb1.y, cb1.z, cb1.w};
; #pragma unroll
;                     for (int dr = 0; dr < 3; ++dr)
; #pragma unroll
;                         for (int dc = 0; dc < 3; ++dc) { const v4u xv = xr[dr][tk + dc]; const f32x4 w0 = w[dr * 3 + dc][0], w1 = w[dr * 3 + dc][1];
;                             acc[0] += w0.x * bflo(xv.x); acc[1] += w0.y * bfhi(xv.x); acc[2] += w0.z * bflo(xv.y); acc[3] += w0.w * bfhi(xv.y);
;                             acc[4] += w1.x * bflo(xv.z); acc[5] += w1.y * bfhi(xv.z); acc[6] += w1.z * bflo(xv.w); acc[7] += w1.w * bfhi(xv.w); }
;                     v4u o; o.x = pk2(silu(acc[0]), silu(acc[1])); o.y = pk2(silu(acc[2]), silu(acc[3])); o.z = pk2(silu(acc[4]), silu(acc[5])); o.w = pk2(silu(acc[6]), silu(acc[7]));
;                     *(v4u*)(XBC + (size_t)(64 * ch + t0 + tk) * 768 + ch0) = o;
	v_cndmask_b32_e64 v169, 0, v82, s[0:1]
	v_cndmask_b32_e64 v168, 0, v83, s[0:1]
	v_lshlrev_b32_e32 v82, 16, v89
	v_and_b32_e32 v83, 0xffff0000, v89
	v_pk_fma_f32 v[82:83], v[42:43], v[82:83], v[78:79]
	v_and_b32_e32 v89, 0xffff0000, v90
	v_pk_fma_f32 v[82:83], v[46:47], v[148:149], v[82:83]
	v_lshlrev_b32_e32 v90, 16, v118
	v_pk_fma_f32 v[82:83], v[50:51], v[104:105], v[82:83]
	v_lshlrev_b32_e32 v118, 16, v156
	v_pk_fma_f32 v[82:83], v[54:55], v[194:195], v[82:83]
	v_lshlrev_b32_e32 v156, 16, v157
	v_pk_fma_f32 v[82:83], v[58:59], v[154:155], v[82:83]
	v_and_b32_e32 v157, 0xffff0000, v157
	v_pk_fma_f32 v[82:83], v[62:63], v[108:109], v[82:83]
	v_cndmask_b32_e64 v167, 0, v84, s[0:1]
	v_pk_fma_f32 v[82:83], v[66:67], v[198:199], v[82:83]
	v_cndmask_b32_e64 v166, 0, v85, s[0:1]
	v_pk_fma_f32 v[82:83], v[70:71], v[156:157], v[82:83]
	v_lshlrev_b32_e32 v84, 16, v98
	v_pk_fma_f32 v[82:83], v[74:75], v[110:111], v[82:83]
	v_and_b32_e32 v85, 0xffff0000, v98
	v_lshlrev_b32_e32 v98, 16, v94
	v_lshlrev_b32_e32 v94, 16, v140
	v_mul_f32_e32 v140, 0xbfb8aa3b, v82
	v_exp_f32_e32 v140, v140
	v_pk_fma_f32 v[84:85], v[2:3], v[84:85], v[38:39]
	v_lshlrev_b32_e32 v122, 16, v107
	v_and_b32_e32 v123, 0xffff0000, v107
	v_add_f32_e32 v140, 1.0, v140
	v_lshlrev_b32_e32 v116, 16, v106
	v_and_b32_e32 v117, 0xffff0000, v106
	v_lshlrev_b32_e32 v106, 16, v186
	v_and_b32_e32 v107, 0xffff0000, v186
	v_rcp_f32_e32 v186, v140
	v_mul_f32_e32 v140, 0xbfb8aa3b, v83
	v_pk_fma_f32 v[84:85], v[6:7], v[124:125], v[84:85]
	v_exp_f32_e32 v140, v140
	v_pk_fma_f32 v[84:85], v[10:11], v[92:93], v[84:85]
	v_cndmask_b32_e64 v159, 0, v128, s[6:7]
	v_pk_fma_f32 v[84:85], v[14:15], v[122:123], v[84:85]
	v_cndmask_b32_e64 v158, 0, v129, s[6:7]
	v_pk_fma_f32 v[84:85], v[18:19], v[134:135], v[84:85]
	v_lshlrev_b32_e32 v128, 16, v189
	v_and_b32_e32 v129, 0xffff0000, v189
	v_pk_fma_f32 v[84:85], v[22:23], v[96:97], v[84:85]
	v_lshlrev_b32_e32 v152, 16, v138
	v_and_b32_e32 v153, 0xffff0000, v138
	v_lshlrev_b32_e32 v138, 16, v139
	v_and_b32_e32 v139, 0xffff0000, v139
	v_add_f32_e32 v140, 1.0, v140
	v_pk_fma_f32 v[84:85], v[26:27], v[128:129], v[84:85]
	v_cndmask_b32_e64 v179, 0, v100, s[54:55]
	v_cndmask_b32_e64 v178, 0, v101, s[54:55]
	v_lshlrev_b32_e32 v100, 16, v145
	v_and_b32_e32 v101, 0xffff0000, v145
	v_rcp_f32_e32 v187, v140
	v_pk_fma_f32 v[84:85], v[30:31], v[138:139], v[84:85]
	v_pk_fma_f32 v[112:113], v[4:5], v[112:113], v[40:41]
	v_pk_fma_f32 v[84:85], v[34:35], v[100:101], v[84:85]
	v_pk_mul_f32 v[82:83], v[82:83], v[186:187]
	v_mul_f32_e32 v122, 0xbfb8aa3b, v84
	v_mul_f32_e32 v123, 0xbfb8aa3b, v85
	v_exp_f32_e32 v122, v122
	v_exp_f32_e32 v123, v123
	v_pk_fma_f32 v[186:187], v[44:45], v[192:193], v[80:81]
	v_pk_fma_f32 v[112:113], v[8:9], v[114:115], v[112:113]
	v_pk_fma_f32 v[186:187], v[48:49], v[136:137], v[186:187]
	v_pk_fma_f32 v[112:113], v[12:13], v[88:89], v[112:113]
	v_pk_fma_f32 v[186:187], v[52:53], v[98:99], v[186:187]
	v_add_f32_e32 v122, 1.0, v122
	v_pk_fma_f32 v[186:187], v[56:57], v[196:197], v[186:187]
	v_add_f32_e32 v123, 1.0, v123
	v_pk_fma_f32 v[112:113], v[16:17], v[116:117], v[112:113]
	v_cndmask_b32_e64 v165, 0, v102, s[56:57]
	v_cndmask_b32_e64 v164, 0, v103, s[56:57]
	v_lshlrev_b32_e32 v102, 16, v126
	v_and_b32_e32 v103, 0xffff0000, v126
	v_pk_fma_f32 v[186:187], v[60:61], v[146:147], v[186:187]
	v_rcp_f32_e32 v122, v122
	v_rcp_f32_e32 v123, v123
	v_pk_fma_f32 v[112:113], v[20:21], v[120:121], v[112:113]
	v_lshlrev_b32_e32 v200, 16, v190
	v_and_b32_e32 v201, 0xffff0000, v190
	v_pk_fma_f32 v[186:187], v[64:65], v[102:103], v[186:187]
	v_pk_fma_f32 v[112:113], v[24:25], v[90:91], v[112:113]
	v_lshlrev_b32_e32 v126, 16, v188
	v_and_b32_e32 v127, 0xffff0000, v188
	v_pk_fma_f32 v[186:187], v[68:69], v[200:201], v[186:187]
	v_pk_fma_f32 v[112:113], v[28:29], v[118:119], v[112:113]
	v_pk_fma_f32 v[186:187], v[72:73], v[152:153], v[186:187]
	v_pk_fma_f32 v[112:113], v[32:33], v[126:127], v[112:113]
	v_pk_fma_f32 v[186:187], v[76:77], v[106:107], v[186:187]
	v_pk_mul_f32 v[84:85], v[84:85], v[122:123]
	v_pk_fma_f32 v[112:113], v[36:37], v[94:95], v[112:113]
	v_cvt_pk_bf16_f32 v82, v82, v83
	v_mul_f32_e32 v83, 0xbfb8aa3b, v186
	v_cvt_pk_bf16_f32 v84, v84, v85
	v_mul_f32_e32 v85, 0xbfb8aa3b, v112
	v_exp_f32_e32 v83, v83
	v_exp_f32_e32 v85, v85
	v_add_u32_e32 v150, s26, v150
	v_lshl_add_u64 v[86:87], s[20:21], 0, v[86:87]
	v_add_f32_e32 v83, 1.0, v83
	v_add_f32_e32 v85, 1.0, v85
	v_rcp_f32_e32 v188, v83
	v_mul_f32_e32 v83, 0xbfb8aa3b, v187
	v_rcp_f32_e32 v116, v85
	v_mul_f32_e32 v85, 0xbfb8aa3b, v113
	v_exp_f32_e32 v83, v83
	v_exp_f32_e32 v85, v85
	v_pk_fma_f32 v[114:115], v[4:5], v[114:115], v[40:41]
	v_pk_fma_f32 v[148:149], v[42:43], v[148:149], v[78:79]
	v_add_f32_e32 v83, 1.0, v83
	v_add_f32_e32 v85, 1.0, v85
	v_rcp_f32_e32 v189, v83
	v_rcp_f32_e32 v117, v85
	v_pk_fma_f32 v[136:137], v[44:45], v[136:137], v[80:81]
	v_pk_fma_f32 v[124:125], v[2:3], v[124:125], v[38:39]
	v_pk_mul_f32 v[186:187], v[186:187], v[188:189]
	v_pk_mul_f32 v[112:113], v[112:113], v[116:117]
	v_cvt_pk_bf16_f32 v83, v186, v187
	v_cvt_pk_bf16_f32 v85, v112, v113
	v_mad_i64_i32 v[112:113], s[0:1], v150, s96, v[86:87]
	global_store_dwordx4 v[112:113], v[82:85], off sc1
	v_pk_fma_f32 v[114:115], v[8:9], v[88:89], v[114:115]
	v_lshlrev_b32_e32 v140, 16, v141
	v_lshlrev_b32_e32 v82, 16, v142
	v_and_b32_e32 v83, 0xffff0000, v142
	v_and_b32_e32 v141, 0xffff0000, v141
	v_lshlrev_b32_e32 v128, 16, v144
	v_and_b32_e32 v129, 0xffff0000, v144
	v_lshlrev_b32_e32 v116, 16, v143
	v_and_b32_e32 v117, 0xffff0000, v143
	v_pk_fma_f32 v[148:149], v[46:47], v[104:105], v[148:149]
	v_pk_fma_f32 v[136:137], v[48:49], v[98:99], v[136:137]
; __device__ __forceinline__ unsigned pk2(float lo, float hi) { const f32x2cv v = {lo, hi}; const bf16x2cv b = __builtin_convertvector(v, bf16x2cv); return __builtin_bit_cast(unsigned, b); }
; __device__ __forceinline__ float silu(float x) { return x * __builtin_amdgcn_rcpf(1.0f + __expf(-x)); }
; __global__ void __launch_bounds__(NT, 2) fwd_kernel(Args args) {
;     ...
; #pragma unroll
;                 for (int tk = 0; tk < 4; ++tk) {
;                     float acc[8] = {cb0.x, cb0.y, cb0.z, cb0.w, cb1.x, cb1.y, cb1.z, cb1.w};
; #pragma unroll
;                     for (int dr = 0; dr < 3; ++dr)
; #pragma unroll
;                         for (int dc = 0; dc < 3; ++dc) { const v4u xv = xr[dr][tk + dc]; const f32x4 w0 = w[dr * 3 + dc][0], w1 = w[dr * 3 + dc][1];
;                             acc[0] += w0.x * bflo(xv.x); acc[1] += w0.y * bfhi(xv.x); acc[2] += w0.z * bflo(xv.y); acc[3] += w0.w * bfhi(xv.y);
;                             acc[4] += w1.x * bflo(xv.z); acc[5] += w1.y * bfhi(xv.z); acc[6] += w1.z * bflo(xv.w); acc[7] += w1.w * bfhi(xv.w); }
;                     v4u o; o.x = pk2(silu(acc[0]), silu(acc[1])); o.y = pk2(silu(acc[2]), silu(acc[3])); o.z = pk2(silu(acc[4]), silu(acc[5])); o.w = pk2(silu(acc[6]), silu(acc[7]));
;                     *(v4u*)(XBC + (size_t)(64 * ch + t0 + tk) * 768 + ch0) = o;
	v_pk_fma_f32 v[124:125], v[6:7], v[92:93], v[124:125]
	v_pk_fma_f32 v[114:115], v[12:13], v[82:83], v[114:115]
	v_pk_fma_f32 v[148:149], v[50:51], v[140:141], v[148:149]
	v_pk_fma_f32 v[136:137], v[52:53], v[128:129], v[136:137]
	v_pk_fma_f32 v[124:125], v[10:11], v[116:117], v[124:125]
	v_pk_fma_f32 v[114:115], v[16:17], v[120:121], v[114:115]
	v_lshlrev_b32_e32 v84, 16, v132
	v_and_b32_e32 v85, 0xffff0000, v132
	v_pk_fma_f32 v[148:149], v[54:55], v[154:155], v[148:149]
	v_pk_fma_f32 v[136:137], v[56:57], v[146:147], v[136:137]
	v_pk_fma_f32 v[124:125], v[14:15], v[134:135], v[124:125]
	v_pk_fma_f32 v[114:115], v[20:21], v[90:91], v[114:115]
	v_lshlrev_b32_e32 v142, 16, v130
	v_and_b32_e32 v143, 0xffff0000, v130
	v_lshlrev_b32_e32 v130, 16, v131
	v_and_b32_e32 v131, 0xffff0000, v131
	v_lshlrev_b32_e32 v118, 16, v133
	v_and_b32_e32 v119, 0xffff0000, v133
	v_pk_fma_f32 v[148:149], v[58:59], v[108:109], v[148:149]
	v_pk_fma_f32 v[136:137], v[60:61], v[102:103], v[136:137]
	v_pk_fma_f32 v[124:125], v[18:19], v[96:97], v[124:125]
	v_pk_fma_f32 v[114:115], v[24:25], v[84:85], v[114:115]
	v_pk_fma_f32 v[148:149], v[62:63], v[142:143], v[148:149]
	v_pk_fma_f32 v[136:137], v[64:65], v[130:131], v[136:137]
	v_pk_fma_f32 v[124:125], v[22:23], v[118:119], v[124:125]
	v_pk_fma_f32 v[114:115], v[28:29], v[126:127], v[114:115]
	v_lshlrev_b32_e32 v112, 16, v182
	v_and_b32_e32 v113, 0xffff0000, v182
	v_pk_fma_f32 v[148:149], v[66:67], v[156:157], v[148:149]
	v_pk_fma_f32 v[136:137], v[68:69], v[152:153], v[136:137]
	v_pk_fma_f32 v[124:125], v[26:27], v[138:139], v[124:125]
	v_pk_fma_f32 v[114:115], v[32:33], v[94:95], v[114:115]
	v_lshlrev_b32_e32 v144, 16, v185
	v_and_b32_e32 v145, 0xffff0000, v185
	v_lshlrev_b32_e32 v132, 16, v184
	v_and_b32_e32 v133, 0xffff0000, v184
	v_lshlrev_b32_e32 v122, 16, v183
	v_and_b32_e32 v123, 0xffff0000, v183
	v_pk_fma_f32 v[148:149], v[70:71], v[110:111], v[148:149]
	v_pk_fma_f32 v[136:137], v[72:73], v[106:107], v[136:137]
	v_pk_fma_f32 v[124:125], v[30:31], v[100:101], v[124:125]
	v_pk_fma_f32 v[114:115], v[36:37], v[112:113], v[114:115]
	v_pk_fma_f32 v[148:149], v[74:75], v[144:145], v[148:149]
	v_pk_fma_f32 v[136:137], v[76:77], v[132:133], v[136:137]
	v_pk_fma_f32 v[124:125], v[34:35], v[122:123], v[124:125]
	v_mul_f32_e32 v120, 0xbfb8aa3b, v114
	v_mul_f32_e32 v121, 0xbfb8aa3b, v115
	v_mul_f32_e32 v154, 0xbfb8aa3b, v148
	v_mul_f32_e32 v155, 0xbfb8aa3b, v149
	v_mul_f32_e32 v146, 0xbfb8aa3b, v136
	v_mul_f32_e32 v147, 0xbfb8aa3b, v137
	v_mul_f32_e32 v134, 0xbfb8aa3b, v124
	v_mul_f32_e32 v135, 0xbfb8aa3b, v125
	v_exp_f32_e32 v120, v120
	v_exp_f32_e32 v121, v121
	v_exp_f32_e32 v154, v154
	v_exp_f32_e32 v155, v155
	v_exp_f32_e32 v146, v146
	v_exp_f32_e32 v147, v147
	v_exp_f32_e32 v134, v134
	v_exp_f32_e32 v135, v135
	v_add_f32_e32 v120, 1.0, v120
	v_add_f32_e32 v121, 1.0, v121
	v_add_f32_e32 v154, 1.0, v154
	v_add_f32_e32 v155, 1.0, v155
	v_add_f32_e32 v146, 1.0, v146
	v_add_f32_e32 v147, 1.0, v147
	v_add_f32_e32 v134, 1.0, v134
	v_add_f32_e32 v135, 1.0, v135
	v_rcp_f32_e32 v120, v120
	v_rcp_f32_e32 v121, v121
	v_rcp_f32_e32 v154, v154
	v_rcp_f32_e32 v155, v155
	v_rcp_f32_e32 v146, v146
	v_rcp_f32_e32 v147, v147
	v_rcp_f32_e32 v134, v134
	v_rcp_f32_e32 v135, v135
	v_pk_mul_f32 v[114:115], v[114:115], v[120:121]
	v_pk_mul_f32 v[148:149], v[148:149], v[154:155]
	v_pk_mul_f32 v[136:137], v[136:137], v[146:147]
	v_pk_mul_f32 v[124:125], v[124:125], v[134:135]
	v_cvt_pk_bf16_f32 v157, v114, v115
	v_or_b32_e32 v114, 1, v150
	v_cvt_pk_bf16_f32 v154, v148, v149
	v_cvt_pk_bf16_f32 v155, v136, v137
	v_cvt_pk_bf16_f32 v156, v124, v125
	v_mad_i64_i32 v[114:115], s[0:1], v114, s96, v[86:87]
	v_pk_fma_f32 v[88:89], v[4:5], v[88:89], v[40:41]
	global_store_dwordx4 v[114:115], v[154:157], off sc1
	v_lshlrev_b32_e32 v114, 16, v178
	v_and_b32_e32 v115, 0xffff0000, v178
	v_pk_fma_f32 v[104:105], v[42:43], v[104:105], v[78:79]
	v_pk_fma_f32 v[98:99], v[44:45], v[98:99], v[80:81]
	v_pk_fma_f32 v[92:93], v[2:3], v[92:93], v[38:39]
	v_pk_fma_f32 v[88:89], v[8:9], v[82:83], v[88:89]
	v_lshlrev_b32_e32 v152, 16, v181
	v_and_b32_e32 v153, 0xffff0000, v181
	v_lshlrev_b32_e32 v138, 16, v180
	v_and_b32_e32 v139, 0xffff0000, v180
	v_lshlrev_b32_e32 v126, 16, v179
	v_and_b32_e32 v127, 0xffff0000, v179
	v_pk_fma_f32 v[104:105], v[46:47], v[140:141], v[104:105]
	v_pk_fma_f32 v[98:99], v[48:49], v[128:129], v[98:99]
	v_pk_fma_f32 v[92:93], v[6:7], v[116:117], v[92:93]
	v_pk_fma_f32 v[88:89], v[12:13], v[114:115], v[88:89]
	v_pk_fma_f32 v[104:105], v[50:51], v[152:153], v[104:105]
	v_pk_fma_f32 v[98:99], v[52:53], v[138:139], v[98:99]
	v_pk_fma_f32 v[92:93], v[10:11], v[126:127], v[92:93]
	v_pk_fma_f32 v[88:89], v[16:17], v[90:91], v[88:89]
	v_lshlrev_b32_e32 v120, 16, v174
	v_and_b32_e32 v121, 0xffff0000, v174
	v_pk_fma_f32 v[104:105], v[54:55], v[108:109], v[104:105]
	v_pk_fma_f32 v[98:99], v[56:57], v[102:103], v[98:99]
	v_pk_fma_f32 v[92:93], v[14:15], v[96:97], v[92:93]
	v_pk_fma_f32 v[88:89], v[20:21], v[84:85], v[88:89]
	v_lshlrev_b32_e32 v154, 16, v177
	v_and_b32_e32 v155, 0xffff0000, v177
	v_lshlrev_b32_e32 v146, 16, v176
	v_and_b32_e32 v147, 0xffff0000, v176
	v_lshlrev_b32_e32 v134, 16, v175
	v_and_b32_e32 v135, 0xffff0000, v175
	v_pk_fma_f32 v[104:105], v[58:59], v[142:143], v[104:105]
	v_pk_fma_f32 v[98:99], v[60:61], v[130:131], v[98:99]
	v_pk_fma_f32 v[92:93], v[18:19], v[118:119], v[92:93]
	v_pk_fma_f32 v[88:89], v[24:25], v[120:121], v[88:89]
	v_pk_fma_f32 v[104:105], v[62:63], v[154:155], v[104:105]
	v_pk_fma_f32 v[98:99], v[64:65], v[146:147], v[98:99]
	v_pk_fma_f32 v[92:93], v[22:23], v[134:135], v[92:93]
	v_pk_fma_f32 v[88:89], v[28:29], v[94:95], v[88:89]
; __device__ __forceinline__ unsigned pk2(float lo, float hi) { const f32x2cv v = {lo, hi}; const bf16x2cv b = __builtin_convertvector(v, bf16x2cv); return __builtin_bit_cast(unsigned, b); }
; __device__ __forceinline__ float silu(float x) { return x * __builtin_amdgcn_rcpf(1.0f + __expf(-x)); }
; __global__ void __launch_bounds__(NT, 2) fwd_kernel(Args args) {
;     ...
; #pragma unroll
;                 for (int tk = 0; tk < 4; ++tk) {
;                     float acc[8] = {cb0.x, cb0.y, cb0.z, cb0.w, cb1.x, cb1.y, cb1.z, cb1.w};
; #pragma unroll
;                     for (int dr = 0; dr < 3; ++dr)
; #pragma unroll
;                         for (int dc = 0; dc < 3; ++dc) { const v4u xv = xr[dr][tk + dc]; const f32x4 w0 = w[dr * 3 + dc][0], w1 = w[dr * 3 + dc][1];
;                             acc[0] += w0.x * bflo(xv.x); acc[1] += w0.y * bfhi(xv.x); acc[2] += w0.z * bflo(xv.y); acc[3] += w0.w * bfhi(xv.y);
;                             acc[4] += w1.x * bflo(xv.z); acc[5] += w1.y * bfhi(xv.z); acc[6] += w1.z * bflo(xv.w); acc[7] += w1.w * bfhi(xv.w); }
;                     v4u o; o.x = pk2(silu(acc[0]), silu(acc[1])); o.y = pk2(silu(acc[2]), silu(acc[3])); o.z = pk2(silu(acc[4]), silu(acc[5])); o.w = pk2(silu(acc[6]), silu(acc[7]));
;                     *(v4u*)(XBC + (size_t)(64 * ch + t0 + tk) * 768 + ch0) = o;
	v_lshlrev_b32_e32 v124, 16, v170
	v_and_b32_e32 v125, 0xffff0000, v170
	v_pk_fma_f32 v[104:105], v[66:67], v[110:111], v[104:105]
	v_pk_fma_f32 v[98:99], v[68:69], v[106:107], v[98:99]
	v_pk_fma_f32 v[92:93], v[26:27], v[100:101], v[92:93]
	v_pk_fma_f32 v[88:89], v[32:33], v[112:113], v[88:89]
	v_lshlrev_b32_e32 v156, 16, v173
	v_and_b32_e32 v157, 0xffff0000, v173
	v_lshlrev_b32_e32 v148, 16, v172
	v_and_b32_e32 v149, 0xffff0000, v172
	v_lshlrev_b32_e32 v136, 16, v171
	v_and_b32_e32 v137, 0xffff0000, v171
	v_pk_fma_f32 v[104:105], v[70:71], v[144:145], v[104:105]
	v_pk_fma_f32 v[98:99], v[72:73], v[132:133], v[98:99]
	v_pk_fma_f32 v[92:93], v[30:31], v[122:123], v[92:93]
	v_pk_fma_f32 v[88:89], v[36:37], v[124:125], v[88:89]
	v_pk_fma_f32 v[104:105], v[74:75], v[156:157], v[104:105]
	v_pk_fma_f32 v[98:99], v[76:77], v[148:149], v[98:99]
	v_pk_fma_f32 v[92:93], v[34:35], v[136:137], v[92:93]
	v_mul_f32_e32 v90, 0xbfb8aa3b, v88
	v_mul_f32_e32 v91, 0xbfb8aa3b, v89
	v_mul_f32_e32 v108, 0xbfb8aa3b, v104
	v_mul_f32_e32 v109, 0xbfb8aa3b, v105
	v_mul_f32_e32 v102, 0xbfb8aa3b, v98
	v_mul_f32_e32 v103, 0xbfb8aa3b, v99
	v_mul_f32_e32 v96, 0xbfb8aa3b, v92
	v_mul_f32_e32 v97, 0xbfb8aa3b, v93
	v_exp_f32_e32 v90, v90
	v_exp_f32_e32 v91, v91
	v_exp_f32_e32 v108, v108
	v_exp_f32_e32 v109, v109
	v_exp_f32_e32 v102, v102
	v_exp_f32_e32 v103, v103
	v_exp_f32_e32 v96, v96
	v_exp_f32_e32 v97, v97
	v_add_f32_e32 v90, 1.0, v90
	v_add_f32_e32 v91, 1.0, v91
	v_add_f32_e32 v108, 1.0, v108
	v_add_f32_e32 v109, 1.0, v109
	v_add_f32_e32 v102, 1.0, v102
	v_add_f32_e32 v103, 1.0, v103
	v_add_f32_e32 v96, 1.0, v96
	v_add_f32_e32 v97, 1.0, v97
	v_rcp_f32_e32 v90, v90
	v_rcp_f32_e32 v91, v91
	v_rcp_f32_e32 v108, v108
	v_rcp_f32_e32 v109, v109
	v_rcp_f32_e32 v102, v102
	v_rcp_f32_e32 v103, v103
	v_rcp_f32_e32 v96, v96
	v_rcp_f32_e32 v97, v97
	v_pk_mul_f32 v[88:89], v[88:89], v[90:91]
	v_pk_mul_f32 v[104:105], v[104:105], v[108:109]
	v_pk_mul_f32 v[98:99], v[98:99], v[102:103]
	v_pk_mul_f32 v[92:93], v[92:93], v[96:97]
	v_cvt_pk_bf16_f32 v107, v88, v89
	v_or_b32_e32 v88, 2, v150
	v_cvt_pk_bf16_f32 v104, v104, v105
	v_cvt_pk_bf16_f32 v105, v98, v99
	v_cvt_pk_bf16_f32 v106, v92, v93
	v_mad_i64_i32 v[88:89], s[0:1], v88, s96, v[86:87]
	v_pk_fma_f32 v[42:43], v[42:43], v[140:141], v[78:79]
	global_store_dwordx4 v[88:89], v[104:107], off sc1
	v_lshlrev_b32_e32 v88, 16, v165
	v_and_b32_e32 v89, 0xffff0000, v165
	v_pk_fma_f32 v[42:43], v[46:47], v[152:153], v[42:43]
	v_lshlrev_b32_e32 v96, 16, v161
	v_pk_fma_f32 v[42:43], v[50:51], v[88:89], v[42:43]
	v_and_b32_e32 v97, 0xffff0000, v161
	v_pk_fma_f32 v[42:43], v[54:55], v[142:143], v[42:43]
	v_lshlrev_b32_e32 v104, 16, v169
	v_pk_fma_f32 v[42:43], v[58:59], v[154:155], v[42:43]
	v_and_b32_e32 v105, 0xffff0000, v169
	v_pk_fma_f32 v[42:43], v[62:63], v[96:97], v[42:43]
	v_pk_fma_f32 v[44:45], v[44:45], v[128:129], v[80:81]
	v_pk_fma_f32 v[42:43], v[66:67], v[144:145], v[42:43]
	v_lshlrev_b32_e32 v90, 16, v164
	v_pk_fma_f32 v[42:43], v[70:71], v[156:157], v[42:43]
	v_and_b32_e32 v91, 0xffff0000, v164
	v_pk_fma_f32 v[42:43], v[74:75], v[104:105], v[42:43]
	v_pk_fma_f32 v[44:45], v[48:49], v[138:139], v[44:45]
	v_mul_f32_e32 v46, 0xbfb8aa3b, v42
	v_mul_f32_e32 v47, 0xbfb8aa3b, v43
	v_exp_f32_e32 v46, v46
	v_exp_f32_e32 v47, v47
	v_pk_fma_f32 v[44:45], v[52:53], v[90:91], v[44:45]
	v_lshlrev_b32_e32 v98, 16, v160
	v_add_f32_e32 v46, 1.0, v46
	v_add_f32_e32 v47, 1.0, v47
	v_pk_fma_f32 v[44:45], v[56:57], v[130:131], v[44:45]
	v_and_b32_e32 v99, 0xffff0000, v160
	v_rcp_f32_e32 v46, v46
	v_rcp_f32_e32 v47, v47
	v_pk_fma_f32 v[44:45], v[60:61], v[146:147], v[44:45]
	v_pk_fma_f32 v[2:3], v[2:3], v[116:117], v[38:39]
	v_pk_fma_f32 v[44:45], v[64:65], v[98:99], v[44:45]
	v_lshlrev_b32_e32 v92, 16, v163
	v_pk_fma_f32 v[44:45], v[68:69], v[132:133], v[44:45]
	v_and_b32_e32 v93, 0xffff0000, v163
	v_lshlrev_b32_e32 v106, 16, v168
	v_and_b32_e32 v107, 0xffff0000, v168
	v_pk_fma_f32 v[44:45], v[72:73], v[148:149], v[44:45]
	v_pk_fma_f32 v[2:3], v[6:7], v[126:127], v[2:3]
	v_pk_mul_f32 v[42:43], v[42:43], v[46:47]
	v_pk_fma_f32 v[44:45], v[76:77], v[106:107], v[44:45]
	v_pk_fma_f32 v[2:3], v[10:11], v[92:93], v[2:3]
	v_cvt_pk_bf16_f32 v42, v42, v43
	v_mul_f32_e32 v43, 0xbfb8aa3b, v44
	v_pk_fma_f32 v[2:3], v[14:15], v[118:119], v[2:3]
	v_lshlrev_b32_e32 v100, 16, v159
	v_and_b32_e32 v101, 0xffff0000, v159
	v_exp_f32_e32 v43, v43
	v_pk_fma_f32 v[2:3], v[18:19], v[134:135], v[2:3]
	v_lshlrev_b32_e32 v108, 16, v167
	v_pk_fma_f32 v[2:3], v[22:23], v[100:101], v[2:3]
	v_and_b32_e32 v109, 0xffff0000, v167
	v_pk_fma_f32 v[2:3], v[26:27], v[122:123], v[2:3]
	v_add_f32_e32 v43, 1.0, v43
	v_pk_fma_f32 v[2:3], v[30:31], v[136:137], v[2:3]
	v_rcp_f32_e32 v46, v43
	v_pk_fma_f32 v[2:3], v[34:35], v[108:109], v[2:3]
	v_mul_f32_e32 v43, 0xbfb8aa3b, v45
	v_mul_f32_e32 v6, 0xbfb8aa3b, v2
	v_mul_f32_e32 v7, 0xbfb8aa3b, v3
	v_exp_f32_e32 v43, v43
	v_exp_f32_e32 v6, v6
	v_exp_f32_e32 v7, v7
	v_lshlrev_b32_e32 v94, 16, v162
	v_add_f32_e32 v43, 1.0, v43
	v_add_f32_e32 v6, 1.0, v6
	v_add_f32_e32 v7, 1.0, v7
	v_rcp_f32_e32 v47, v43
	v_rcp_f32_e32 v6, v6
	v_rcp_f32_e32 v7, v7
	v_and_b32_e32 v95, 0xffff0000, v162
	v_pk_mul_f32 v[44:45], v[44:45], v[46:47]
	v_lshlrev_b32_e32 v102, 16, v158
	v_pk_mul_f32 v[2:3], v[2:3], v[6:7]
	v_cvt_pk_bf16_f32 v43, v44, v45
	v_cvt_pk_bf16_f32 v44, v2, v3
	v_pk_fma_f32 v[2:3], v[4:5], v[82:83], v[40:41]
	v_and_b32_e32 v103, 0xffff0000, v158
	v_pk_fma_f32 v[2:3], v[8:9], v[114:115], v[2:3]
	v_lshlrev_b32_e32 v110, 16, v166
	v_pk_fma_f32 v[2:3], v[12:13], v[94:95], v[2:3]
	v_and_b32_e32 v111, 0xffff0000, v166
	v_pk_fma_f32 v[2:3], v[16:17], v[84:85], v[2:3]
	s_nop 0
	v_pk_fma_f32 v[2:3], v[20:21], v[120:121], v[2:3]
	s_nop 0
	v_pk_fma_f32 v[2:3], v[24:25], v[102:103], v[2:3]
	s_nop 0
	v_pk_fma_f32 v[2:3], v[28:29], v[112:113], v[2:3]
	s_nop 0
	v_pk_fma_f32 v[2:3], v[32:33], v[124:125], v[2:3]
	s_nop 0
	v_pk_fma_f32 v[2:3], v[36:37], v[110:111], v[2:3]
	s_nop 0
	v_mul_f32_e32 v4, 0xbfb8aa3b, v2
	v_mul_f32_e32 v5, 0xbfb8aa3b, v3
	v_exp_f32_e32 v4, v4
	v_exp_f32_e32 v5, v5
	v_add_f32_e32 v4, 1.0, v4
	v_add_f32_e32 v5, 1.0, v5
	v_rcp_f32_e32 v4, v4
	v_rcp_f32_e32 v5, v5
	s_nop 0
	v_pk_mul_f32 v[2:3], v[2:3], v[4:5]
	s_nop 0
	v_cvt_pk_bf16_f32 v45, v2, v3
	v_or_b32_e32 v2, 3, v150
	v_mad_i64_i32 v[2:3], s[0:1], v2, s96, v[86:87]
	global_store_dwordx4 v[2:3], v[42:45], off sc1

; #define LAS __attribute__((address_space(3)))
; __device__ __forceinline__ unsigned pk2(float lo, float hi) { const f32x2cv v = {lo, hi}; const bf16x2cv b = __builtin_convertvector(v, bf16x2cv); return __builtin_bit_cast(unsigned, b); }
; #define LDS_WAIT() asm volatile("s_waitcnt lgkmcnt(0)" ::: "memory")
; __device__ __forceinline__ void transpose_item(const float* W, int K, int N, bf16* WT, int dst_row0, int k0, int n0, LAS float* scr, int lane) {
; #pragma unroll
;     for (int i = 0; i < 8; ++i) { const int kk = 8 * i + (lane >> 3), c4 = 4 * (lane & 7), n = n0 + c4;
;         const f32x4 v = (n < N) ? *(const f32x4*)(W + (size_t)(k0 + kk) * N + n) : (f32x4){0.f, 0.f, 0.f, 0.f};
;         scr[kk * 33 + c4] = v.x; scr[kk * 33 + c4 + 1] = v.y; scr[kk * 33 + c4 + 2] = v.z; scr[kk * 33 + c4 + 3] = v.w; }
;     LDS_WAIT(); asm volatile("" ::: "memory");
;     const int c = lane & 7;
; #pragma unroll
;     for (int j = 0; j < 4; ++j) { const int n = (lane >> 3) + 8 * j; const LAS float* s = scr + (8 * c) * 33 + n;
;         v4u o; o.x = pk2(s[0 * 33], s[1 * 33]); o.y = pk2(s[2 * 33], s[3 * 33]); o.z = pk2(s[4 * 33], s[5 * 33]); o.w = pk2(s[6 * 33], s[7 * 33]);
;         *(v4u*)(WT + (size_t)(dst_row0 + n) * K + k0 + 8 * c) = o; }
;     LDS_WAIT(); asm volatile("" ::: "memory");
; __global__ void __launch_bounds__(NT, 2) fwd_kernel(Args args) {
;     ...
;             for (int it = (bl - 80) * NW + wave; it < 2 * 16 * 88; it += 176 * NW) { int r = it; const int up = r >= 16 * 88; if (up) r -= 16 * 88; const int kb = r / 88, nb = r % 88;
;                 transpose_item(up ? w_up : w_gate, 1024, DFF, Wgu_t, 256 * (nb >> 2) + 32 * (nb & 3) + (up ? 128 : 0), 64 * kb, 32 * nb, scr, lane); }
.LBB0_505:
	s_add_i32 s3, s0, 0xfffffa80
	s_cmpk_gt_i32 s0, 0x57f
	s_cselect_b32 s4, s29, s27
	s_cselect_b32 s3, s3, s0
	s_cselect_b32 s5, s28, s26
	v_mov_b32_e32 v29, s4
	s_mul_hi_i32 s4, s3, 0x2e8ba2e9
	s_cselect_b32 s8, 0x80, 0
	v_mov_b32_e32 v28, s5
	s_lshr_b32 s5, s4, 31
	s_ashr_i32 s4, s4, 4
	s_add_i32 s4, s4, s5
	s_mul_i32 s5, s4, 0x58
	s_sub_i32 s3, s3, s5
	s_lshl_b32 s9, s3, 5
	v_or_b32_e32 v30, s9, v4
	s_lshl_b32 s4, s4, 6
	v_ashrrev_i32_e32 v31, 31, v30
	v_or_b32_e32 v32, s4, v1
	v_or_b32_e32 v33, s4, v5
	v_or_b32_e32 v34, s4, v6
	v_or_b32_e32 v35, s4, v7
	v_or_b32_e32 v38, s4, v8
	v_or_b32_e32 v39, s4, v9
	v_or_b32_e32 v42, s4, v10
	v_or_b32_e32 v43, s4, v11
	v_lshl_add_u64 v[28:29], v[30:31], 2, v[28:29]
	v_mad_i64_i32 v[30:31], s[6:7], v32, s1, v[28:29]
	v_mad_i64_i32 v[32:33], s[6:7], v33, s1, v[28:29]
	v_mad_i64_i32 v[36:37], s[6:7], v34, s1, v[28:29]
	v_mad_i64_i32 v[40:41], s[6:7], v35, s1, v[28:29]
	v_mad_i64_i32 v[44:45], s[6:7], v38, s1, v[28:29]
	v_mad_i64_i32 v[48:49], s[6:7], v39, s1, v[28:29]
	v_mad_i64_i32 v[52:53], s[6:7], v42, s1, v[28:29]
	v_mad_i64_i32 v[56:57], s[6:7], v43, s1, v[28:29]
	global_load_dwordx4 v[28:31], v[30:31], off
	s_nop 0
	global_load_dwordx4 v[32:35], v[32:33], off
	s_nop 0
	global_load_dwordx4 v[36:39], v[36:37], off
	s_nop 0
	global_load_dwordx4 v[40:43], v[40:41], off
	s_nop 0
	global_load_dwordx4 v[44:47], v[44:45], off
	s_nop 0
	global_load_dwordx4 v[48:51], v[48:49], off
	s_nop 0
	global_load_dwordx4 v[52:55], v[52:53], off
	s_nop 0
	global_load_dwordx4 v[56:59], v[56:57], off
	s_ashr_i32 s5, s4, 31
	s_lshl_b32 s3, s3, 6
	v_lshl_add_u64 v[60:61], s[4:5], 1, v[2:3]
	s_and_b32 s4, s9, 0x60
	s_and_b32 s3, s3, 0xffffff00
	s_or_b32 s4, s4, s8
	s_or_b32 s3, s4, s3
	v_or_b32_e32 v62, s3, v1
	v_or_b32_e32 v64, s3, v5
	v_or_b32_e32 v66, s3, v6
	v_or_b32_e32 v68, s3, v7
	v_ashrrev_i32_e32 v63, 31, v62
	v_ashrrev_i32_e32 v65, 31, v64
	v_ashrrev_i32_e32 v67, 31, v66
	v_ashrrev_i32_e32 v69, 31, v68
	v_lshlrev_b64 v[62:63], 11, v[62:63]
	v_lshlrev_b64 v[64:65], 11, v[64:65]
	v_lshlrev_b64 v[66:67], 11, v[66:67]
	v_lshlrev_b64 v[68:69], 11, v[68:69]
	v_lshl_add_u64 v[62:63], v[60:61], 0, v[62:63]
	v_lshl_add_u64 v[64:65], v[60:61], 0, v[64:65]
	v_lshl_add_u64 v[66:67], v[60:61], 0, v[66:67]
	v_lshl_add_u64 v[60:61], v[60:61], 0, v[68:69]
	s_add_i32 s3, s0, 0x580
	s_cmpk_lt_i32 s0, 0x580
	s_mov_b32 s0, s3
	s_waitcnt vmcnt(7)
	ds_write2_b32 v13, v28, v29 offset1:1
	ds_write2_b32 v13, v30, v31 offset0:2 offset1:3
	s_waitcnt vmcnt(6)
	ds_write2_b32 v14, v32, v33 offset1:1
	ds_write2_b32 v15, v34, v35 offset1:1
	s_waitcnt vmcnt(5)
	ds_write2_b32 v16, v36, v37 offset1:1
	ds_write2_b32 v17, v38, v39 offset1:1
	s_waitcnt vmcnt(4)
	ds_write2_b32 v18, v40, v41 offset1:1
	ds_write2_b32 v19, v42, v43 offset1:1
	s_waitcnt vmcnt(3)
	ds_write2_b32 v20, v44, v45 offset1:1
	ds_write2_b32 v21, v46, v47 offset1:1
	s_waitcnt vmcnt(2)
	ds_write2_b32 v22, v48, v49 offset1:1
	ds_write2_b32 v23, v50, v51 offset1:1
	s_waitcnt vmcnt(1)
	ds_write2_b32 v24, v52, v53 offset1:1
	ds_write2_b32 v25, v54, v55 offset1:1
	s_waitcnt vmcnt(0)
	ds_write2_b32 v26, v56, v57 offset1:1
	ds_write2_b32 v27, v58, v59 offset1:1
	s_waitcnt lgkmcnt(0)
	ds_read2_b32 v[32:33], v12 offset0:33 offset1:41
	ds_read2_b32 v[34:35], v12 offset1:8
	ds_read2_b32 v[36:37], v12 offset0:66 offset1:74
	ds_read2_b32 v[38:39], v12 offset0:99 offset1:107
	ds_read2_b32 v[40:41], v12 offset0:132 offset1:140
	ds_read2_b32 v[42:43], v12 offset0:165 offset1:173
	ds_read2_b32 v[44:45], v12 offset0:198 offset1:206
	ds_read2_b32 v[46:47], v12 offset0:231 offset1:239
	ds_read2_b32 v[48:49], v12 offset0:49 offset1:57
	ds_read2_b32 v[50:51], v12 offset0:16 offset1:24
	ds_read2_b32 v[52:53], v12 offset0:82 offset1:90
	ds_read2_b32 v[54:55], v12 offset0:115 offset1:123
	ds_read2_b32 v[56:57], v12 offset0:148 offset1:156
	ds_read2_b32 v[58:59], v12 offset0:181 offset1:189
	ds_read2_b32 v[68:69], v12 offset0:214 offset1:222
	ds_read2_b32 v[70:71], v12 offset0:247 offset1:255
	s_waitcnt lgkmcnt(14)
	v_cvt_pk_bf16_f32 v28, v34, v32
	s_waitcnt lgkmcnt(12)
	v_cvt_pk_bf16_f32 v29, v36, v38
	s_waitcnt lgkmcnt(10)
	v_cvt_pk_bf16_f32 v30, v40, v42
	s_waitcnt lgkmcnt(8)
	v_cvt_pk_bf16_f32 v31, v44, v46
	v_cvt_pk_bf16_f32 v32, v35, v33
	v_cvt_pk_bf16_f32 v33, v37, v39
	v_cvt_pk_bf16_f32 v34, v41, v43
	v_cvt_pk_bf16_f32 v35, v45, v47
	s_waitcnt lgkmcnt(6)
	v_cvt_pk_bf16_f32 v36, v50, v48
	s_waitcnt lgkmcnt(4)
	v_cvt_pk_bf16_f32 v37, v52, v54
	s_waitcnt lgkmcnt(2)
	v_cvt_pk_bf16_f32 v38, v56, v58
	s_waitcnt lgkmcnt(0)
	v_cvt_pk_bf16_f32 v39, v68, v70
	v_cvt_pk_bf16_f32 v40, v51, v49
	v_cvt_pk_bf16_f32 v41, v53, v55
	v_cvt_pk_bf16_f32 v42, v57, v59
	v_cvt_pk_bf16_f32 v43, v69, v71
	global_store_dwordx4 v[62:63], v[28:31], off sc1
	global_store_dwordx4 v[64:65], v[32:35], off sc1
	global_store_dwordx4 v[66:67], v[36:39], off sc1
	global_store_dwordx4 v[60:61], v[40:43], off sc1
	s_waitcnt lgkmcnt(0)
	s_cbranch_scc1 .LBB0_505

; __device__ __forceinline__ unsigned cvt_pk_bf16(float lo, float hi) { unsigned r; asm volatile("v_cvt_pk_bf16_f32 %0, %1, %2" : "=v"(r) : "v"(lo), "v"(hi)); return r; }
;     __device__ __forceinline__ void fused(f32x4 (&acc)[2][2][4][2], const Unit& u, int wr, int wc, int fr, int fq, PG8_LAS unsigned char* lds, int wid, int lane) const {
;     ...
;         f32x4 ca2[2][2], cb2[2][2];
; #pragma unroll
;         for (int bj = 0; bj < 2; ++bj)
; #pragma unroll
;             for (int n = 0; n < 2; ++n) { ca2[bj][n] = *(const f32x4*)(cv + 1024 + bj * HALF + n * 16); cb2[bj][n] = *(const f32x4*)(cv + 2048 + bj * HALF + n * 16); }
; #pragma unroll
;         for (int ai = 0; ai < 2; ++ai)
; #pragma unroll
;             for (int m = 0; m < 4; ++m) { const int r = ai * HALF + wr * 64 + m * 16 + fr; const f32x2v sr = S[r]; const size_t off = (size_t)(u.pm * BM + r) * ldc + col0;
; #pragma unroll
;                 for (int bj = 0; bj < 2; ++bj)
; #pragma unroll
;                     for (int n = 0; n < 2; ++n) { const f32x4 x1 = acc[ai][bj][m][n]; *(f32x4*)(out + off + bj * HALF + n * 16) = bad1 ? (f32x4){qnan, qnan, qnan, qnan} : x1;
;                         const f32x4 o = (x1 * sr.y) * ca2[bj][n] + cb2[bj][n]; u32x2v w; w.x = cvt_pk_bf16(o[0], o[1]); w.y = cvt_pk_bf16(o[2], o[3]);
;                         if (bad) { w.x = 0x7fc07fc0u; w.y = 0x7fc07fc0u; } *(u32x2v*)(xn + off + bj * HALF + n * 16) = w; }
;                 asm volatile("" ::: "memory"); }
.LBB0_1113:
	s_or_b64 exec, exec, s[0:1]
	v_add_co_u32_e32 v130, vcc, 0x1000, v146
	s_waitcnt lgkmcnt(0)
	s_barrier
	s_nop 0
	v_addc_co_u32_e32 v131, vcc, 0, v147, vcc
	v_add_co_u32_e32 v134, vcc, 0x2000, v146
	v_or_b32_e32 v167, v183, v1
	s_nop 0
	v_addc_co_u32_e32 v135, vcc, 0, v147, vcc
	global_load_dwordx4 v[154:157], v[134:135], off
	global_load_dwordx4 v[158:161], v[130:131], off
	global_load_dwordx4 v[146:149], v[130:131], off offset:64
	global_load_dwordx4 v[150:153], v[134:135], off offset:64
	global_load_dwordx4 v[138:141], v[134:135], off offset:512
	global_load_dwordx4 v[142:145], v[130:131], off offset:512
	s_waitcnt lgkmcnt(1)
	global_load_dwordx4 v[130:133], v[130:131], off offset:576
	s_nop 0
	global_load_dwordx4 v[134:137], v[134:135], off offset:576
	ds_read_b64 v[200:201], v182 offset:8192
	v_mov_b32_e32 v1, 0x7fc00000
	v_cmp_ne_u32_e32 vcc, 0, v167
	v_lshl_add_u64 v[186:187], v[180:181], 0, v[162:163]
	v_lshl_add_u64 v[198:199], v[178:179], 0, v[162:163]
	v_cndmask_b32_e32 v179, v115, v1, vcc
	v_cndmask_b32_e32 v178, v114, v1, vcc
	s_waitcnt lgkmcnt(0)
	v_pk_mul_f32 v[114:115], v[114:115], v[200:201] op_sel:[0,1]
	v_or_b32_e32 v183, v185, v167
	v_cndmask_b32_e32 v181, v117, v1, vcc
	v_lshl_add_u64 v[202:203], v[186:187], 2, s[18:19]
	v_cndmask_b32_e32 v180, v116, v1, vcc
	v_pk_mul_f32 v[116:117], v[116:117], v[200:201] op_sel:[0,1]
	v_mov_b32_e32 v166, 0x7fc07fc0
	global_store_dwordx4 v[202:203], v[178:181], off sc1
	v_cmp_ne_u32_e64 s[4:5], 0, v183
	v_lshl_add_u64 v[204:205], v[186:187], 1, s[20:21]
	v_cndmask_b32_e32 v187, v121, v1, vcc
	v_cndmask_b32_e32 v186, v120, v1, vcc
	v_cndmask_b32_e32 v185, v119, v1, vcc
	v_cndmask_b32_e32 v184, v118, v1, vcc
	v_pk_mul_f32 v[118:119], v[118:119], v[200:201] op_sel:[0,1]
	v_pk_mul_f32 v[120:121], v[120:121], v[200:201] op_sel:[0,1]
	v_cndmask_b32_e32 v191, v125, v1, vcc
	v_cndmask_b32_e32 v190, v124, v1, vcc
	v_cndmask_b32_e32 v189, v123, v1, vcc
	v_cndmask_b32_e32 v188, v122, v1, vcc
	v_pk_mul_f32 v[122:123], v[122:123], v[200:201] op_sel:[0,1]
	v_pk_mul_f32 v[124:125], v[124:125], v[200:201] op_sel:[0,1]
	v_cndmask_b32_e32 v195, v129, v1, vcc
	v_cndmask_b32_e32 v194, v128, v1, vcc
	v_cndmask_b32_e32 v193, v127, v1, vcc
	v_cndmask_b32_e32 v192, v126, v1, vcc
	v_pk_mul_f32 v[126:127], v[126:127], v[200:201] op_sel:[0,1]
	v_pk_mul_f32 v[128:129], v[128:129], v[200:201] op_sel:[0,1]
	v_lshl_add_u64 v[206:207], v[198:199], 2, s[18:19]
	v_cndmask_b32_e32 v197, v113, v1, vcc
	v_cndmask_b32_e32 v196, v112, v1, vcc
	s_waitcnt vmcnt(7)
	v_pk_fma_f32 v[114:115], v[158:159], v[114:115], v[154:155]
	v_pk_fma_f32 v[116:117], v[160:161], v[116:117], v[156:157]
	v_cvt_pk_bf16_f32 v114, v114, v115
	s_waitcnt vmcnt(5)
	v_pk_fma_f32 v[120:121], v[148:149], v[120:121], v[152:153]
	v_cvt_pk_bf16_f32 v115, v116, v117
	v_cndmask_b32_e64 v114, v114, v166, s[4:5]
	v_cndmask_b32_e64 v115, v115, v166, s[4:5]
	v_pk_fma_f32 v[118:119], v[146:147], v[118:119], v[150:151]
	global_store_dwordx2 v[204:205], v[114:115], off
	global_store_dwordx4 v[202:203], v[184:187], off offset:64 sc1
	v_cvt_pk_bf16_f32 v114, v118, v119
	v_cvt_pk_bf16_f32 v115, v120, v121
	s_waitcnt vmcnt(5)
	v_pk_fma_f32 v[124:125], v[144:145], v[124:125], v[140:141]
	v_cndmask_b32_e64 v115, v115, v166, s[4:5]
	v_cndmask_b32_e64 v114, v114, v166, s[4:5]
	v_pk_fma_f32 v[122:123], v[142:143], v[122:123], v[138:139]
	global_store_dwordx2 v[204:205], v[114:115], off offset:32
	global_store_dwordx4 v[202:203], v[188:191], off offset:512 sc1
	v_cvt_pk_bf16_f32 v114, v122, v123
	v_cvt_pk_bf16_f32 v115, v124, v125
	s_waitcnt vmcnt(5)
	v_pk_fma_f32 v[128:129], v[132:133], v[128:129], v[136:137]
	v_cndmask_b32_e64 v115, v115, v166, s[4:5]
	v_cndmask_b32_e64 v114, v114, v166, s[4:5]
	v_pk_fma_f32 v[126:127], v[130:131], v[126:127], v[134:135]
	global_store_dwordx2 v[204:205], v[114:115], off offset:256
	global_store_dwordx4 v[202:203], v[192:195], off offset:576 sc1
	v_cvt_pk_bf16_f32 v114, v126, v127
	v_cvt_pk_bf16_f32 v115, v128, v129
	v_lshl_add_u64 v[116:117], v[198:199], 1, s[20:21]
	v_cndmask_b32_e64 v115, v115, v166, s[4:5]
	v_cndmask_b32_e64 v114, v114, v166, s[4:5]
	global_store_dwordx2 v[204:205], v[114:115], off offset:288
	ds_read_b64 v[114:115], v182 offset:8320
	v_cndmask_b32_e32 v195, v111, v1, vcc
	v_cndmask_b32_e32 v194, v110, v1, vcc
	global_store_dwordx4 v[206:207], v[194:197], off sc1
	s_waitcnt lgkmcnt(0)
; __device__ __forceinline__ unsigned cvt_pk_bf16(float lo, float hi) { unsigned r; asm volatile("v_cvt_pk_bf16_f32 %0, %1, %2" : "=v"(r) : "v"(lo), "v"(hi)); return r; }
;     __device__ __forceinline__ void fused(f32x4 (&acc)[2][2][4][2], const Unit& u, int wr, int wc, int fr, int fq, PG8_LAS unsigned char* lds, int wid, int lane) const {
;     ...
;         for (int ai = 0; ai < 2; ++ai)
; #pragma unroll
;             for (int m = 0; m < 4; ++m) { const int r = ai * HALF + wr * 64 + m * 16 + fr; const f32x2v sr = S[r]; const size_t off = (size_t)(u.pm * BM + r) * ldc + col0;
; #pragma unroll
;                 for (int bj = 0; bj < 2; ++bj)
; #pragma unroll
;                     for (int n = 0; n < 2; ++n) { const f32x4 x1 = acc[ai][bj][m][n]; *(f32x4*)(out + off + bj * HALF + n * 16) = bad1 ? (f32x4){qnan, qnan, qnan, qnan} : x1;
;                         const f32x4 o = (x1 * sr.y) * ca2[bj][n] + cb2[bj][n]; u32x2v w; w.x = cvt_pk_bf16(o[0], o[1]); w.y = cvt_pk_bf16(o[2], o[3]);
;                         if (bad) { w.x = 0x7fc07fc0u; w.y = 0x7fc07fc0u; } *(u32x2v*)(xn + off + bj * HALF + n * 16) = w; }
;                 asm volatile("" ::: "memory"); }
	v_pk_mul_f32 v[110:111], v[110:111], v[114:115] op_sel:[0,1]
	v_pk_mul_f32 v[112:113], v[112:113], v[114:115] op_sel:[0,1]
	v_pk_fma_f32 v[110:111], v[158:159], v[110:111], v[154:155]
	v_pk_fma_f32 v[112:113], v[160:161], v[112:113], v[156:157]
	v_cvt_pk_bf16_f32 v110, v110, v111
	s_nop 0
	v_cvt_pk_bf16_f32 v111, v112, v113
	v_cndmask_b32_e64 v110, v110, v166, s[4:5]
	v_cndmask_b32_e64 v111, v111, v166, s[4:5]
	global_store_dwordx2 v[116:117], v[110:111], off
	v_cndmask_b32_e32 v111, v107, v1, vcc
	v_cndmask_b32_e32 v110, v106, v1, vcc
	v_pk_mul_f32 v[106:107], v[106:107], v[114:115] op_sel:[0,1]
	v_cndmask_b32_e32 v113, v109, v1, vcc
	v_cndmask_b32_e32 v112, v108, v1, vcc
	v_pk_mul_f32 v[108:109], v[108:109], v[114:115] op_sel:[0,1]
	v_pk_fma_f32 v[106:107], v[146:147], v[106:107], v[150:151]
	global_store_dwordx4 v[206:207], v[110:113], off offset:64 sc1
	v_pk_fma_f32 v[108:109], v[148:149], v[108:109], v[152:153]
	v_cvt_pk_bf16_f32 v106, v106, v107
	s_nop 0
	v_cvt_pk_bf16_f32 v107, v108, v109
	v_cndmask_b32_e64 v106, v106, v166, s[4:5]
	v_cndmask_b32_e64 v107, v107, v166, s[4:5]
	global_store_dwordx2 v[116:117], v[106:107], off offset:32
	v_cndmask_b32_e32 v107, v103, v1, vcc
	v_cndmask_b32_e32 v106, v102, v1, vcc
	v_pk_mul_f32 v[102:103], v[102:103], v[114:115] op_sel:[0,1]
	v_cndmask_b32_e32 v109, v105, v1, vcc
	v_cndmask_b32_e32 v108, v104, v1, vcc
	v_pk_mul_f32 v[104:105], v[104:105], v[114:115] op_sel:[0,1]
	v_pk_fma_f32 v[102:103], v[142:143], v[102:103], v[138:139]
	global_store_dwordx4 v[206:207], v[106:109], off offset:512 sc1
	v_pk_fma_f32 v[104:105], v[144:145], v[104:105], v[140:141]
	v_cvt_pk_bf16_f32 v102, v102, v103
	s_nop 0
	v_cvt_pk_bf16_f32 v103, v104, v105
	v_cndmask_b32_e64 v102, v102, v166, s[4:5]
	v_cndmask_b32_e64 v103, v103, v166, s[4:5]
	global_store_dwordx2 v[116:117], v[102:103], off offset:256
	v_cndmask_b32_e32 v103, v99, v1, vcc
	v_cndmask_b32_e32 v102, v98, v1, vcc
	v_pk_mul_f32 v[98:99], v[98:99], v[114:115] op_sel:[0,1]
	v_cndmask_b32_e32 v105, v101, v1, vcc
	v_cndmask_b32_e32 v104, v100, v1, vcc
	v_pk_mul_f32 v[100:101], v[100:101], v[114:115] op_sel:[0,1]
	v_pk_fma_f32 v[98:99], v[130:131], v[98:99], v[134:135]
	global_store_dwordx4 v[206:207], v[102:105], off offset:576 sc1
	v_pk_fma_f32 v[100:101], v[132:133], v[100:101], v[136:137]
	v_cvt_pk_bf16_f32 v98, v98, v99
	s_nop 0
	v_cvt_pk_bf16_f32 v99, v100, v101
	v_cndmask_b32_e64 v98, v98, v166, s[4:5]
	v_cndmask_b32_e64 v99, v99, v166, s[4:5]
	global_store_dwordx2 v[116:117], v[98:99], off offset:288
	ds_read_b64 v[102:103], v182 offset:8448
	v_lshl_add_u64 v[104:105], v[176:177], 0, v[162:163]
	v_cndmask_b32_e32 v99, v95, v1, vcc
	v_cndmask_b32_e32 v98, v94, v1, vcc
	v_cndmask_b32_e32 v101, v97, v1, vcc
	s_waitcnt lgkmcnt(0)
	v_pk_mul_f32 v[94:95], v[94:95], v[102:103] op_sel:[0,1]
	v_cndmask_b32_e32 v100, v96, v1, vcc
	v_lshl_add_u64 v[106:107], v[104:105], 2, s[18:19]
	v_pk_mul_f32 v[96:97], v[96:97], v[102:103] op_sel:[0,1]
	v_pk_fma_f32 v[94:95], v[158:159], v[94:95], v[154:155]
	global_store_dwordx4 v[106:107], v[98:101], off sc1
	v_pk_fma_f32 v[96:97], v[160:161], v[96:97], v[156:157]
	v_cvt_pk_bf16_f32 v94, v94, v95
	s_nop 0
	v_cvt_pk_bf16_f32 v95, v96, v97
	v_cndmask_b32_e64 v94, v94, v166, s[4:5]
	v_cndmask_b32_e64 v95, v95, v166, s[4:5]
	v_lshl_add_u64 v[98:99], v[104:105], 1, s[20:21]
	global_store_dwordx2 v[98:99], v[94:95], off
	v_cndmask_b32_e32 v95, v91, v1, vcc
	v_cndmask_b32_e32 v94, v90, v1, vcc
	v_pk_mul_f32 v[90:91], v[90:91], v[102:103] op_sel:[0,1]
	v_cndmask_b32_e32 v97, v93, v1, vcc
	v_cndmask_b32_e32 v96, v92, v1, vcc
	v_pk_mul_f32 v[92:93], v[92:93], v[102:103] op_sel:[0,1]
	v_pk_fma_f32 v[90:91], v[146:147], v[90:91], v[150:151]
	global_store_dwordx4 v[106:107], v[94:97], off offset:64 sc1
	v_pk_fma_f32 v[92:93], v[148:149], v[92:93], v[152:153]
	v_cvt_pk_bf16_f32 v90, v90, v91
	s_nop 0
	v_cvt_pk_bf16_f32 v91, v92, v93
	v_cndmask_b32_e64 v90, v90, v166, s[4:5]
	v_cndmask_b32_e64 v91, v91, v166, s[4:5]
	global_store_dwordx2 v[98:99], v[90:91], off offset:32
	v_cndmask_b32_e32 v91, v87, v1, vcc
	v_cndmask_b32_e32 v90, v86, v1, vcc
	v_pk_mul_f32 v[86:87], v[86:87], v[102:103] op_sel:[0,1]
	v_cndmask_b32_e32 v93, v89, v1, vcc
	v_cndmask_b32_e32 v92, v88, v1, vcc
	v_pk_mul_f32 v[88:89], v[88:89], v[102:103] op_sel:[0,1]
	v_pk_fma_f32 v[86:87], v[142:143], v[86:87], v[138:139]
	global_store_dwordx4 v[106:107], v[90:93], off offset:512 sc1
	v_pk_fma_f32 v[88:89], v[144:145], v[88:89], v[140:141]
	v_cvt_pk_bf16_f32 v86, v86, v87
	s_nop 0
	v_cvt_pk_bf16_f32 v87, v88, v89
	v_cndmask_b32_e64 v86, v86, v166, s[4:5]
	v_cndmask_b32_e64 v87, v87, v166, s[4:5]
	global_store_dwordx2 v[98:99], v[86:87], off offset:256
	v_cndmask_b32_e32 v87, v83, v1, vcc
	v_cndmask_b32_e32 v86, v82, v1, vcc
	v_pk_mul_f32 v[82:83], v[82:83], v[102:103] op_sel:[0,1]
	v_cndmask_b32_e32 v89, v85, v1, vcc
	v_cndmask_b32_e32 v88, v84, v1, vcc
	v_pk_mul_f32 v[84:85], v[84:85], v[102:103] op_sel:[0,1]
	v_pk_fma_f32 v[82:83], v[130:131], v[82:83], v[134:135]
	global_store_dwordx4 v[106:107], v[86:89], off offset:576 sc1
	v_pk_fma_f32 v[84:85], v[132:133], v[84:85], v[136:137]
	v_cvt_pk_bf16_f32 v82, v82, v83
	s_nop 0
	v_cvt_pk_bf16_f32 v83, v84, v85
	v_cndmask_b32_e64 v82, v82, v166, s[4:5]
	v_cndmask_b32_e64 v83, v83, v166, s[4:5]
	global_store_dwordx2 v[98:99], v[82:83], off offset:288
	ds_read_b64 v[86:87], v182 offset:8576
	v_lshl_add_u64 v[88:89], v[174:175], 0, v[162:163]
	v_cndmask_b32_e32 v83, v79, v1, vcc
	v_cndmask_b32_e32 v82, v78, v1, vcc
	v_cndmask_b32_e32 v85, v81, v1, vcc
	s_waitcnt lgkmcnt(0)
; __device__ __forceinline__ unsigned cvt_pk_bf16(float lo, float hi) { unsigned r; asm volatile("v_cvt_pk_bf16_f32 %0, %1, %2" : "=v"(r) : "v"(lo), "v"(hi)); return r; }
;     __device__ __forceinline__ void fused(f32x4 (&acc)[2][2][4][2], const Unit& u, int wr, int wc, int fr, int fq, PG8_LAS unsigned char* lds, int wid, int lane) const {
;     ...
;         for (int ai = 0; ai < 2; ++ai)
; #pragma unroll
;             for (int m = 0; m < 4; ++m) { const int r = ai * HALF + wr * 64 + m * 16 + fr; const f32x2v sr = S[r]; const size_t off = (size_t)(u.pm * BM + r) * ldc + col0;
; #pragma unroll
;                 for (int bj = 0; bj < 2; ++bj)
; #pragma unroll
;                     for (int n = 0; n < 2; ++n) { const f32x4 x1 = acc[ai][bj][m][n]; *(f32x4*)(out + off + bj * HALF + n * 16) = bad1 ? (f32x4){qnan, qnan, qnan, qnan} : x1;
;                         const f32x4 o = (x1 * sr.y) * ca2[bj][n] + cb2[bj][n]; u32x2v w; w.x = cvt_pk_bf16(o[0], o[1]); w.y = cvt_pk_bf16(o[2], o[3]);
;                         if (bad) { w.x = 0x7fc07fc0u; w.y = 0x7fc07fc0u; } *(u32x2v*)(xn + off + bj * HALF + n * 16) = w; }
;                 asm volatile("" ::: "memory"); }
	v_pk_mul_f32 v[78:79], v[78:79], v[86:87] op_sel:[0,1]
	v_cndmask_b32_e32 v84, v80, v1, vcc
	v_lshl_add_u64 v[90:91], v[88:89], 2, s[18:19]
	v_pk_mul_f32 v[80:81], v[80:81], v[86:87] op_sel:[0,1]
	v_pk_fma_f32 v[78:79], v[158:159], v[78:79], v[154:155]
	global_store_dwordx4 v[90:91], v[82:85], off sc1
	v_pk_fma_f32 v[80:81], v[160:161], v[80:81], v[156:157]
	v_cvt_pk_bf16_f32 v78, v78, v79
	s_nop 0
	v_cvt_pk_bf16_f32 v79, v80, v81
	v_cndmask_b32_e64 v78, v78, v166, s[4:5]
	v_cndmask_b32_e64 v79, v79, v166, s[4:5]
	v_lshl_add_u64 v[82:83], v[88:89], 1, s[20:21]
	global_store_dwordx2 v[82:83], v[78:79], off
	v_cndmask_b32_e32 v79, v75, v1, vcc
	v_cndmask_b32_e32 v78, v74, v1, vcc
	v_pk_mul_f32 v[74:75], v[74:75], v[86:87] op_sel:[0,1]
	v_cndmask_b32_e32 v81, v77, v1, vcc
	v_cndmask_b32_e32 v80, v76, v1, vcc
	v_pk_mul_f32 v[76:77], v[76:77], v[86:87] op_sel:[0,1]
	v_pk_fma_f32 v[74:75], v[146:147], v[74:75], v[150:151]
	global_store_dwordx4 v[90:91], v[78:81], off offset:64 sc1
	v_pk_fma_f32 v[76:77], v[148:149], v[76:77], v[152:153]
	v_cvt_pk_bf16_f32 v74, v74, v75
	s_nop 0
	v_cvt_pk_bf16_f32 v75, v76, v77
	v_cndmask_b32_e64 v74, v74, v166, s[4:5]
	v_cndmask_b32_e64 v75, v75, v166, s[4:5]
	global_store_dwordx2 v[82:83], v[74:75], off offset:32
	v_cndmask_b32_e32 v75, v71, v1, vcc
	v_cndmask_b32_e32 v74, v70, v1, vcc
	v_pk_mul_f32 v[70:71], v[70:71], v[86:87] op_sel:[0,1]
	v_cndmask_b32_e32 v77, v73, v1, vcc
	v_cndmask_b32_e32 v76, v72, v1, vcc
	v_pk_mul_f32 v[72:73], v[72:73], v[86:87] op_sel:[0,1]
	v_pk_fma_f32 v[70:71], v[142:143], v[70:71], v[138:139]
	global_store_dwordx4 v[90:91], v[74:77], off offset:512 sc1
	v_pk_fma_f32 v[72:73], v[144:145], v[72:73], v[140:141]
	v_cvt_pk_bf16_f32 v70, v70, v71
	s_nop 0
	v_cvt_pk_bf16_f32 v71, v72, v73
	v_cndmask_b32_e64 v70, v70, v166, s[4:5]
	v_cndmask_b32_e64 v71, v71, v166, s[4:5]
	global_store_dwordx2 v[82:83], v[70:71], off offset:256
	v_cndmask_b32_e32 v71, v67, v1, vcc
	v_cndmask_b32_e32 v70, v66, v1, vcc
	v_pk_mul_f32 v[66:67], v[66:67], v[86:87] op_sel:[0,1]
	v_cndmask_b32_e32 v73, v69, v1, vcc
	v_cndmask_b32_e32 v72, v68, v1, vcc
	v_pk_mul_f32 v[68:69], v[68:69], v[86:87] op_sel:[0,1]
	v_pk_fma_f32 v[66:67], v[130:131], v[66:67], v[134:135]
	global_store_dwordx4 v[90:91], v[70:73], off offset:576 sc1
	v_pk_fma_f32 v[68:69], v[132:133], v[68:69], v[136:137]
	v_cvt_pk_bf16_f32 v66, v66, v67
	s_nop 0
	v_cvt_pk_bf16_f32 v67, v68, v69
	v_cndmask_b32_e64 v66, v66, v166, s[4:5]
	v_cndmask_b32_e64 v67, v67, v166, s[4:5]
	global_store_dwordx2 v[82:83], v[66:67], off offset:288
	ds_read_b64 v[70:71], v182 offset:9216
	v_lshl_add_u64 v[72:73], v[172:173], 0, v[162:163]
	v_cndmask_b32_e32 v67, v63, v1, vcc
	v_cndmask_b32_e32 v66, v62, v1, vcc
	v_cndmask_b32_e32 v69, v65, v1, vcc
	s_waitcnt lgkmcnt(0)
	v_pk_mul_f32 v[62:63], v[62:63], v[70:71] op_sel:[0,1]
	v_cndmask_b32_e32 v68, v64, v1, vcc
	v_lshl_add_u64 v[74:75], v[72:73], 2, s[18:19]
	v_pk_mul_f32 v[64:65], v[64:65], v[70:71] op_sel:[0,1]
	v_pk_fma_f32 v[62:63], v[158:159], v[62:63], v[154:155]
	global_store_dwordx4 v[74:75], v[66:69], off sc1
	v_pk_fma_f32 v[64:65], v[160:161], v[64:65], v[156:157]
	v_cvt_pk_bf16_f32 v62, v62, v63
	s_nop 0
	v_cvt_pk_bf16_f32 v63, v64, v65
	v_cndmask_b32_e64 v62, v62, v166, s[4:5]
	v_cndmask_b32_e64 v63, v63, v166, s[4:5]
	v_lshl_add_u64 v[66:67], v[72:73], 1, s[20:21]
	global_store_dwordx2 v[66:67], v[62:63], off
	v_cndmask_b32_e32 v63, v59, v1, vcc
	v_cndmask_b32_e32 v62, v58, v1, vcc
	v_pk_mul_f32 v[58:59], v[58:59], v[70:71] op_sel:[0,1]
	v_cndmask_b32_e32 v65, v61, v1, vcc
	v_cndmask_b32_e32 v64, v60, v1, vcc
	v_pk_mul_f32 v[60:61], v[60:61], v[70:71] op_sel:[0,1]
	v_pk_fma_f32 v[58:59], v[146:147], v[58:59], v[150:151]
	global_store_dwordx4 v[74:75], v[62:65], off offset:64 sc1
	v_pk_fma_f32 v[60:61], v[148:149], v[60:61], v[152:153]
	v_cvt_pk_bf16_f32 v58, v58, v59
	s_nop 0
	v_cvt_pk_bf16_f32 v59, v60, v61
	v_cndmask_b32_e64 v58, v58, v166, s[4:5]
	v_cndmask_b32_e64 v59, v59, v166, s[4:5]
	global_store_dwordx2 v[66:67], v[58:59], off offset:32
	v_cndmask_b32_e32 v59, v55, v1, vcc
	v_cndmask_b32_e32 v58, v54, v1, vcc
	v_pk_mul_f32 v[54:55], v[54:55], v[70:71] op_sel:[0,1]
	v_cndmask_b32_e32 v61, v57, v1, vcc
	v_cndmask_b32_e32 v60, v56, v1, vcc
	v_pk_mul_f32 v[56:57], v[56:57], v[70:71] op_sel:[0,1]
	v_pk_fma_f32 v[54:55], v[142:143], v[54:55], v[138:139]
	global_store_dwordx4 v[74:75], v[58:61], off offset:512 sc1
	v_pk_fma_f32 v[56:57], v[144:145], v[56:57], v[140:141]
	v_cvt_pk_bf16_f32 v54, v54, v55
	s_nop 0
	v_cvt_pk_bf16_f32 v55, v56, v57
	v_cndmask_b32_e64 v54, v54, v166, s[4:5]
	v_cndmask_b32_e64 v55, v55, v166, s[4:5]
	global_store_dwordx2 v[66:67], v[54:55], off offset:256
	v_cndmask_b32_e32 v55, v51, v1, vcc
	v_cndmask_b32_e32 v54, v50, v1, vcc
	v_pk_mul_f32 v[50:51], v[50:51], v[70:71] op_sel:[0,1]
	v_cndmask_b32_e32 v57, v53, v1, vcc
	v_cndmask_b32_e32 v56, v52, v1, vcc
	v_pk_mul_f32 v[52:53], v[52:53], v[70:71] op_sel:[0,1]
	v_pk_fma_f32 v[50:51], v[130:131], v[50:51], v[134:135]
	global_store_dwordx4 v[74:75], v[54:57], off offset:576 sc1
	v_pk_fma_f32 v[52:53], v[132:133], v[52:53], v[136:137]
	v_cvt_pk_bf16_f32 v50, v50, v51
	s_nop 0
	v_cvt_pk_bf16_f32 v51, v52, v53
	v_cndmask_b32_e64 v50, v50, v166, s[4:5]
	v_cndmask_b32_e64 v51, v51, v166, s[4:5]
	global_store_dwordx2 v[66:67], v[50:51], off offset:288
	ds_read_b64 v[54:55], v182 offset:9344
	v_lshl_add_u64 v[56:57], v[170:171], 0, v[162:163]
	v_cndmask_b32_e32 v51, v47, v1, vcc
	v_cndmask_b32_e32 v50, v46, v1, vcc
	v_cndmask_b32_e32 v53, v49, v1, vcc
	s_waitcnt lgkmcnt(0)
; __device__ __forceinline__ unsigned cvt_pk_bf16(float lo, float hi) { unsigned r; asm volatile("v_cvt_pk_bf16_f32 %0, %1, %2" : "=v"(r) : "v"(lo), "v"(hi)); return r; }
;     __device__ __forceinline__ void fused(f32x4 (&acc)[2][2][4][2], const Unit& u, int wr, int wc, int fr, int fq, PG8_LAS unsigned char* lds, int wid, int lane) const {
;     ...
;         for (int ai = 0; ai < 2; ++ai)
; #pragma unroll
;             for (int m = 0; m < 4; ++m) { const int r = ai * HALF + wr * 64 + m * 16 + fr; const f32x2v sr = S[r]; const size_t off = (size_t)(u.pm * BM + r) * ldc + col0;
; #pragma unroll
;                 for (int bj = 0; bj < 2; ++bj)
; #pragma unroll
;                     for (int n = 0; n < 2; ++n) { const f32x4 x1 = acc[ai][bj][m][n]; *(f32x4*)(out + off + bj * HALF + n * 16) = bad1 ? (f32x4){qnan, qnan, qnan, qnan} : x1;
;                         const f32x4 o = (x1 * sr.y) * ca2[bj][n] + cb2[bj][n]; u32x2v w; w.x = cvt_pk_bf16(o[0], o[1]); w.y = cvt_pk_bf16(o[2], o[3]);
;                         if (bad) { w.x = 0x7fc07fc0u; w.y = 0x7fc07fc0u; } *(u32x2v*)(xn + off + bj * HALF + n * 16) = w; }
;                 asm volatile("" ::: "memory"); }
	v_pk_mul_f32 v[46:47], v[46:47], v[54:55] op_sel:[0,1]
	v_cndmask_b32_e32 v52, v48, v1, vcc
	v_lshl_add_u64 v[58:59], v[56:57], 2, s[18:19]
	v_pk_mul_f32 v[48:49], v[48:49], v[54:55] op_sel:[0,1]
	v_pk_fma_f32 v[46:47], v[158:159], v[46:47], v[154:155]
	global_store_dwordx4 v[58:59], v[50:53], off sc1
	v_pk_fma_f32 v[48:49], v[160:161], v[48:49], v[156:157]
	v_cvt_pk_bf16_f32 v46, v46, v47
	s_nop 0
	v_cvt_pk_bf16_f32 v47, v48, v49
	v_cndmask_b32_e64 v46, v46, v166, s[4:5]
	v_cndmask_b32_e64 v47, v47, v166, s[4:5]
	v_lshl_add_u64 v[50:51], v[56:57], 1, s[20:21]
	global_store_dwordx2 v[50:51], v[46:47], off
	v_cndmask_b32_e32 v47, v43, v1, vcc
	v_cndmask_b32_e32 v46, v42, v1, vcc
	v_pk_mul_f32 v[42:43], v[42:43], v[54:55] op_sel:[0,1]
	v_cndmask_b32_e32 v49, v45, v1, vcc
	v_cndmask_b32_e32 v48, v44, v1, vcc
	v_pk_mul_f32 v[44:45], v[44:45], v[54:55] op_sel:[0,1]
	v_pk_fma_f32 v[42:43], v[146:147], v[42:43], v[150:151]
	global_store_dwordx4 v[58:59], v[46:49], off offset:64 sc1
	v_pk_fma_f32 v[44:45], v[148:149], v[44:45], v[152:153]
	v_cvt_pk_bf16_f32 v42, v42, v43
	s_nop 0
	v_cvt_pk_bf16_f32 v43, v44, v45
	v_cndmask_b32_e64 v42, v42, v166, s[4:5]
	v_cndmask_b32_e64 v43, v43, v166, s[4:5]
	global_store_dwordx2 v[50:51], v[42:43], off offset:32
	v_cndmask_b32_e32 v43, v39, v1, vcc
	v_cndmask_b32_e32 v42, v38, v1, vcc
	v_pk_mul_f32 v[38:39], v[38:39], v[54:55] op_sel:[0,1]
	v_cndmask_b32_e32 v45, v41, v1, vcc
	v_cndmask_b32_e32 v44, v40, v1, vcc
	v_pk_mul_f32 v[40:41], v[40:41], v[54:55] op_sel:[0,1]
	v_pk_fma_f32 v[38:39], v[142:143], v[38:39], v[138:139]
	global_store_dwordx4 v[58:59], v[42:45], off offset:512 sc1
	v_pk_fma_f32 v[40:41], v[144:145], v[40:41], v[140:141]
	v_cvt_pk_bf16_f32 v38, v38, v39
	s_nop 0
	v_cvt_pk_bf16_f32 v39, v40, v41
	v_cndmask_b32_e64 v38, v38, v166, s[4:5]
	v_cndmask_b32_e64 v39, v39, v166, s[4:5]
	global_store_dwordx2 v[50:51], v[38:39], off offset:256
	v_cndmask_b32_e32 v39, v35, v1, vcc
	v_cndmask_b32_e32 v38, v34, v1, vcc
	v_pk_mul_f32 v[34:35], v[34:35], v[54:55] op_sel:[0,1]
	v_cndmask_b32_e32 v41, v37, v1, vcc
	v_cndmask_b32_e32 v40, v36, v1, vcc
	v_pk_mul_f32 v[36:37], v[36:37], v[54:55] op_sel:[0,1]
	v_pk_fma_f32 v[34:35], v[130:131], v[34:35], v[134:135]
	global_store_dwordx4 v[58:59], v[38:41], off offset:576 sc1
	v_pk_fma_f32 v[36:37], v[132:133], v[36:37], v[136:137]
	v_cvt_pk_bf16_f32 v34, v34, v35
	s_nop 0
	v_cvt_pk_bf16_f32 v35, v36, v37
	v_cndmask_b32_e64 v34, v34, v166, s[4:5]
	v_cndmask_b32_e64 v35, v35, v166, s[4:5]
	global_store_dwordx2 v[50:51], v[34:35], off offset:288
	ds_read_b64 v[38:39], v182 offset:9472
	v_lshl_add_u64 v[40:41], v[168:169], 0, v[162:163]
	v_cndmask_b32_e32 v35, v31, v1, vcc
	v_cndmask_b32_e32 v34, v30, v1, vcc
	v_cndmask_b32_e32 v37, v33, v1, vcc
	s_waitcnt lgkmcnt(0)
; __device__ __forceinline__ unsigned cvt_pk_bf16(float lo, float hi) { unsigned r; asm volatile("v_cvt_pk_bf16_f32 %0, %1, %2" : "=v"(r) : "v"(lo), "v"(hi)); return r; }
;     __device__ __forceinline__ void fused(f32x4 (&acc)[2][2][4][2], const Unit& u, int wr, int wc, int fr, int fq, PG8_LAS unsigned char* lds, int wid, int lane) const {
;     ...
; #pragma unroll
;         for (int ai = 0; ai < 2; ++ai)
; #pragma unroll
;             for (int m = 0; m < 4; ++m) { const int r = ai * HALF + wr * 64 + m * 16 + fr; const f32x2v sr = S[r]; const size_t off = (size_t)(u.pm * BM + r) * ldc + col0;
; #pragma unroll
;                 for (int bj = 0; bj < 2; ++bj)
; #pragma unroll
;                     for (int n = 0; n < 2; ++n) { const f32x4 x1 = acc[ai][bj][m][n]; *(f32x4*)(out + off + bj * HALF + n * 16) = bad1 ? (f32x4){qnan, qnan, qnan, qnan} : x1;
;                         const f32x4 o = (x1 * sr.y) * ca2[bj][n] + cb2[bj][n]; u32x2v w; w.x = cvt_pk_bf16(o[0], o[1]); w.y = cvt_pk_bf16(o[2], o[3]);
;                         if (bad) { w.x = 0x7fc07fc0u; w.y = 0x7fc07fc0u; } *(u32x2v*)(xn + off + bj * HALF + n * 16) = w; }
;                 asm volatile("" ::: "memory"); }
	v_pk_mul_f32 v[30:31], v[30:31], v[38:39] op_sel:[0,1]
	v_cndmask_b32_e32 v36, v32, v1, vcc
	v_lshl_add_u64 v[42:43], v[40:41], 2, s[18:19]
	v_pk_mul_f32 v[32:33], v[32:33], v[38:39] op_sel:[0,1]
	v_pk_fma_f32 v[30:31], v[158:159], v[30:31], v[154:155]
	global_store_dwordx4 v[42:43], v[34:37], off sc1
	v_pk_fma_f32 v[32:33], v[160:161], v[32:33], v[156:157]
	v_cvt_pk_bf16_f32 v30, v30, v31
	s_nop 0
	v_cvt_pk_bf16_f32 v31, v32, v33
	v_cndmask_b32_e64 v30, v30, v166, s[4:5]
	v_cndmask_b32_e64 v31, v31, v166, s[4:5]
	v_lshl_add_u64 v[34:35], v[40:41], 1, s[20:21]
	global_store_dwordx2 v[34:35], v[30:31], off
	v_cndmask_b32_e32 v31, v27, v1, vcc
	v_cndmask_b32_e32 v30, v26, v1, vcc
	v_pk_mul_f32 v[26:27], v[26:27], v[38:39] op_sel:[0,1]
	v_cndmask_b32_e32 v33, v29, v1, vcc
	v_cndmask_b32_e32 v32, v28, v1, vcc
	v_pk_mul_f32 v[28:29], v[28:29], v[38:39] op_sel:[0,1]
	v_pk_fma_f32 v[26:27], v[146:147], v[26:27], v[150:151]
	global_store_dwordx4 v[42:43], v[30:33], off offset:64 sc1
	v_pk_fma_f32 v[28:29], v[148:149], v[28:29], v[152:153]
	v_cvt_pk_bf16_f32 v26, v26, v27
	s_nop 0
	v_cvt_pk_bf16_f32 v27, v28, v29
	v_cndmask_b32_e64 v26, v26, v166, s[4:5]
	v_cndmask_b32_e64 v27, v27, v166, s[4:5]
	global_store_dwordx2 v[34:35], v[26:27], off offset:32
	v_cndmask_b32_e32 v27, v23, v1, vcc
	v_cndmask_b32_e32 v26, v22, v1, vcc
	v_pk_mul_f32 v[22:23], v[22:23], v[38:39] op_sel:[0,1]
	v_cndmask_b32_e32 v29, v25, v1, vcc
	v_cndmask_b32_e32 v28, v24, v1, vcc
	v_pk_mul_f32 v[24:25], v[24:25], v[38:39] op_sel:[0,1]
	v_pk_fma_f32 v[22:23], v[142:143], v[22:23], v[138:139]
	global_store_dwordx4 v[42:43], v[26:29], off offset:512 sc1
	v_pk_fma_f32 v[24:25], v[144:145], v[24:25], v[140:141]
	v_cvt_pk_bf16_f32 v22, v22, v23
	s_nop 0
	v_cvt_pk_bf16_f32 v23, v24, v25
	v_cndmask_b32_e64 v22, v22, v166, s[4:5]
	v_cndmask_b32_e64 v23, v23, v166, s[4:5]
	global_store_dwordx2 v[34:35], v[22:23], off offset:256
	v_cndmask_b32_e32 v23, v19, v1, vcc
	v_cndmask_b32_e32 v22, v18, v1, vcc
	v_pk_mul_f32 v[18:19], v[18:19], v[38:39] op_sel:[0,1]
	v_cndmask_b32_e32 v25, v21, v1, vcc
	v_cndmask_b32_e32 v24, v20, v1, vcc
	v_pk_mul_f32 v[20:21], v[20:21], v[38:39] op_sel:[0,1]
	v_pk_fma_f32 v[18:19], v[130:131], v[18:19], v[134:135]
	global_store_dwordx4 v[42:43], v[22:25], off offset:576 sc1
	v_pk_fma_f32 v[20:21], v[132:133], v[20:21], v[136:137]
	v_cvt_pk_bf16_f32 v18, v18, v19
	s_nop 0
	v_cvt_pk_bf16_f32 v19, v20, v21
	v_cndmask_b32_e64 v18, v18, v166, s[4:5]
	v_cndmask_b32_e64 v19, v19, v166, s[4:5]
	global_store_dwordx2 v[34:35], v[18:19], off offset:288
	ds_read_b64 v[22:23], v182 offset:9600
	v_lshl_add_u64 v[24:25], v[164:165], 0, v[162:163]
	v_cndmask_b32_e32 v19, v15, v1, vcc
	v_cndmask_b32_e32 v18, v14, v1, vcc
	v_cndmask_b32_e32 v21, v17, v1, vcc
	s_waitcnt lgkmcnt(0)
	v_pk_mul_f32 v[14:15], v[14:15], v[22:23] op_sel:[0,1]
	v_cndmask_b32_e32 v20, v16, v1, vcc
	v_lshl_add_u64 v[26:27], v[24:25], 2, s[18:19]
	v_pk_mul_f32 v[16:17], v[16:17], v[22:23] op_sel:[0,1]
	v_pk_fma_f32 v[14:15], v[158:159], v[14:15], v[154:155]
	global_store_dwordx4 v[26:27], v[18:21], off sc1
	v_pk_fma_f32 v[16:17], v[160:161], v[16:17], v[156:157]
	v_cvt_pk_bf16_f32 v14, v14, v15
	s_nop 0
	v_cvt_pk_bf16_f32 v15, v16, v17
	v_cndmask_b32_e64 v14, v14, v166, s[4:5]
	v_cndmask_b32_e64 v15, v15, v166, s[4:5]
	v_lshl_add_u64 v[18:19], v[24:25], 1, s[20:21]
	global_store_dwordx2 v[18:19], v[14:15], off
	v_cndmask_b32_e32 v15, v11, v1, vcc
	v_cndmask_b32_e32 v14, v10, v1, vcc
	v_pk_mul_f32 v[10:11], v[10:11], v[22:23] op_sel:[0,1]
	v_cndmask_b32_e32 v17, v13, v1, vcc
	v_cndmask_b32_e32 v16, v12, v1, vcc
	v_pk_mul_f32 v[12:13], v[12:13], v[22:23] op_sel:[0,1]
	v_pk_fma_f32 v[10:11], v[146:147], v[10:11], v[150:151]
	global_store_dwordx4 v[26:27], v[14:17], off offset:64 sc1
	v_pk_fma_f32 v[12:13], v[148:149], v[12:13], v[152:153]
	v_cvt_pk_bf16_f32 v10, v10, v11
	s_nop 0
	v_cvt_pk_bf16_f32 v11, v12, v13
	v_cndmask_b32_e64 v10, v10, v166, s[4:5]
	v_cndmask_b32_e64 v11, v11, v166, s[4:5]
	global_store_dwordx2 v[18:19], v[10:11], off offset:32
	v_cndmask_b32_e32 v11, v7, v1, vcc
	v_cndmask_b32_e32 v10, v6, v1, vcc
	v_pk_mul_f32 v[6:7], v[6:7], v[22:23] op_sel:[0,1]
	v_cndmask_b32_e32 v13, v9, v1, vcc
	v_cndmask_b32_e32 v12, v8, v1, vcc
	v_pk_mul_f32 v[8:9], v[8:9], v[22:23] op_sel:[0,1]
	v_pk_fma_f32 v[6:7], v[142:143], v[6:7], v[138:139]
	global_store_dwordx4 v[26:27], v[10:13], off offset:512 sc1
	v_pk_fma_f32 v[8:9], v[144:145], v[8:9], v[140:141]
	v_cvt_pk_bf16_f32 v6, v6, v7
	s_nop 0
	v_cvt_pk_bf16_f32 v7, v8, v9
	v_cndmask_b32_e64 v6, v6, v166, s[4:5]
	v_cndmask_b32_e64 v7, v7, v166, s[4:5]
	global_store_dwordx2 v[18:19], v[6:7], off offset:256
	v_cndmask_b32_e32 v7, v3, v1, vcc
	v_cndmask_b32_e32 v6, v2, v1, vcc
	v_pk_mul_f32 v[2:3], v[2:3], v[22:23] op_sel:[0,1]
	v_cndmask_b32_e32 v9, v5, v1, vcc
	v_cndmask_b32_e32 v8, v4, v1, vcc
	v_pk_mul_f32 v[4:5], v[4:5], v[22:23] op_sel:[0,1]
	v_pk_fma_f32 v[2:3], v[130:131], v[2:3], v[134:135]
	global_store_dwordx4 v[26:27], v[6:9], off offset:576 sc1
	v_pk_fma_f32 v[4:5], v[132:133], v[4:5], v[136:137]
	v_cvt_pk_bf16_f32 v1, v2, v3
	s_nop 0
	v_cvt_pk_bf16_f32 v2, v4, v5
	s_nop 0
	v_cndmask_b32_e64 v3, v2, v166, s[4:5]
	v_cndmask_b32_e64 v2, v1, v166, s[4:5]
	global_store_dwordx2 v[18:19], v[2:3], off offset:288

; __device__ __forceinline__ unsigned cvt_pk_bf16(float lo, float hi) { unsigned r; asm volatile("v_cvt_pk_bf16_f32 %0, %1, %2" : "=v"(r) : "v"(lo), "v"(hi)); return r; }
; __device__ __forceinline__ float silu_f(float x) { return x * __builtin_amdgcn_rcpf(1.0f + __expf(-x)); }
;     __device__ __forceinline__ void operator()(const f32x4 (&acc)[2][2][4][2], const Unit& u, int wr, int wc, int fr, int fq) const {
;         const int row0 = u.pm * BM + wr * 64 + fr, col0 = u.pn * HALF + wc * 32 + 8 * fq;
; #pragma unroll
;         for (int ai = 0; ai < 2; ++ai)
; #pragma unroll
;             for (int m = 0; m < 4; ++m) {
;                 float r[8];
; #pragma unroll
;                 for (int n = 0; n < 2; ++n)
; #pragma unroll
;                     for (int j = 0; j < 4; ++j) r[n * 4 + j] = silu_f(acc[ai][0][m][n][j]) * acc[ai][1][m][n][j];
;                 u32x4 w; w.x = cvt_pk_bf16(r[0], r[1]); w.y = cvt_pk_bf16(r[2], r[3]); w.z = cvt_pk_bf16(r[4], r[5]); w.w = cvt_pk_bf16(r[6], r[7]);
;                 *(u32x4*)(O + (size_t)(row0 + ai * HALF + m * 16) * 2816 + col0) = w;
;             }
.LBB0_1178:
	v_mul_f32_e32 v152, 0xbfb8aa3b, v126
	v_exp_f32_e32 v153, v152
	v_mul_f32_e32 v152, 0xbfb8aa3b, v127
	v_exp_f32_e32 v154, v152
	v_lshl_or_b32 v152, s52, 7, v147
	v_add_f32_e32 v153, 1.0, v153
	v_rcp_f32_e32 v155, v153
	v_add_f32_e32 v153, 1.0, v154
	v_rcp_f32_e32 v154, v153
	v_lshl_add_u32 v151, s38, 8, v1
	v_mul_f32_e32 v126, v126, v155
	v_mul_f32_e32 v118, v126, v118
	v_mul_f32_e32 v126, v127, v154
	v_mul_f32_e32 v127, 0xbfb8aa3b, v128
	v_exp_f32_e32 v127, v127
	v_mul_f32_e32 v154, 0xbfb8aa3b, v129
	v_exp_f32_e32 v154, v154
	v_mul_f32_e32 v119, v126, v119
	v_add_f32_e32 v126, 1.0, v127
	v_rcp_f32_e32 v126, v126
	v_add_f32_e32 v127, 1.0, v154
	v_mul_f32_e32 v154, 0xbfb8aa3b, v122
	v_rcp_f32_e32 v127, v127
	v_exp_f32_e32 v154, v154
	v_mul_f32_e32 v126, v128, v126
	v_mul_f32_e32 v120, v126, v120
	v_mul_f32_e32 v126, v129, v127
	v_add_f32_e32 v127, 1.0, v154
	v_rcp_f32_e32 v127, v127
	v_mul_f32_e32 v128, 0xbfb8aa3b, v123
	v_exp_f32_e32 v128, v128
	v_mul_f32_e32 v121, v126, v121
	v_mul_f32_e32 v122, v122, v127
	v_mul_f32_e32 v114, v122, v114
	v_add_f32_e32 v122, 1.0, v128
	v_mul_f32_e32 v126, 0xbfb8aa3b, v124
	v_rcp_f32_e32 v122, v122
	v_exp_f32_e32 v126, v126
	v_mul_f32_e32 v127, 0xbfb8aa3b, v125
	v_exp_f32_e32 v127, v127
	v_mul_f32_e32 v122, v123, v122
	v_add_f32_e32 v123, 1.0, v126
	v_rcp_f32_e32 v123, v123
	v_add_f32_e32 v126, 1.0, v127
	v_rcp_f32_e32 v126, v126
	v_mul_f32_e32 v115, v122, v115
	v_mul_f32_e32 v122, v124, v123
	v_mul_f32_e32 v124, 0xbfb8aa3b, v110
	v_mul_f32_e32 v116, v122, v116
	v_mul_f32_e32 v122, v125, v126
	v_exp_f32_e32 v124, v124
	v_mul_f32_e32 v125, 0xbfb8aa3b, v111
	v_exp_f32_e32 v125, v125
	v_ashrrev_i32_e32 v153, 31, v152
	v_add_f32_e32 v124, 1.0, v124
	v_rcp_f32_e32 v124, v124
	v_add_f32_e32 v125, 1.0, v125
	v_rcp_f32_e32 v125, v125
	v_mul_f32_e32 v117, v122, v117
	v_cvt_pk_bf16_f32 v118, v118, v119
	v_cvt_pk_bf16_f32 v119, v120, v121
	v_cvt_pk_bf16_f32 v120, v114, v115
	v_mov_b64_e32 v[114:115], s[8:9]
	v_cvt_pk_bf16_f32 v121, v116, v117
	v_mad_i64_i32 v[122:123], s[0:1], v151, s51, v[114:115]
	v_lshlrev_b64 v[116:117], 1, v[152:153]
	v_mul_f32_e32 v110, v110, v124
	v_lshl_add_u64 v[122:123], v[122:123], 0, v[116:117]
	v_mul_f32_e32 v102, v110, v102
	v_mul_f32_e32 v110, v111, v125
	v_mul_f32_e32 v111, 0xbfb8aa3b, v112
	global_store_dwordx4 v[122:123], v[118:121], off sc1
	v_exp_f32_e32 v111, v111
	v_mul_f32_e32 v103, v110, v103
	v_mul_f32_e32 v118, 0xbfb8aa3b, v113
	v_exp_f32_e32 v118, v118
	v_add_f32_e32 v110, 1.0, v111
	v_rcp_f32_e32 v110, v110
	s_andn2_b64 vcc, exec, s[4:5]
	v_add_f32_e32 v111, 1.0, v118
	v_mul_f32_e32 v118, 0xbfb8aa3b, v106
	v_rcp_f32_e32 v111, v111
	v_exp_f32_e32 v118, v118
	v_mul_f32_e32 v110, v112, v110
	v_mul_f32_e32 v104, v110, v104
	v_mul_f32_e32 v110, v113, v111
	v_add_f32_e32 v111, 1.0, v118
	v_rcp_f32_e32 v111, v111
	v_mul_f32_e32 v112, 0xbfb8aa3b, v107
	v_exp_f32_e32 v112, v112
	v_mul_f32_e32 v105, v110, v105
	v_mul_f32_e32 v106, v106, v111
	v_mul_f32_e32 v106, v106, v98
	v_add_f32_e32 v98, 1.0, v112
	v_mul_f32_e32 v110, 0xbfb8aa3b, v108
	v_rcp_f32_e32 v98, v98
	v_exp_f32_e32 v110, v110
	v_mul_f32_e32 v111, 0xbfb8aa3b, v109
	v_exp_f32_e32 v111, v111
	v_mul_f32_e32 v98, v107, v98
	v_add_f32_e32 v107, 1.0, v110
	v_rcp_f32_e32 v107, v107
	v_add_f32_e32 v110, 1.0, v111
	v_rcp_f32_e32 v110, v110
	v_mul_f32_e32 v111, v98, v99
	v_mul_f32_e32 v98, v108, v107
	v_mul_f32_e32 v107, v98, v100
	v_mul_f32_e32 v98, v109, v110
	v_mul_f32_e32 v101, v98, v101
	v_cvt_pk_bf16_f32 v98, v102, v103
	v_cvt_pk_bf16_f32 v99, v104, v105
	v_mul_f32_e32 v104, 0xbfb8aa3b, v94
	v_exp_f32_e32 v104, v104
	v_mul_f32_e32 v105, 0xbfb8aa3b, v95
	v_exp_f32_e32 v105, v105
	v_or_b32_e32 v102, 16, v151
	v_add_f32_e32 v104, 1.0, v104
	v_rcp_f32_e32 v104, v104
	v_add_f32_e32 v105, 1.0, v105
	v_rcp_f32_e32 v105, v105
	v_mad_i64_i32 v[102:103], s[0:1], v102, s51, v[114:115]
	v_mul_f32_e32 v94, v94, v104
	v_lshl_add_u64 v[102:103], v[102:103], 0, v[116:117]
	v_mul_f32_e32 v86, v94, v86
	v_mul_f32_e32 v94, v95, v105
	v_mul_f32_e32 v95, 0xbfb8aa3b, v96
	v_cvt_pk_bf16_f32 v100, v106, v111
	v_cvt_pk_bf16_f32 v101, v107, v101
	global_store_dwordx4 v[102:103], v[98:101], off sc1
	v_exp_f32_e32 v95, v95
	v_mul_f32_e32 v87, v94, v87
	v_mul_f32_e32 v98, 0xbfb8aa3b, v97
	v_exp_f32_e32 v98, v98
	v_add_f32_e32 v94, 1.0, v95
	v_rcp_f32_e32 v94, v94
	v_add_f32_e32 v95, 1.0, v98
	v_mul_f32_e32 v98, 0xbfb8aa3b, v90
	v_rcp_f32_e32 v95, v95
	v_exp_f32_e32 v98, v98
	v_mul_f32_e32 v94, v96, v94
	v_mul_f32_e32 v88, v94, v88
	v_mul_f32_e32 v94, v97, v95
	v_add_f32_e32 v95, 1.0, v98
	v_rcp_f32_e32 v95, v95
	v_mul_f32_e32 v96, 0xbfb8aa3b, v91
	v_exp_f32_e32 v96, v96
	v_mul_f32_e32 v89, v94, v89
	v_mul_f32_e32 v90, v90, v95
	v_mul_f32_e32 v90, v90, v82
	v_add_f32_e32 v82, 1.0, v96
	v_mul_f32_e32 v94, 0xbfb8aa3b, v92
	v_rcp_f32_e32 v82, v82
	v_exp_f32_e32 v94, v94
	v_mul_f32_e32 v95, 0xbfb8aa3b, v93
	v_exp_f32_e32 v95, v95
	v_mul_f32_e32 v82, v91, v82
	v_add_f32_e32 v91, 1.0, v94
	v_rcp_f32_e32 v91, v91
	v_add_f32_e32 v94, 1.0, v95
	v_rcp_f32_e32 v94, v94
	v_mul_f32_e32 v95, v82, v83
	v_mul_f32_e32 v82, v92, v91
	v_mul_f32_e32 v91, v82, v84
	v_mul_f32_e32 v82, v93, v94
	v_mul_f32_e32 v85, v82, v85
	v_cvt_pk_bf16_f32 v82, v86, v87
	v_cvt_pk_bf16_f32 v83, v88, v89
	v_mul_f32_e32 v88, 0xbfb8aa3b, v78
	v_exp_f32_e32 v88, v88
	v_mul_f32_e32 v89, 0xbfb8aa3b, v79
	v_exp_f32_e32 v89, v89
	v_or_b32_e32 v86, 32, v151
	v_add_f32_e32 v88, 1.0, v88
	v_rcp_f32_e32 v88, v88
	v_add_f32_e32 v89, 1.0, v89
	v_rcp_f32_e32 v89, v89
	v_mad_i64_i32 v[86:87], s[0:1], v86, s51, v[114:115]
	v_mul_f32_e32 v78, v78, v88
	v_lshl_add_u64 v[86:87], v[86:87], 0, v[116:117]
; __device__ __forceinline__ unsigned cvt_pk_bf16(float lo, float hi) { unsigned r; asm volatile("v_cvt_pk_bf16_f32 %0, %1, %2" : "=v"(r) : "v"(lo), "v"(hi)); return r; }
; __device__ __forceinline__ float silu_f(float x) { return x * __builtin_amdgcn_rcpf(1.0f + __expf(-x)); }
;     __device__ __forceinline__ void operator()(const f32x4 (&acc)[2][2][4][2], const Unit& u, int wr, int wc, int fr, int fq) const {
;         const int row0 = u.pm * BM + wr * 64 + fr, col0 = u.pn * HALF + wc * 32 + 8 * fq;
; #pragma unroll
;         for (int ai = 0; ai < 2; ++ai)
; #pragma unroll
;             for (int m = 0; m < 4; ++m) {
;                 float r[8];
; #pragma unroll
;                 for (int n = 0; n < 2; ++n)
; #pragma unroll
;                     for (int j = 0; j < 4; ++j) r[n * 4 + j] = silu_f(acc[ai][0][m][n][j]) * acc[ai][1][m][n][j];
;                 u32x4 w; w.x = cvt_pk_bf16(r[0], r[1]); w.y = cvt_pk_bf16(r[2], r[3]); w.z = cvt_pk_bf16(r[4], r[5]); w.w = cvt_pk_bf16(r[6], r[7]);
;                 *(u32x4*)(O + (size_t)(row0 + ai * HALF + m * 16) * 2816 + col0) = w;
;             }
	v_mul_f32_e32 v70, v78, v70
	v_mul_f32_e32 v78, v79, v89
	v_mul_f32_e32 v79, 0xbfb8aa3b, v80
	v_cvt_pk_bf16_f32 v84, v90, v95
	v_cvt_pk_bf16_f32 v85, v91, v85
	global_store_dwordx4 v[86:87], v[82:85], off sc1
	v_exp_f32_e32 v79, v79
	v_mul_f32_e32 v71, v78, v71
	v_mul_f32_e32 v82, 0xbfb8aa3b, v81
	v_exp_f32_e32 v82, v82
	v_add_f32_e32 v78, 1.0, v79
	v_rcp_f32_e32 v78, v78
	v_add_f32_e32 v79, 1.0, v82
	v_mul_f32_e32 v82, 0xbfb8aa3b, v74
	v_rcp_f32_e32 v79, v79
	v_exp_f32_e32 v82, v82
	v_mul_f32_e32 v78, v80, v78
	v_mul_f32_e32 v72, v78, v72
	v_mul_f32_e32 v78, v81, v79
	v_add_f32_e32 v79, 1.0, v82
	v_rcp_f32_e32 v79, v79
	v_mul_f32_e32 v80, 0xbfb8aa3b, v75
	v_exp_f32_e32 v80, v80
	v_mul_f32_e32 v73, v78, v73
	v_mul_f32_e32 v74, v74, v79
	v_mul_f32_e32 v74, v74, v66
	v_add_f32_e32 v66, 1.0, v80
	v_mul_f32_e32 v78, 0xbfb8aa3b, v76
	v_rcp_f32_e32 v66, v66
	v_exp_f32_e32 v78, v78
	v_mul_f32_e32 v79, 0xbfb8aa3b, v77
	v_exp_f32_e32 v79, v79
	v_mul_f32_e32 v66, v75, v66
	v_add_f32_e32 v75, 1.0, v78
	v_rcp_f32_e32 v75, v75
	v_add_f32_e32 v78, 1.0, v79
	v_rcp_f32_e32 v78, v78
	v_mul_f32_e32 v79, v66, v67
	v_mul_f32_e32 v66, v76, v75
	v_mul_f32_e32 v75, v66, v68
	v_mul_f32_e32 v66, v77, v78
	v_mul_f32_e32 v69, v66, v69
	v_cvt_pk_bf16_f32 v66, v70, v71
	v_cvt_pk_bf16_f32 v67, v72, v73
	v_mul_f32_e32 v72, 0xbfb8aa3b, v62
	v_exp_f32_e32 v72, v72
	v_mul_f32_e32 v73, 0xbfb8aa3b, v63
	v_or_b32_e32 v70, 48, v151
	v_exp_f32_e32 v73, v73
	v_mad_i64_i32 v[70:71], s[0:1], v70, s51, v[114:115]
	v_lshl_add_u64 v[70:71], v[70:71], 0, v[116:117]
	v_cvt_pk_bf16_f32 v68, v74, v79
	v_cvt_pk_bf16_f32 v69, v75, v69
	global_store_dwordx4 v[70:71], v[66:69], off sc1
	s_nop 1
	v_add_f32_e32 v66, 1.0, v72
	v_rcp_f32_e32 v66, v66
	v_add_f32_e32 v67, 1.0, v73
	v_rcp_f32_e32 v67, v67
	v_add_u32_e32 v68, 0x80, v151
	v_mul_f32_e32 v62, v62, v66
	v_mul_f32_e32 v54, v62, v54
	v_mul_f32_e32 v62, v63, v67
	v_mul_f32_e32 v63, 0xbfb8aa3b, v64
	v_exp_f32_e32 v63, v63
	v_mul_f32_e32 v66, 0xbfb8aa3b, v65
	v_exp_f32_e32 v66, v66
	v_mul_f32_e32 v55, v62, v55
	v_add_f32_e32 v62, 1.0, v63
	v_rcp_f32_e32 v62, v62
	v_add_f32_e32 v63, 1.0, v66
	v_mul_f32_e32 v66, 0xbfb8aa3b, v58
	v_rcp_f32_e32 v63, v63
	v_exp_f32_e32 v66, v66
	v_mul_f32_e32 v62, v64, v62
	v_mul_f32_e32 v56, v62, v56
	v_mul_f32_e32 v62, v65, v63
	v_add_f32_e32 v63, 1.0, v66
	v_rcp_f32_e32 v63, v63
	v_mul_f32_e32 v64, 0xbfb8aa3b, v59
	v_exp_f32_e32 v64, v64
	v_mul_f32_e32 v57, v62, v57
	v_mul_f32_e32 v58, v58, v63
	v_mul_f32_e32 v58, v58, v50
	v_add_f32_e32 v50, 1.0, v64
	v_mul_f32_e32 v62, 0xbfb8aa3b, v60
	v_rcp_f32_e32 v50, v50
	v_exp_f32_e32 v62, v62
	v_mul_f32_e32 v63, 0xbfb8aa3b, v61
	v_exp_f32_e32 v63, v63
	v_mul_f32_e32 v50, v59, v50
	v_add_f32_e32 v59, 1.0, v62
	v_rcp_f32_e32 v59, v59
	v_add_f32_e32 v62, 1.0, v63
	v_rcp_f32_e32 v62, v62
	v_mul_f32_e32 v63, v50, v51
	v_mul_f32_e32 v50, v60, v59
	v_mul_f32_e32 v59, v50, v52
	v_mul_f32_e32 v50, v61, v62
	v_mul_f32_e32 v53, v50, v53
	v_cvt_pk_bf16_f32 v50, v54, v55
	v_cvt_pk_bf16_f32 v51, v56, v57
	v_mul_f32_e32 v56, 0xbfb8aa3b, v46
	v_exp_f32_e32 v56, v56
	v_mul_f32_e32 v57, 0xbfb8aa3b, v47
	v_exp_f32_e32 v57, v57
	v_mad_i64_i32 v[54:55], s[0:1], v68, s51, v[114:115]
	v_add_f32_e32 v56, 1.0, v56
	v_rcp_f32_e32 v56, v56
	v_add_f32_e32 v57, 1.0, v57
	v_rcp_f32_e32 v57, v57
	v_lshl_add_u64 v[54:55], v[54:55], 0, v[116:117]
	v_mul_f32_e32 v46, v46, v56
	v_mul_f32_e32 v38, v46, v38
	v_mul_f32_e32 v46, v47, v57
	v_mul_f32_e32 v47, 0xbfb8aa3b, v48
	v_cvt_pk_bf16_f32 v52, v58, v63
	v_cvt_pk_bf16_f32 v53, v59, v53
	global_store_dwordx4 v[54:55], v[50:53], off sc1
	v_exp_f32_e32 v47, v47
	v_mul_f32_e32 v39, v46, v39
	v_mul_f32_e32 v50, 0xbfb8aa3b, v49
	v_exp_f32_e32 v50, v50
	v_add_f32_e32 v46, 1.0, v47
	v_rcp_f32_e32 v46, v46
	v_add_f32_e32 v47, 1.0, v50
	v_mul_f32_e32 v50, 0xbfb8aa3b, v42
	v_rcp_f32_e32 v47, v47
	v_exp_f32_e32 v50, v50
	v_mul_f32_e32 v46, v48, v46
	v_mul_f32_e32 v40, v46, v40
	v_mul_f32_e32 v46, v49, v47
	v_add_f32_e32 v47, 1.0, v50
	v_rcp_f32_e32 v47, v47
	v_mul_f32_e32 v48, 0xbfb8aa3b, v43
	v_exp_f32_e32 v48, v48
	v_mul_f32_e32 v41, v46, v41
	v_mul_f32_e32 v42, v42, v47
	v_mul_f32_e32 v42, v42, v34
	v_add_f32_e32 v34, 1.0, v48
; __device__ __forceinline__ unsigned cvt_pk_bf16(float lo, float hi) { unsigned r; asm volatile("v_cvt_pk_bf16_f32 %0, %1, %2" : "=v"(r) : "v"(lo), "v"(hi)); return r; }
; __device__ __forceinline__ float silu_f(float x) { return x * __builtin_amdgcn_rcpf(1.0f + __expf(-x)); }
;     __device__ __forceinline__ void operator()(const f32x4 (&acc)[2][2][4][2], const Unit& u, int wr, int wc, int fr, int fq) const {
;         const int row0 = u.pm * BM + wr * 64 + fr, col0 = u.pn * HALF + wc * 32 + 8 * fq;
; #pragma unroll
;         for (int ai = 0; ai < 2; ++ai)
; #pragma unroll
;             for (int m = 0; m < 4; ++m) {
;                 float r[8];
; #pragma unroll
;                 for (int n = 0; n < 2; ++n)
; #pragma unroll
;                     for (int j = 0; j < 4; ++j) r[n * 4 + j] = silu_f(acc[ai][0][m][n][j]) * acc[ai][1][m][n][j];
;                 u32x4 w; w.x = cvt_pk_bf16(r[0], r[1]); w.y = cvt_pk_bf16(r[2], r[3]); w.z = cvt_pk_bf16(r[4], r[5]); w.w = cvt_pk_bf16(r[6], r[7]);
;                 *(u32x4*)(O + (size_t)(row0 + ai * HALF + m * 16) * 2816 + col0) = w;
;             }
	v_mul_f32_e32 v46, 0xbfb8aa3b, v44
	v_rcp_f32_e32 v34, v34
	v_exp_f32_e32 v46, v46
	v_mul_f32_e32 v47, 0xbfb8aa3b, v45
	v_exp_f32_e32 v47, v47
	v_mul_f32_e32 v34, v43, v34
	v_add_f32_e32 v43, 1.0, v46
	v_rcp_f32_e32 v43, v43
	v_add_f32_e32 v46, 1.0, v47
	v_rcp_f32_e32 v46, v46
	v_mul_f32_e32 v47, v34, v35
	v_mul_f32_e32 v34, v44, v43
	v_mul_f32_e32 v43, v34, v36
	v_mul_f32_e32 v34, v45, v46
	v_mul_f32_e32 v37, v34, v37
	v_cvt_pk_bf16_f32 v34, v38, v39
	v_cvt_pk_bf16_f32 v35, v40, v41
	v_mul_f32_e32 v40, 0xbfb8aa3b, v30
	v_exp_f32_e32 v40, v40
	v_mul_f32_e32 v41, 0xbfb8aa3b, v31
	v_exp_f32_e32 v41, v41
	v_add_u32_e32 v38, 0x90, v151
	v_add_f32_e32 v40, 1.0, v40
	v_rcp_f32_e32 v40, v40
	v_add_f32_e32 v41, 1.0, v41
	v_rcp_f32_e32 v41, v41
	v_mad_i64_i32 v[38:39], s[0:1], v38, s51, v[114:115]
	v_mul_f32_e32 v30, v30, v40
	v_lshl_add_u64 v[38:39], v[38:39], 0, v[116:117]
	v_mul_f32_e32 v22, v30, v22
	v_mul_f32_e32 v30, v31, v41
	v_mul_f32_e32 v31, 0xbfb8aa3b, v32
	v_cvt_pk_bf16_f32 v36, v42, v47
	v_cvt_pk_bf16_f32 v37, v43, v37
	global_store_dwordx4 v[38:39], v[34:37], off sc1
	v_exp_f32_e32 v31, v31
	v_mul_f32_e32 v23, v30, v23
	v_mul_f32_e32 v34, 0xbfb8aa3b, v33
	v_exp_f32_e32 v34, v34
	v_add_f32_e32 v30, 1.0, v31
	v_rcp_f32_e32 v30, v30
	v_add_f32_e32 v31, 1.0, v34
	v_mul_f32_e32 v34, 0xbfb8aa3b, v26
	v_rcp_f32_e32 v31, v31
	v_exp_f32_e32 v34, v34
	v_mul_f32_e32 v30, v32, v30
	v_mul_f32_e32 v24, v30, v24
	v_mul_f32_e32 v30, v33, v31
	v_add_f32_e32 v31, 1.0, v34
	v_rcp_f32_e32 v31, v31
	v_mul_f32_e32 v32, 0xbfb8aa3b, v27
	v_exp_f32_e32 v32, v32
	v_mul_f32_e32 v25, v30, v25
	v_mul_f32_e32 v26, v26, v31
	v_mul_f32_e32 v26, v26, v18
	v_add_f32_e32 v18, 1.0, v32
	v_mul_f32_e32 v30, 0xbfb8aa3b, v28
	v_rcp_f32_e32 v18, v18
	v_exp_f32_e32 v30, v30
	v_mul_f32_e32 v31, 0xbfb8aa3b, v29
	v_exp_f32_e32 v31, v31
	v_mul_f32_e32 v18, v27, v18
	v_add_f32_e32 v27, 1.0, v30
	v_rcp_f32_e32 v27, v27
	v_add_f32_e32 v30, 1.0, v31
	v_rcp_f32_e32 v30, v30
	v_mul_f32_e32 v31, v18, v19
	v_mul_f32_e32 v18, v28, v27
	v_mul_f32_e32 v27, v18, v20
	v_mul_f32_e32 v18, v29, v30
	v_mul_f32_e32 v21, v18, v21
	v_cvt_pk_bf16_f32 v18, v22, v23
	v_cvt_pk_bf16_f32 v19, v24, v25
	v_mul_f32_e32 v24, 0xbfb8aa3b, v14
	v_exp_f32_e32 v24, v24
	v_mul_f32_e32 v25, 0xbfb8aa3b, v15
	v_exp_f32_e32 v25, v25
	v_add_u32_e32 v22, 0xa0, v151
	v_add_f32_e32 v24, 1.0, v24
	v_rcp_f32_e32 v24, v24
	v_add_f32_e32 v25, 1.0, v25
	v_rcp_f32_e32 v25, v25
	v_mad_i64_i32 v[22:23], s[0:1], v22, s51, v[114:115]
	v_mul_f32_e32 v14, v14, v24
	v_lshl_add_u64 v[22:23], v[22:23], 0, v[116:117]
	v_mul_f32_e32 v6, v14, v6
	v_mul_f32_e32 v14, v15, v25
	v_mul_f32_e32 v15, 0xbfb8aa3b, v16
	v_cvt_pk_bf16_f32 v20, v26, v31
	v_cvt_pk_bf16_f32 v21, v27, v21
	global_store_dwordx4 v[22:23], v[18:21], off sc1
	v_exp_f32_e32 v15, v15
	v_mul_f32_e32 v7, v14, v7
	v_mul_f32_e32 v18, 0xbfb8aa3b, v17
	v_exp_f32_e32 v18, v18
	v_add_f32_e32 v14, 1.0, v15
	v_rcp_f32_e32 v14, v14
	v_add_f32_e32 v15, 1.0, v18
	v_mul_f32_e32 v18, 0xbfb8aa3b, v10
	v_rcp_f32_e32 v15, v15
	v_exp_f32_e32 v18, v18
	v_mul_f32_e32 v14, v16, v14
	v_mul_f32_e32 v8, v14, v8
	v_mul_f32_e32 v14, v17, v15
	v_add_f32_e32 v15, 1.0, v18
	v_rcp_f32_e32 v15, v15
	v_mul_f32_e32 v16, 0xbfb8aa3b, v11
	v_exp_f32_e32 v16, v16
	v_mul_f32_e32 v9, v14, v9
	v_mul_f32_e32 v10, v10, v15
	v_mul_f32_e32 v10, v10, v2
	v_add_f32_e32 v2, 1.0, v16
	v_mul_f32_e32 v14, 0xbfb8aa3b, v12
	v_rcp_f32_e32 v2, v2
	v_exp_f32_e32 v14, v14
	v_mul_f32_e32 v15, 0xbfb8aa3b, v13
	v_exp_f32_e32 v15, v15
	v_mul_f32_e32 v2, v11, v2
	v_add_f32_e32 v11, 1.0, v14
	v_rcp_f32_e32 v11, v11
	v_add_f32_e32 v14, 1.0, v15
	v_rcp_f32_e32 v14, v14
	v_mul_f32_e32 v15, v2, v3
	v_mul_f32_e32 v2, v12, v11
	v_mul_f32_e32 v11, v2, v4
	v_mul_f32_e32 v2, v13, v14
	v_mul_f32_e32 v5, v2, v5
	v_cvt_pk_bf16_f32 v2, v6, v7
	v_add_u32_e32 v6, 0xb0, v151
	v_mad_i64_i32 v[6:7], s[0:1], v6, s51, v[114:115]
	v_lshl_add_u64 v[6:7], v[6:7], 0, v[116:117]
	s_mov_b64 s[0:1], -1
	v_cvt_pk_bf16_f32 v3, v8, v9
	v_cvt_pk_bf16_f32 v4, v10, v15
	v_cvt_pk_bf16_f32 v5, v11, v5
	global_store_dwordx4 v[6:7], v[2:5], off sc1
	s_cbranch_vccnz .LBB0_1171
	s_andn2_b64 vcc, exec, s[10:11]
	s_cbranch_vccnz .LBB0_1170
	s_barrier
	s_branch .LBB0_1170

; #define LAS __attribute__((address_space(3)))
; __device__ __forceinline__ unsigned pk2(float lo, float hi) { const f32x2cv v = {lo, hi}; const bf16x2cv b = __builtin_convertvector(v, bf16x2cv); return __builtin_bit_cast(unsigned, b); }
; #define LDS_WAIT() asm volatile("s_waitcnt lgkmcnt(0)" ::: "memory")
; __device__ __forceinline__ void transpose_item(const float* W, int K, int N, bf16* WT, int dst_row0, int k0, int n0, LAS float* scr, int lane) {
;     ...
;     for (int i = 0; i < 8; ++i) { const int kk = 8 * i + (lane >> 3), c4 = 4 * (lane & 7), n = n0 + c4;
;         const f32x4 v = (n < N) ? *(const f32x4*)(W + (size_t)(k0 + kk) * N + n) : (f32x4){0.f, 0.f, 0.f, 0.f};
;         scr[kk * 33 + c4] = v.x; scr[kk * 33 + c4 + 1] = v.y; scr[kk * 33 + c4 + 2] = v.z; scr[kk * 33 + c4 + 3] = v.w; }
;     LDS_WAIT(); asm volatile("" ::: "memory");
;     const int c = lane & 7;
; #pragma unroll
;     for (int j = 0; j < 4; ++j) { const int n = (lane >> 3) + 8 * j; const LAS float* s = scr + (8 * c) * 33 + n;
;         v4u o; o.x = pk2(s[0 * 33], s[1 * 33]); o.y = pk2(s[2 * 33], s[3 * 33]); o.z = pk2(s[4 * 33], s[5 * 33]); o.w = pk2(s[6 * 33], s[7 * 33]);
;         *(v4u*)(WT + (size_t)(dst_row0 + n) * K + k0 + 8 * c) = o; }
;     LDS_WAIT(); asm volatile("" ::: "memory");
; __global__ void __launch_bounds__(NT, 2) fwd_kernel(Args args) {
;     ...
;             for (int it = (bl - 128) * NW + wave; it < 44 * 32; it += 128 * NW) { const int kb = it / 32, nb = it % 32; transpose_item(w_down, DFF, 1024, Wdn_t, 32 * nb, 64 * kb, 32 * nb, scr, lane); }
.LBB0_1185:
	s_ashr_i32 s1, s0, 31
	s_lshr_b32 s1, s1, 27
	s_add_i32 s1, s0, s1
	s_ashr_i32 s1, s1, 5
	s_lshl_b32 s4, s1, 6
	s_lshl_b32 s3, s1, 10
	v_subrev_u32_e32 v30, s3, v13
	v_or_b32_e32 v32, s4, v1
	v_or_b32_e32 v34, s4, v4
	v_or_b32_e32 v36, s4, v5
	v_or_b32_e32 v38, s4, v6
	v_or_b32_e32 v40, s4, v7
	v_or_b32_e32 v42, s4, v8
	v_or_b32_e32 v44, s4, v9
	v_or_b32_e32 v46, s4, v10
	v_ashrrev_i32_e32 v31, 31, v30
	v_ashrrev_i32_e32 v33, 31, v32
	v_ashrrev_i32_e32 v35, 31, v34
	v_ashrrev_i32_e32 v37, 31, v36
	v_ashrrev_i32_e32 v39, 31, v38
	v_ashrrev_i32_e32 v41, 31, v40
	v_ashrrev_i32_e32 v43, 31, v42
	v_ashrrev_i32_e32 v45, 31, v44
	v_ashrrev_i32_e32 v47, 31, v46
	v_lshl_add_u64 v[30:31], v[30:31], 2, s[6:7]
	v_lshlrev_b64 v[32:33], 12, v[32:33]
	v_lshlrev_b64 v[34:35], 12, v[34:35]
	v_lshlrev_b64 v[36:37], 12, v[36:37]
	v_lshlrev_b64 v[38:39], 12, v[38:39]
	v_lshlrev_b64 v[40:41], 12, v[40:41]
	v_lshlrev_b64 v[42:43], 12, v[42:43]
	v_lshlrev_b64 v[44:45], 12, v[44:45]
	v_lshlrev_b64 v[46:47], 12, v[46:47]
	v_lshl_add_u64 v[62:63], v[30:31], 0, v[32:33]
	v_lshl_add_u64 v[64:65], v[30:31], 0, v[34:35]
	v_lshl_add_u64 v[66:67], v[30:31], 0, v[36:37]
	v_lshl_add_u64 v[68:69], v[30:31], 0, v[38:39]
	v_lshl_add_u64 v[70:71], v[30:31], 0, v[40:41]
	v_lshl_add_u64 v[72:73], v[30:31], 0, v[42:43]
	v_lshl_add_u64 v[74:75], v[30:31], 0, v[44:45]
	v_lshl_add_u64 v[76:77], v[30:31], 0, v[46:47]
	global_load_dwordx4 v[30:33], v[62:63], off
	global_load_dwordx4 v[34:37], v[64:65], off
	global_load_dwordx4 v[38:41], v[66:67], off
	global_load_dwordx4 v[42:45], v[68:69], off
	global_load_dwordx4 v[46:49], v[70:71], off
	global_load_dwordx4 v[50:53], v[72:73], off
	global_load_dwordx4 v[54:57], v[74:75], off
	global_load_dwordx4 v[58:61], v[76:77], off
	s_mul_i32 s1, s1, 0xffd40000
	v_add_u32_e32 v62, s1, v12
	s_ashr_i32 s5, s4, 31
	v_add_u32_e32 v66, 0x5800, v62
	v_add_u32_e32 v68, 0xb000, v62
	v_add_u32_e32 v70, 0x10800, v62
	v_lshl_add_u64 v[64:65], s[4:5], 1, v[2:3]
	v_ashrrev_i32_e32 v63, 31, v62
	v_ashrrev_i32_e32 v67, 31, v66
	v_ashrrev_i32_e32 v69, 31, v68
	v_ashrrev_i32_e32 v71, 31, v70
	v_lshl_add_u64 v[62:63], v[62:63], 1, v[64:65]
	v_lshl_add_u64 v[66:67], v[66:67], 1, v[64:65]
	v_lshl_add_u64 v[68:69], v[68:69], 1, v[64:65]
	v_lshl_add_u64 v[64:65], v[70:71], 1, v[64:65]
	s_add_i32 s3, s0, 0x400
	v_add_u32_e32 v12, 0x5800000, v12
	v_add_u32_e32 v13, 0x8000, v13
	s_cmpk_lt_i32 s0, 0x180
	s_mov_b32 s0, s3
	s_waitcnt vmcnt(7)
	ds_write2_b32 v14, v30, v31 offset1:1
	ds_write2_b32 v14, v32, v33 offset0:2 offset1:3
	s_waitcnt vmcnt(6)
	ds_write2_b32 v15, v34, v35 offset1:1
	ds_write2_b32 v16, v36, v37 offset1:1
	s_waitcnt vmcnt(5)
	ds_write2_b32 v17, v38, v39 offset1:1
	ds_write2_b32 v18, v40, v41 offset1:1
	s_waitcnt vmcnt(4)
	ds_write2_b32 v19, v42, v43 offset1:1
	ds_write2_b32 v20, v44, v45 offset1:1
	s_waitcnt vmcnt(3)
	ds_write2_b32 v21, v46, v47 offset1:1
	ds_write2_b32 v22, v48, v49 offset1:1
	s_waitcnt vmcnt(2)
	ds_write2_b32 v23, v50, v51 offset1:1
	ds_write2_b32 v24, v52, v53 offset1:1
	s_waitcnt vmcnt(1)
	ds_write2_b32 v25, v54, v55 offset1:1
	ds_write2_b32 v26, v56, v57 offset1:1
	s_waitcnt vmcnt(0)
	ds_write2_b32 v27, v58, v59 offset1:1
	ds_write2_b32 v28, v60, v61 offset1:1
	s_waitcnt lgkmcnt(0)
	ds_read2_b32 v[34:35], v11 offset0:33 offset1:41
	ds_read2_b32 v[36:37], v11 offset1:8
	ds_read2_b32 v[38:39], v11 offset0:66 offset1:74
	ds_read2_b32 v[40:41], v11 offset0:99 offset1:107
	ds_read2_b32 v[42:43], v11 offset0:132 offset1:140
	ds_read2_b32 v[44:45], v11 offset0:165 offset1:173
	ds_read2_b32 v[46:47], v11 offset0:198 offset1:206
	ds_read2_b32 v[48:49], v11 offset0:231 offset1:239
	ds_read2_b32 v[50:51], v11 offset0:49 offset1:57
	ds_read2_b32 v[52:53], v11 offset0:16 offset1:24
	ds_read2_b32 v[54:55], v11 offset0:82 offset1:90
	ds_read2_b32 v[56:57], v11 offset0:115 offset1:123
	ds_read2_b32 v[58:59], v11 offset0:148 offset1:156
	ds_read2_b32 v[60:61], v11 offset0:181 offset1:189
	ds_read2_b32 v[70:71], v11 offset0:214 offset1:222
	ds_read2_b32 v[72:73], v11 offset0:247 offset1:255
	s_waitcnt lgkmcnt(14)
	v_cvt_pk_bf16_f32 v30, v36, v34
	s_waitcnt lgkmcnt(12)
	v_cvt_pk_bf16_f32 v31, v38, v40
	s_waitcnt lgkmcnt(10)
	v_cvt_pk_bf16_f32 v32, v42, v44
	s_waitcnt lgkmcnt(8)
	v_cvt_pk_bf16_f32 v33, v46, v48
	v_cvt_pk_bf16_f32 v34, v37, v35
	v_cvt_pk_bf16_f32 v35, v39, v41
	v_cvt_pk_bf16_f32 v36, v43, v45
	v_cvt_pk_bf16_f32 v37, v47, v49
	s_waitcnt lgkmcnt(6)
	v_cvt_pk_bf16_f32 v38, v52, v50
	s_waitcnt lgkmcnt(4)
	v_cvt_pk_bf16_f32 v39, v54, v56
	s_waitcnt lgkmcnt(2)
	v_cvt_pk_bf16_f32 v40, v58, v60
	s_waitcnt lgkmcnt(0)
	v_cvt_pk_bf16_f32 v41, v70, v72
	v_cvt_pk_bf16_f32 v42, v53, v51
	v_cvt_pk_bf16_f32 v43, v55, v57
	v_cvt_pk_bf16_f32 v44, v59, v61
	v_cvt_pk_bf16_f32 v45, v71, v73
	global_store_dwordx4 v[62:63], v[30:33], off sc1
	global_store_dwordx4 v[66:67], v[34:37], off sc1
	global_store_dwordx4 v[68:69], v[38:41], off sc1
	global_store_dwordx4 v[64:65], v[42:45], off sc1
	s_waitcnt lgkmcnt(0)
	s_cbranch_scc1 .LBB0_1185

;     __device__ __forceinline__ void fused(f32x4 (&acc)[2][2][4][2], const Unit& u, int wr, int wc, int fr, int fq, PG8_LAS unsigned char* lds, int wid, int lane) const {
;     ...
;         const float qnan = __builtin_nanf("");
; #pragma unroll
;         for (int ai = 0; ai < 2; ++ai)
; #pragma unroll
;             for (int m = 0; m < 4; ++m) { const int r = ai * HALF + wr * 64 + m * 16 + fr; const f32x2v sr = S[r]; const size_t off = (size_t)(u.pm * BM + r) * ldc + col0;
; #pragma unroll
;                 for (int bj = 0; bj < 2; ++bj)
; #pragma unroll
;                     for (int n = 0; n < 2; ++n) { const f32x4 bs = ai == 0 ? pre[m][bj][n] : *(const f32x4*)(base + off + bj * HALF + n * 16); f32x4 o = bs + cvv[bj][n] * (acc[ai][bj][m][n] * sr.y);
;                         if (bad) o = (f32x4){qnan, qnan, qnan, qnan}; *(f32x4*)(out + off + bj * HALF + n * 16) = o; }
.LBB0_1304:
	s_or_b64 exec, exec, s[2:3]
	v_lshl_add_u32 v0, v219, 3, 0
	s_waitcnt lgkmcnt(0)
	s_barrier
	v_add_u32_e32 v216, 0x2000, v0
	ds_read2_b64 v[220:223], v216 offset1:16
	s_waitcnt vmcnt(0) lgkmcnt(0)
	v_or_b32_e32 v217, v217, v218
	v_add_u32_e32 v0, s16, v219
	v_ashrrev_i32_e32 v1, 31, v0
	v_cmp_ne_u32_e32 vcc, 0, v217
	v_pk_mul_f32 v[128:129], v[128:129], v[220:221] op_sel:[0,1]
	v_pk_mul_f32 v[126:127], v[126:127], v[220:221] op_sel:[0,1]
	v_pk_fma_f32 v[128:129], v[144:145], v[128:129], v[208:209]
	v_pk_fma_f32 v[206:207], v[142:143], v[126:127], v[206:207]
	v_mov_b32_e32 v126, 0x7fc00000
	v_cndmask_b32_e32 v209, v129, v126, vcc
	v_cndmask_b32_e32 v208, v128, v126, vcc
	v_lshlrev_b64 v[128:129], 12, v[0:1]
	v_pk_mul_f32 v[120:121], v[120:121], v[220:221] op_sel:[0,1]
	v_pk_mul_f32 v[118:119], v[118:119], v[220:221] op_sel:[0,1]
	v_pk_mul_f32 v[112:113], v[112:113], v[220:221] op_sel:[0,1]
	v_pk_mul_f32 v[110:111], v[110:111], v[220:221] op_sel:[0,1]
	v_lshl_add_u64 v[128:129], s[76:77], 0, v[128:129]
	v_pk_fma_f32 v[118:119], v[134:135], v[118:119], v[198:199]
	v_pk_fma_f32 v[120:121], v[136:137], v[120:121], v[200:201]
	v_pk_fma_f32 v[110:111], v[130:131], v[110:111], v[194:195]
	v_pk_fma_f32 v[112:113], v[132:133], v[112:113], v[196:197]
	v_lshl_add_u64 v[128:129], v[128:129], 0, v[214:215]
	v_cndmask_b32_e32 v121, v121, v126, vcc
	v_cndmask_b32_e32 v120, v120, v126, vcc
	v_cndmask_b32_e32 v119, v119, v126, vcc
	v_cndmask_b32_e32 v118, v118, v126, vcc
	v_cndmask_b32_e32 v113, v113, v126, vcc
	v_cndmask_b32_e32 v112, v112, v126, vcc
	v_cndmask_b32_e32 v111, v111, v126, vcc
	v_cndmask_b32_e32 v110, v110, v126, vcc
	global_store_dwordx4 v[128:129], v[118:121], off offset:512 sc1
	global_store_dwordx4 v[128:129], v[110:113], off offset:576 sc1
	v_pk_mul_f32 v[124:125], v[124:125], v[220:221] op_sel:[0,1]
	v_add_u32_e32 v118, 16, v0
	v_pk_mul_f32 v[110:111], v[116:117], v[222:223] op_sel:[0,1]
	v_pk_mul_f32 v[112:113], v[114:115], v[222:223] op_sel:[0,1]
	v_ashrrev_i32_e32 v119, 31, v118
	v_pk_fma_f32 v[114:115], v[142:143], v[112:113], v[190:191]
	v_pk_fma_f32 v[110:111], v[144:145], v[110:111], v[192:193]
	v_pk_mul_f32 v[122:123], v[122:123], v[220:221] op_sel:[0,1]
	v_cndmask_b32_e32 v113, v111, v126, vcc
	v_cndmask_b32_e32 v112, v110, v126, vcc
	v_cndmask_b32_e32 v111, v115, v126, vcc
	v_cndmask_b32_e32 v110, v114, v126, vcc
	v_lshlrev_b64 v[114:115], 12, v[118:119]
	v_pk_mul_f32 v[108:109], v[108:109], v[222:223] op_sel:[0,1]
	v_pk_mul_f32 v[106:107], v[106:107], v[222:223] op_sel:[0,1]
	v_pk_mul_f32 v[104:105], v[104:105], v[222:223] op_sel:[0,1]
	v_pk_mul_f32 v[102:103], v[102:103], v[222:223] op_sel:[0,1]
	v_pk_mul_f32 v[96:97], v[96:97], v[222:223] op_sel:[0,1]
	v_pk_mul_f32 v[94:95], v[94:95], v[222:223] op_sel:[0,1]
	v_pk_fma_f32 v[122:123], v[138:139], v[122:123], v[202:203]
	v_pk_fma_f32 v[124:125], v[140:141], v[124:125], v[204:205]
	v_lshl_add_u64 v[114:115], s[76:77], 0, v[114:115]
	v_pk_fma_f32 v[106:107], v[138:139], v[106:107], v[186:187]
	v_pk_fma_f32 v[108:109], v[140:141], v[108:109], v[188:189]
	v_pk_fma_f32 v[102:103], v[134:135], v[102:103], v[182:183]
	v_pk_fma_f32 v[104:105], v[136:137], v[104:105], v[184:185]
	v_pk_fma_f32 v[94:95], v[130:131], v[94:95], v[178:179]
	v_pk_fma_f32 v[96:97], v[132:133], v[96:97], v[180:181]
	v_cndmask_b32_e32 v207, v207, v126, vcc
	v_cndmask_b32_e32 v206, v206, v126, vcc
	v_cndmask_b32_e32 v125, v125, v126, vcc
	v_cndmask_b32_e32 v124, v124, v126, vcc
	v_cndmask_b32_e32 v123, v123, v126, vcc
	v_cndmask_b32_e32 v122, v122, v126, vcc
	v_lshl_add_u64 v[114:115], v[114:115], 0, v[214:215]
	v_cndmask_b32_e32 v109, v109, v126, vcc
	v_cndmask_b32_e32 v108, v108, v126, vcc
	v_cndmask_b32_e32 v107, v107, v126, vcc
	v_cndmask_b32_e32 v106, v106, v126, vcc
	v_cndmask_b32_e32 v105, v105, v126, vcc
	v_cndmask_b32_e32 v104, v104, v126, vcc
	v_cndmask_b32_e32 v103, v103, v126, vcc
	v_cndmask_b32_e32 v102, v102, v126, vcc
	v_cndmask_b32_e32 v97, v97, v126, vcc
	v_cndmask_b32_e32 v96, v96, v126, vcc
	v_cndmask_b32_e32 v95, v95, v126, vcc
	v_cndmask_b32_e32 v94, v94, v126, vcc
	global_store_dwordx4 v[128:129], v[206:209], off sc1
	global_store_dwordx4 v[128:129], v[122:125], off offset:64 sc1
	global_store_dwordx4 v[114:115], v[110:113], off sc1
	global_store_dwordx4 v[114:115], v[106:109], off offset:64 sc1
	global_store_dwordx4 v[114:115], v[102:105], off offset:512 sc1
	global_store_dwordx4 v[114:115], v[94:97], off offset:576 sc1
	ds_read2_b64 v[94:97], v216 offset0:32 offset1:48
	v_add_u32_e32 v102, 32, v0
	v_ashrrev_i32_e32 v103, 31, v102
	v_lshlrev_b64 v[102:103], 12, v[102:103]
	v_lshl_add_u64 v[102:103], s[76:77], 0, v[102:103]
	s_waitcnt lgkmcnt(0)
;     __device__ __forceinline__ void fused(f32x4 (&acc)[2][2][4][2], const Unit& u, int wr, int wc, int fr, int fq, PG8_LAS unsigned char* lds, int wid, int lane) const {
;     ...
;         for (int ai = 0; ai < 2; ++ai)
; #pragma unroll
;             for (int m = 0; m < 4; ++m) { const int r = ai * HALF + wr * 64 + m * 16 + fr; const f32x2v sr = S[r]; const size_t off = (size_t)(u.pm * BM + r) * ldc + col0;
; #pragma unroll
;                 for (int bj = 0; bj < 2; ++bj)
; #pragma unroll
;                     for (int n = 0; n < 2; ++n) { const f32x4 bs = ai == 0 ? pre[m][bj][n] : *(const f32x4*)(base + off + bj * HALF + n * 16); f32x4 o = bs + cvv[bj][n] * (acc[ai][bj][m][n] * sr.y);
;                         if (bad) o = (f32x4){qnan, qnan, qnan, qnan}; *(f32x4*)(out + off + bj * HALF + n * 16) = o; }
;                 if (m & 1) asm volatile("" ::: "memory"); }
	v_pk_mul_f32 v[88:89], v[88:89], v[94:95] op_sel:[0,1]
	v_pk_mul_f32 v[86:87], v[86:87], v[94:95] op_sel:[0,1]
	v_pk_mul_f32 v[80:81], v[80:81], v[94:95] op_sel:[0,1]
	v_pk_mul_f32 v[78:79], v[78:79], v[94:95] op_sel:[0,1]
	v_pk_fma_f32 v[86:87], v[134:135], v[86:87], v[166:167]
	v_pk_fma_f32 v[88:89], v[136:137], v[88:89], v[168:169]
	v_pk_fma_f32 v[78:79], v[130:131], v[78:79], v[162:163]
	v_pk_fma_f32 v[80:81], v[132:133], v[80:81], v[164:165]
	v_lshl_add_u64 v[102:103], v[102:103], 0, v[214:215]
	v_cndmask_b32_e32 v89, v89, v126, vcc
	v_cndmask_b32_e32 v88, v88, v126, vcc
	v_cndmask_b32_e32 v87, v87, v126, vcc
	v_cndmask_b32_e32 v86, v86, v126, vcc
	v_cndmask_b32_e32 v81, v81, v126, vcc
	v_cndmask_b32_e32 v80, v80, v126, vcc
	v_cndmask_b32_e32 v79, v79, v126, vcc
	v_cndmask_b32_e32 v78, v78, v126, vcc
	global_store_dwordx4 v[102:103], v[86:89], off offset:512 sc1
	global_store_dwordx4 v[102:103], v[78:81], off offset:576 sc1
	v_pk_mul_f32 v[76:77], v[76:77], v[96:97] op_sel:[0,1]
	v_add_u32_e32 v86, 48, v0
	v_pk_mul_f32 v[78:79], v[84:85], v[96:97] op_sel:[0,1]
	v_pk_mul_f32 v[80:81], v[82:83], v[96:97] op_sel:[0,1]
	v_ashrrev_i32_e32 v87, 31, v86
	v_pk_fma_f32 v[82:83], v[142:143], v[80:81], v[158:159]
	v_pk_fma_f32 v[78:79], v[144:145], v[78:79], v[160:161]
	v_pk_mul_f32 v[74:75], v[74:75], v[96:97] op_sel:[0,1]
	v_cndmask_b32_e32 v81, v79, v126, vcc
	v_cndmask_b32_e32 v80, v78, v126, vcc
	v_cndmask_b32_e32 v79, v83, v126, vcc
	v_cndmask_b32_e32 v78, v82, v126, vcc
	v_lshlrev_b64 v[82:83], 12, v[86:87]
	v_lshl_add_u64 v[82:83], s[76:77], 0, v[82:83]
	v_pk_fma_f32 v[74:75], v[138:139], v[74:75], v[154:155]
	v_pk_fma_f32 v[76:77], v[140:141], v[76:77], v[156:157]
	v_pk_mul_f32 v[100:101], v[100:101], v[94:95] op_sel:[0,1]
	v_pk_mul_f32 v[98:99], v[98:99], v[94:95] op_sel:[0,1]
	v_pk_mul_f32 v[92:93], v[92:93], v[94:95] op_sel:[0,1]
	v_pk_mul_f32 v[90:91], v[90:91], v[94:95] op_sel:[0,1]
	v_lshl_add_u64 v[82:83], v[82:83], 0, v[214:215]
	v_cndmask_b32_e32 v77, v77, v126, vcc
	v_cndmask_b32_e32 v76, v76, v126, vcc
	v_cndmask_b32_e32 v75, v75, v126, vcc
	v_cndmask_b32_e32 v74, v74, v126, vcc
	v_pk_mul_f32 v[72:73], v[72:73], v[96:97] op_sel:[0,1]
	v_pk_mul_f32 v[70:71], v[70:71], v[96:97] op_sel:[0,1]
	v_pk_mul_f32 v[68:69], v[68:69], v[96:97] op_sel:[0,1]
	v_pk_mul_f32 v[66:67], v[66:67], v[96:97] op_sel:[0,1]
	v_pk_fma_f32 v[98:99], v[142:143], v[98:99], v[174:175]
	v_pk_fma_f32 v[100:101], v[144:145], v[100:101], v[176:177]
	v_pk_fma_f32 v[90:91], v[138:139], v[90:91], v[170:171]
	v_pk_fma_f32 v[92:93], v[140:141], v[92:93], v[172:173]
	global_store_dwordx4 v[82:83], v[74:77], off offset:64 sc1
	v_pk_fma_f32 v[70:71], v[134:135], v[70:71], v[150:151]
	v_pk_fma_f32 v[72:73], v[136:137], v[72:73], v[152:153]
	v_pk_fma_f32 v[66:67], v[130:131], v[66:67], v[146:147]
	v_pk_fma_f32 v[68:69], v[132:133], v[68:69], v[148:149]
	v_add_u32_e32 v74, 0x80, v0
	v_cndmask_b32_e32 v101, v101, v126, vcc
	v_cndmask_b32_e32 v100, v100, v126, vcc
	v_cndmask_b32_e32 v99, v99, v126, vcc
	v_cndmask_b32_e32 v98, v98, v126, vcc
	v_cndmask_b32_e32 v93, v93, v126, vcc
	v_cndmask_b32_e32 v92, v92, v126, vcc
	v_cndmask_b32_e32 v91, v91, v126, vcc
	v_cndmask_b32_e32 v90, v90, v126, vcc
	v_cndmask_b32_e32 v73, v73, v126, vcc
	v_cndmask_b32_e32 v72, v72, v126, vcc
	v_cndmask_b32_e32 v71, v71, v126, vcc
	v_cndmask_b32_e32 v70, v70, v126, vcc
	v_cndmask_b32_e32 v69, v69, v126, vcc
	v_cndmask_b32_e32 v68, v68, v126, vcc
	v_cndmask_b32_e32 v67, v67, v126, vcc
	v_cndmask_b32_e32 v66, v66, v126, vcc
	v_ashrrev_i32_e32 v75, 31, v74
	global_store_dwordx4 v[102:103], v[98:101], off sc1
	global_store_dwordx4 v[102:103], v[90:93], off offset:64 sc1
	global_store_dwordx4 v[82:83], v[78:81], off sc1
	global_store_dwordx4 v[82:83], v[70:73], off offset:512 sc1
	global_store_dwordx4 v[82:83], v[66:69], off offset:576 sc1
	ds_read2_b64 v[88:91], v216 offset0:128 offset1:144
	ds_read2_b64 v[92:95], v216 offset0:160 offset1:176
	v_mov_b32_e32 v86, 0x10000
	v_mov_b32_e32 v87, 0
	v_add_u32_e32 v66, 0x80, v0
	v_ashrrev_i32_e32 v67, 31, v66
	v_lshlrev_b64 v[68:69], 12, v[66:67]
	v_lshl_add_u64 v[70:71], v[212:213], 0, v[68:69]
	v_lshl_add_u64 v[72:73], s[76:77], 0, v[68:69]
	v_lshl_add_u64 v[72:73], v[72:73], 0, v[214:215]
	global_load_dwordx4 v[146:149], v[70:71], off
	global_load_dwordx4 v[150:153], v[70:71], off offset:64
	global_load_dwordx4 v[154:157], v[70:71], off offset:512
	global_load_dwordx4 v[158:161], v[70:71], off offset:576
	v_lshl_add_u64 v[74:75], v[70:71], 0, v[86:87]
	v_lshl_add_u64 v[76:77], v[72:73], 0, v[86:87]
	global_load_dwordx4 v[162:165], v[74:75], off
	global_load_dwordx4 v[166:169], v[74:75], off offset:64
	global_load_dwordx4 v[170:173], v[74:75], off offset:512
	global_load_dwordx4 v[174:177], v[74:75], off offset:576
	v_lshl_add_u64 v[78:79], v[74:75], 0, v[86:87]
	v_lshl_add_u64 v[80:81], v[76:77], 0, v[86:87]
	global_load_dwordx4 v[178:181], v[78:79], off
	global_load_dwordx4 v[182:185], v[78:79], off offset:64
	global_load_dwordx4 v[186:189], v[78:79], off offset:512
	global_load_dwordx4 v[190:193], v[78:79], off offset:576
	v_lshl_add_u64 v[82:83], v[78:79], 0, v[86:87]
	v_lshl_add_u64 v[84:85], v[80:81], 0, v[86:87]
	global_load_dwordx4 v[194:197], v[82:83], off
	global_load_dwordx4 v[198:201], v[82:83], off offset:64
	global_load_dwordx4 v[202:205], v[82:83], off offset:512
	global_load_dwordx4 v[206:209], v[82:83], off offset:576
	s_waitcnt lgkmcnt(0)
;     __device__ __forceinline__ void fused(f32x4 (&acc)[2][2][4][2], const Unit& u, int wr, int wc, int fr, int fq, PG8_LAS unsigned char* lds, int wid, int lane) const {
;     ...
;             for (int m = 0; m < 4; ++m) { const int r = ai * HALF + wr * 64 + m * 16 + fr; const f32x2v sr = S[r]; const size_t off = (size_t)(u.pm * BM + r) * ldc + col0;
; #pragma unroll
;                 for (int bj = 0; bj < 2; ++bj)
; #pragma unroll
;                     for (int n = 0; n < 2; ++n) { const f32x4 bs = ai == 0 ? pre[m][bj][n] : *(const f32x4*)(base + off + bj * HALF + n * 16); f32x4 o = bs + cvv[bj][n] * (acc[ai][bj][m][n] * sr.y);
;                         if (bad) o = (f32x4){qnan, qnan, qnan, qnan}; *(f32x4*)(out + off + bj * HALF + n * 16) = o; }
	v_pk_mul_f32 v[62:63], v[62:63], v[88:89] op_sel:[0,1]
	v_pk_mul_f32 v[64:65], v[64:65], v[88:89] op_sel:[0,1]
	v_pk_mul_f32 v[58:59], v[58:59], v[88:89] op_sel:[0,1]
	v_pk_mul_f32 v[60:61], v[60:61], v[88:89] op_sel:[0,1]
	v_pk_mul_f32 v[54:55], v[54:55], v[88:89] op_sel:[0,1]
	v_pk_mul_f32 v[56:57], v[56:57], v[88:89] op_sel:[0,1]
	v_pk_mul_f32 v[46:47], v[46:47], v[88:89] op_sel:[0,1]
	v_pk_mul_f32 v[48:49], v[48:49], v[88:89] op_sel:[0,1]
	s_waitcnt vmcnt(15)
	v_pk_fma_f32 v[62:63], v[142:143], v[62:63], v[146:147]
	v_pk_fma_f32 v[64:65], v[144:145], v[64:65], v[148:149]
	v_cndmask_b32_e32 v62, v62, v126, vcc
	v_cndmask_b32_e32 v63, v63, v126, vcc
	v_cndmask_b32_e32 v64, v64, v126, vcc
	v_cndmask_b32_e32 v65, v65, v126, vcc
	global_store_dwordx4 v[72:73], v[62:65], off sc1
	s_waitcnt vmcnt(15)
	v_pk_fma_f32 v[58:59], v[138:139], v[58:59], v[150:151]
	v_pk_fma_f32 v[60:61], v[140:141], v[60:61], v[152:153]
	v_cndmask_b32_e32 v58, v58, v126, vcc
	v_cndmask_b32_e32 v59, v59, v126, vcc
	v_cndmask_b32_e32 v60, v60, v126, vcc
	v_cndmask_b32_e32 v61, v61, v126, vcc
	global_store_dwordx4 v[72:73], v[58:61], off offset:64 sc1
	s_waitcnt vmcnt(15)
	v_pk_fma_f32 v[54:55], v[134:135], v[54:55], v[154:155]
	v_pk_fma_f32 v[56:57], v[136:137], v[56:57], v[156:157]
	v_cndmask_b32_e32 v54, v54, v126, vcc
	v_cndmask_b32_e32 v55, v55, v126, vcc
	v_cndmask_b32_e32 v56, v56, v126, vcc
	v_cndmask_b32_e32 v57, v57, v126, vcc
	global_store_dwordx4 v[72:73], v[54:57], off offset:512 sc1
	s_waitcnt vmcnt(15)
	v_pk_fma_f32 v[46:47], v[130:131], v[46:47], v[158:159]
	v_pk_fma_f32 v[48:49], v[132:133], v[48:49], v[160:161]
	v_cndmask_b32_e32 v46, v46, v126, vcc
	v_cndmask_b32_e32 v47, v47, v126, vcc
	v_cndmask_b32_e32 v48, v48, v126, vcc
	v_cndmask_b32_e32 v49, v49, v126, vcc
	global_store_dwordx4 v[72:73], v[46:49], off offset:576 sc1
	v_pk_mul_f32 v[50:51], v[50:51], v[90:91] op_sel:[0,1]
	v_pk_mul_f32 v[52:53], v[52:53], v[90:91] op_sel:[0,1]
	v_pk_mul_f32 v[42:43], v[42:43], v[90:91] op_sel:[0,1]
	v_pk_mul_f32 v[44:45], v[44:45], v[90:91] op_sel:[0,1]
	v_pk_mul_f32 v[38:39], v[38:39], v[90:91] op_sel:[0,1]
	v_pk_mul_f32 v[40:41], v[40:41], v[90:91] op_sel:[0,1]
	v_pk_mul_f32 v[30:31], v[30:31], v[90:91] op_sel:[0,1]
	v_pk_mul_f32 v[32:33], v[32:33], v[90:91] op_sel:[0,1]
	s_waitcnt vmcnt(15)
	v_pk_fma_f32 v[50:51], v[142:143], v[50:51], v[162:163]
	v_pk_fma_f32 v[52:53], v[144:145], v[52:53], v[164:165]
	v_cndmask_b32_e32 v50, v50, v126, vcc
	v_cndmask_b32_e32 v51, v51, v126, vcc
	v_cndmask_b32_e32 v52, v52, v126, vcc
	v_cndmask_b32_e32 v53, v53, v126, vcc
	global_store_dwordx4 v[76:77], v[50:53], off sc1
	s_waitcnt vmcnt(15)
	v_pk_fma_f32 v[42:43], v[138:139], v[42:43], v[166:167]
	v_pk_fma_f32 v[44:45], v[140:141], v[44:45], v[168:169]
	v_cndmask_b32_e32 v42, v42, v126, vcc
	v_cndmask_b32_e32 v43, v43, v126, vcc
	v_cndmask_b32_e32 v44, v44, v126, vcc
	v_cndmask_b32_e32 v45, v45, v126, vcc
	global_store_dwordx4 v[76:77], v[42:45], off offset:64 sc1
	s_waitcnt vmcnt(15)
	v_pk_fma_f32 v[38:39], v[134:135], v[38:39], v[170:171]
	v_pk_fma_f32 v[40:41], v[136:137], v[40:41], v[172:173]
	v_cndmask_b32_e32 v38, v38, v126, vcc
	v_cndmask_b32_e32 v39, v39, v126, vcc
	v_cndmask_b32_e32 v40, v40, v126, vcc
	v_cndmask_b32_e32 v41, v41, v126, vcc
	global_store_dwordx4 v[76:77], v[38:41], off offset:512 sc1
	s_waitcnt vmcnt(15)
;     __device__ __forceinline__ void fused(f32x4 (&acc)[2][2][4][2], const Unit& u, int wr, int wc, int fr, int fq, PG8_LAS unsigned char* lds, int wid, int lane) const {
;     ...
;             for (int m = 0; m < 4; ++m) { const int r = ai * HALF + wr * 64 + m * 16 + fr; const f32x2v sr = S[r]; const size_t off = (size_t)(u.pm * BM + r) * ldc + col0;
; #pragma unroll
;                 for (int bj = 0; bj < 2; ++bj)
; #pragma unroll
;                     for (int n = 0; n < 2; ++n) { const f32x4 bs = ai == 0 ? pre[m][bj][n] : *(const f32x4*)(base + off + bj * HALF + n * 16); f32x4 o = bs + cvv[bj][n] * (acc[ai][bj][m][n] * sr.y);
;                         if (bad) o = (f32x4){qnan, qnan, qnan, qnan}; *(f32x4*)(out + off + bj * HALF + n * 16) = o; }
;                 if (m & 1) asm volatile("" ::: "memory"); }
	v_pk_fma_f32 v[30:31], v[130:131], v[30:31], v[174:175]
	v_pk_fma_f32 v[32:33], v[132:133], v[32:33], v[176:177]
	v_cndmask_b32_e32 v30, v30, v126, vcc
	v_cndmask_b32_e32 v31, v31, v126, vcc
	v_cndmask_b32_e32 v32, v32, v126, vcc
	v_cndmask_b32_e32 v33, v33, v126, vcc
	global_store_dwordx4 v[76:77], v[30:33], off offset:576 sc1
	v_pk_mul_f32 v[34:35], v[34:35], v[92:93] op_sel:[0,1]
	v_pk_mul_f32 v[36:37], v[36:37], v[92:93] op_sel:[0,1]
	v_pk_mul_f32 v[26:27], v[26:27], v[92:93] op_sel:[0,1]
	v_pk_mul_f32 v[28:29], v[28:29], v[92:93] op_sel:[0,1]
	v_pk_mul_f32 v[22:23], v[22:23], v[92:93] op_sel:[0,1]
	v_pk_mul_f32 v[24:25], v[24:25], v[92:93] op_sel:[0,1]
	v_pk_mul_f32 v[14:15], v[14:15], v[92:93] op_sel:[0,1]
	v_pk_mul_f32 v[16:17], v[16:17], v[92:93] op_sel:[0,1]
	s_waitcnt vmcnt(15)
	v_pk_fma_f32 v[34:35], v[142:143], v[34:35], v[178:179]
	v_pk_fma_f32 v[36:37], v[144:145], v[36:37], v[180:181]
	v_cndmask_b32_e32 v34, v34, v126, vcc
	v_cndmask_b32_e32 v35, v35, v126, vcc
	v_cndmask_b32_e32 v36, v36, v126, vcc
	v_cndmask_b32_e32 v37, v37, v126, vcc
	global_store_dwordx4 v[80:81], v[34:37], off sc1
	s_waitcnt vmcnt(15)
	v_pk_fma_f32 v[26:27], v[138:139], v[26:27], v[182:183]
	v_pk_fma_f32 v[28:29], v[140:141], v[28:29], v[184:185]
	v_cndmask_b32_e32 v26, v26, v126, vcc
	v_cndmask_b32_e32 v27, v27, v126, vcc
	v_cndmask_b32_e32 v28, v28, v126, vcc
	v_cndmask_b32_e32 v29, v29, v126, vcc
	global_store_dwordx4 v[80:81], v[26:29], off offset:64 sc1
	s_waitcnt vmcnt(15)
	v_pk_fma_f32 v[22:23], v[134:135], v[22:23], v[186:187]
	v_pk_fma_f32 v[24:25], v[136:137], v[24:25], v[188:189]
	v_cndmask_b32_e32 v22, v22, v126, vcc
	v_cndmask_b32_e32 v23, v23, v126, vcc
	v_cndmask_b32_e32 v24, v24, v126, vcc
	v_cndmask_b32_e32 v25, v25, v126, vcc
	global_store_dwordx4 v[80:81], v[22:25], off offset:512 sc1
	s_waitcnt vmcnt(15)
	v_pk_fma_f32 v[14:15], v[130:131], v[14:15], v[190:191]
	v_pk_fma_f32 v[16:17], v[132:133], v[16:17], v[192:193]
	v_cndmask_b32_e32 v14, v14, v126, vcc
	v_cndmask_b32_e32 v15, v15, v126, vcc
	v_cndmask_b32_e32 v16, v16, v126, vcc
	v_cndmask_b32_e32 v17, v17, v126, vcc
	global_store_dwordx4 v[80:81], v[14:17], off offset:576 sc1
	v_pk_mul_f32 v[18:19], v[18:19], v[94:95] op_sel:[0,1]
	v_pk_mul_f32 v[20:21], v[20:21], v[94:95] op_sel:[0,1]
	v_pk_mul_f32 v[10:11], v[10:11], v[94:95] op_sel:[0,1]
	v_pk_mul_f32 v[12:13], v[12:13], v[94:95] op_sel:[0,1]
	v_pk_mul_f32 v[6:7], v[6:7], v[94:95] op_sel:[0,1]
	v_pk_mul_f32 v[8:9], v[8:9], v[94:95] op_sel:[0,1]
	v_pk_mul_f32 v[2:3], v[2:3], v[94:95] op_sel:[0,1]
	v_pk_mul_f32 v[4:5], v[4:5], v[94:95] op_sel:[0,1]
	s_waitcnt vmcnt(15)
	v_pk_fma_f32 v[18:19], v[142:143], v[18:19], v[194:195]
	v_pk_fma_f32 v[20:21], v[144:145], v[20:21], v[196:197]
	v_cndmask_b32_e32 v18, v18, v126, vcc
	v_cndmask_b32_e32 v19, v19, v126, vcc
	v_cndmask_b32_e32 v20, v20, v126, vcc
	v_cndmask_b32_e32 v21, v21, v126, vcc
	global_store_dwordx4 v[84:85], v[18:21], off sc1
	s_waitcnt vmcnt(15)
	v_pk_fma_f32 v[10:11], v[138:139], v[10:11], v[198:199]
	v_pk_fma_f32 v[12:13], v[140:141], v[12:13], v[200:201]
	v_cndmask_b32_e32 v10, v10, v126, vcc
	v_cndmask_b32_e32 v11, v11, v126, vcc
	v_cndmask_b32_e32 v12, v12, v126, vcc
	v_cndmask_b32_e32 v13, v13, v126, vcc
	global_store_dwordx4 v[84:85], v[10:13], off offset:64 sc1
	s_waitcnt vmcnt(15)
	v_pk_fma_f32 v[6:7], v[134:135], v[6:7], v[202:203]
	v_pk_fma_f32 v[8:9], v[136:137], v[8:9], v[204:205]
	v_cndmask_b32_e32 v6, v6, v126, vcc
	v_cndmask_b32_e32 v7, v7, v126, vcc
	v_cndmask_b32_e32 v8, v8, v126, vcc
	v_cndmask_b32_e32 v9, v9, v126, vcc
	global_store_dwordx4 v[84:85], v[6:9], off offset:512 sc1
	s_waitcnt vmcnt(15)
	v_pk_fma_f32 v[2:3], v[130:131], v[2:3], v[206:207]
	v_pk_fma_f32 v[4:5], v[132:133], v[4:5], v[208:209]
	v_cndmask_b32_e32 v2, v2, v126, vcc
	v_cndmask_b32_e32 v3, v3, v126, vcc
	v_cndmask_b32_e32 v4, v4, v126, vcc
	v_cndmask_b32_e32 v5, v5, v126, vcc
	global_store_dwordx4 v[84:85], v[2:5], off offset:576 sc1
